# attention softmax: row max/sum xor-16/32 shuffles via permlane swaps (13 of 16 sites)
# baseline (speedup 1.0000x reference)
.LBB0_567:
	s_add_i32 s26, s26, 6
	s_max_i32 s18, s26, 4
	s_add_i32 s18, s18, -4
	s_min_u32 s34, s18, 24
	s_mul_i32 s18, s34, 29
	s_lshr_b32 s18, s18, 8
	s_mul_i32 s18, s18, 9
	s_sub_i32 s18, s34, s18
	s_and_b32 s18, s18, 0xff
	s_lshl_b32 s29, s18, 13
	s_add_i32 s18, s29, 0x100
	s_waitcnt lgkmcnt(0)
	s_barrier
	v_add_u32_e32 v16, s18, v134
	v_add_u32_e32 v24, s18, v135
	ds_read_b128 v[12:15], v16
	ds_read_b128 v[16:19], v16 offset:2048
	ds_read_b128 v[20:23], v24
	ds_read_b128 v[24:27], v24 offset:2048
	s_mul_i32 s18, s34, 57
	s_add_i32 s22, s18, 57
	s_bfe_u32 s22, s22, 0x30009
	s_mul_i32 s22, s22, 9
	s_sub_i32 s22, s34, s22
	s_waitcnt lgkmcnt(2)
	v_mfma_f32_16x16x32_bf16 v[16:19], v[16:19], v[8:11], 0
	s_add_i32 s22, s22, 1
	s_and_b32 s22, s22, 0xff
	s_lshl_b32 s28, s22, 13
	v_mfma_f32_16x16x32_bf16 v[12:15], v[12:15], v[8:11], 0
	s_add_i32 s22, s28, 0x100
	s_add_i32 s29, s53, s29
	s_add_i32 s28, s53, s28
	s_waitcnt lgkmcnt(0)
	v_mfma_f32_16x16x32_bf16 v[48:51], v[24:27], v[4:7], v[16:19]
	v_add_u32_e32 v24, s22, v135
	s_add_i32 s60, s60, s33
	s_nop 0
	v_add_u32_e32 v16, s22, v134
	v_mfma_f32_16x16x32_bf16 v[44:47], v[20:23], v[4:7], v[12:15]
	s_add_i32 s22, s18, 0x72
	s_bfe_u32 s22, s22, 0x30009
	s_mul_i32 s22, s22, 9
	ds_read_b128 v[12:15], v16
	ds_read_b128 v[16:19], v16 offset:2048
	s_waitcnt lgkmcnt(1)
	v_mfma_f32_16x16x32_bf16 v[12:15], v[12:15], v[8:11], 0
	ds_read_b128 v[20:23], v24
	ds_read_b128 v[24:27], v24 offset:2048
	s_sub_i32 s22, s34, s22
	s_add_i32 s22, s22, 2
	s_waitcnt lgkmcnt(1)
	v_mfma_f32_16x16x32_bf16 v[52:55], v[20:23], v[4:7], v[12:15]
	s_and_b32 s22, s22, 0xff
	s_lshl_b32 s27, s22, 13
	s_add_i32 s22, s27, 0x100
	v_mfma_f32_16x16x32_bf16 v[12:15], v[16:19], v[8:11], 0
	v_add_u32_e32 v16, s22, v134
	s_add_i32 s27, s53, s27
	s_waitcnt lgkmcnt(0)
	v_mfma_f32_16x16x32_bf16 v[56:59], v[24:27], v[4:7], v[12:15]
	v_add_u32_e32 v24, s22, v135
	s_add_i32 s22, s18, 0xab
	s_bfe_u32 s22, s22, 0x30009
	s_nop 0
	ds_read_b128 v[12:15], v16
	ds_read_b128 v[16:19], v16 offset:2048
	s_waitcnt lgkmcnt(1)
	v_mfma_f32_16x16x32_bf16 v[12:15], v[12:15], v[8:11], 0
	ds_read_b128 v[20:23], v24
	ds_read_b128 v[24:27], v24 offset:2048
	s_mul_i32 s22, s22, 9
	s_sub_i32 s22, s34, s22
	s_add_i32 s22, s22, 3
	s_waitcnt lgkmcnt(1)
	v_mfma_f32_16x16x32_bf16 v[60:63], v[20:23], v[4:7], v[12:15]
	s_and_b32 s22, s22, 0xff
	s_lshl_b32 s25, s22, 13
	s_add_i32 s22, s25, 0x100
	v_mfma_f32_16x16x32_bf16 v[12:15], v[16:19], v[8:11], 0
	v_add_u32_e32 v16, s22, v134
	s_add_i32 s25, s53, s25
	s_waitcnt lgkmcnt(0)
	v_mfma_f32_16x16x32_bf16 v[64:67], v[24:27], v[4:7], v[12:15]
	v_add_u32_e32 v24, s22, v135
	s_add_i32 s22, s18, 0xe4
	s_bfe_u32 s22, s22, 0x30009
	s_nop 0
	ds_read_b128 v[12:15], v16
	ds_read_b128 v[16:19], v16 offset:2048
	s_waitcnt lgkmcnt(1)
	v_mfma_f32_16x16x32_bf16 v[12:15], v[12:15], v[8:11], 0
	ds_read_b128 v[20:23], v24
	ds_read_b128 v[24:27], v24 offset:2048
	s_mul_i32 s22, s22, 9
	s_sub_i32 s22, s34, s22
	s_add_i32 s22, s22, 4
	s_waitcnt lgkmcnt(1)
	v_mfma_f32_16x16x32_bf16 v[68:71], v[20:23], v[4:7], v[12:15]
	s_and_b32 s22, s22, 0xff
	s_lshl_b32 s24, s22, 13
	s_add_i32 s22, s24, 0x100
	v_mfma_f32_16x16x32_bf16 v[12:15], v[16:19], v[8:11], 0
	v_add_u32_e32 v16, s22, v134
	s_add_i32 s24, s53, s24
	s_waitcnt lgkmcnt(0)
	v_mfma_f32_16x16x32_bf16 v[40:43], v[24:27], v[4:7], v[12:15]
	v_add_u32_e32 v24, s22, v135
	s_add_i32 s22, s18, 0x11d
	s_bfe_u32 s22, s22, 0x30009
	s_nop 0
	ds_read_b128 v[12:15], v16
	ds_read_b128 v[16:19], v16 offset:2048
	s_waitcnt lgkmcnt(1)
	v_mfma_f32_16x16x32_bf16 v[12:15], v[12:15], v[8:11], 0
	ds_read_b128 v[20:23], v24
	ds_read_b128 v[24:27], v24 offset:2048
	s_mul_i32 s22, s22, 9
	s_sub_i32 s22, s34, s22
	s_add_i32 s22, s22, 5
	s_waitcnt lgkmcnt(1)
	v_mfma_f32_16x16x32_bf16 v[36:39], v[20:23], v[4:7], v[12:15]
	s_and_b32 s22, s22, 0xff
	s_lshl_b32 s23, s22, 13
	s_add_i32 s22, s23, 0x100
	v_mfma_f32_16x16x32_bf16 v[12:15], v[16:19], v[8:11], 0
	v_add_u32_e32 v16, s22, v134
	s_add_i32 s23, s53, s23
	s_waitcnt lgkmcnt(0)
	v_mfma_f32_16x16x32_bf16 v[32:35], v[24:27], v[4:7], v[12:15]
	v_add_u32_e32 v24, s22, v135
	s_add_i32 s22, s18, 0x156
	s_bfe_u32 s22, s22, 0x30009
	s_nop 0
	ds_read_b128 v[12:15], v16
	ds_read_b128 v[16:19], v16 offset:2048
	s_waitcnt lgkmcnt(1)
	v_mfma_f32_16x16x32_bf16 v[12:15], v[12:15], v[8:11], 0
	ds_read_b128 v[20:23], v24
	ds_read_b128 v[24:27], v24 offset:2048
	s_mul_i32 s22, s22, 9
	s_sub_i32 s22, s34, s22
	s_add_i32 s22, s22, 6
	s_waitcnt lgkmcnt(1)
	v_mfma_f32_16x16x32_bf16 v[28:31], v[20:23], v[4:7], v[12:15]
	s_and_b32 s22, s22, 0xff
	s_lshl_b32 s22, s22, 13
	s_add_i32 s35, s22, 0x100
	v_mfma_f32_16x16x32_bf16 v[12:15], v[16:19], v[8:11], 0
	v_add_u32_e32 v16, s35, v134
	v_add_u32_e32 v72, s35, v135
	s_addk_i32 s18, 0x18f
	s_waitcnt lgkmcnt(0)
	v_mfma_f32_16x16x32_bf16 v[24:27], v[24:27], v[4:7], v[12:15]
	s_bfe_u32 s18, s18, 0x30009
	s_mul_i32 s18, s18, 9
	s_sub_i32 s18, s34, s18
	ds_read_b128 v[12:15], v16
	ds_read_b128 v[16:19], v16 offset:2048
	s_waitcnt lgkmcnt(1)
	v_mfma_f32_16x16x32_bf16 v[12:15], v[12:15], v[8:11], 0
	ds_read_b128 v[20:23], v72
	ds_read_b128 v[72:75], v72 offset:2048
	s_add_i32 s18, s18, 7
	s_and_b32 s18, s18, 0xff
	s_waitcnt lgkmcnt(1)
	v_mfma_f32_16x16x32_bf16 v[20:23], v[20:23], v[4:7], v[12:15]
	s_lshl_b32 s18, s18, 13
	s_add_i32 s35, s18, 0x100
	v_add_u32_e32 v80, s35, v135
	v_mfma_f32_16x16x32_bf16 v[12:15], v[16:19], v[8:11], 0
	s_sub_i32 s34, s34, s26
	s_mulk_i32 s34, 0x7c
	s_add_i32 s22, s53, s22
	s_waitcnt lgkmcnt(0)
	v_mfma_f32_16x16x32_bf16 v[16:19], v[72:75], v[4:7], v[12:15]
	v_add_u32_e32 v72, s35, v134
	s_add_i32 s18, s53, s18
	s_nop 0
	ds_read_b128 v[12:15], v72
	ds_read_b128 v[72:75], v72 offset:2048
	s_waitcnt lgkmcnt(1)
	v_mfma_f32_16x16x32_bf16 v[12:15], v[12:15], v[8:11], 0
	ds_read_b128 v[76:79], v80
	ds_read_b128 v[80:83], v80 offset:2048
	s_waitcnt lgkmcnt(2)
	v_mfma_f32_16x16x32_bf16 v[8:11], v[72:75], v[8:11], 0
	s_waitcnt lgkmcnt(1)
	v_mfma_f32_16x16x32_bf16 v[12:15], v[76:79], v[4:7], v[12:15]
	v_add_u32_e32 v76, s34, v148
	ds_read2_b32 v[72:73], v76 offset0:232 offset1:233
	s_waitcnt lgkmcnt(0)
	v_add_f32_e32 v44, v44, v72
	v_mfma_f32_16x16x32_bf16 v[4:7], v[80:83], v[4:7], v[8:11]
	s_nop 2
	ds_read2_b32 v[8:9], v76 offset0:234 offset1:235
	ds_read2_b32 v[10:11], v76 offset0:248 offset1:249
	ds_read2_b32 v[74:75], v76 offset0:250 offset1:251
	v_add_f32_e32 v72, v140, v44
	v_add_f32_e32 v44, v45, v73
	s_waitcnt lgkmcnt(2)
	v_add_f32_e32 v8, v46, v8
	v_add_f32_e32 v77, v142, v8
	v_add_f32_e32 v8, v47, v9
	s_waitcnt lgkmcnt(1)
	v_add_f32_e32 v9, v48, v10
	v_add_f32_e32 v73, v141, v44
	v_add_f32_e32 v48, v144, v9
	v_add_f32_e32 v9, v49, v11
	v_max3_f32 v44, v72, s59, v73
	v_add_f32_e32 v78, v143, v8
	v_add_f32_e32 v49, v145, v9
	s_waitcnt lgkmcnt(0)
	v_add_f32_e32 v9, v50, v74
	v_max3_f32 v8, v44, v77, v78
	v_add_f32_e32 v50, v146, v9
	v_add_f32_e32 v9, v51, v75
	v_max3_f32 v8, v8, v48, v49
	v_add_f32_e32 v51, v147, v9
	v_max3_f32 v74, v8, v50, v51
	v_add_u32_e32 v8, 0x41c, v76
	ds_read2_b32 v[8:9], v8 offset1:1
	v_add_u32_e32 v10, 0x424, v76
	v_add_u32_e32 v44, 0x45c, v76
	v_add_u32_e32 v46, 0x464, v76
	ds_read2_b32 v[10:11], v10 offset1:1
	ds_read2_b32 v[44:45], v44 offset1:1
	ds_read2_b32 v[46:47], v46 offset1:1
	s_waitcnt lgkmcnt(3)
	v_add_f32_e32 v8, v52, v8
	v_add_f32_e32 v52, v140, v8
	v_add_f32_e32 v8, v53, v9
	s_waitcnt lgkmcnt(2)
	v_add_f32_e32 v9, v54, v10
	v_add_f32_e32 v54, v142, v9
	v_add_f32_e32 v9, v55, v11
	v_add_f32_e32 v55, v143, v9
	s_waitcnt lgkmcnt(1)
	v_add_f32_e32 v9, v56, v44
	v_add_f32_e32 v53, v141, v8
	v_add_f32_e32 v56, v144, v9
	v_add_f32_e32 v9, v57, v45
	v_max3_f32 v8, v74, v52, v53
	v_add_f32_e32 v57, v145, v9
	s_waitcnt lgkmcnt(0)
	v_add_f32_e32 v9, v58, v46
	v_max3_f32 v8, v8, v54, v55
	v_add_f32_e32 v58, v146, v9
	v_add_f32_e32 v9, v59, v47
	v_max3_f32 v8, v8, v56, v57
	v_add_f32_e32 v59, v147, v9
	v_max3_f32 v74, v8, v58, v59
	v_add_u32_e32 v8, 0x498, v76
	ds_read2_b32 v[8:9], v8 offset1:1
	v_add_u32_e32 v10, 0x4a0, v76
	v_add_u32_e32 v44, 0x4d8, v76
	v_add_u32_e32 v46, 0x4e0, v76
	ds_read2_b32 v[10:11], v10 offset1:1
	ds_read2_b32 v[44:45], v44 offset1:1
	ds_read2_b32 v[46:47], v46 offset1:1
	s_waitcnt lgkmcnt(3)
	v_add_f32_e32 v8, v60, v8
	v_add_f32_e32 v60, v140, v8
	v_add_f32_e32 v8, v61, v9
	s_waitcnt lgkmcnt(2)
	v_add_f32_e32 v9, v62, v10
	v_add_f32_e32 v62, v142, v9
	v_add_f32_e32 v9, v63, v11
	v_add_f32_e32 v63, v143, v9
	s_waitcnt lgkmcnt(1)
	v_add_f32_e32 v9, v64, v44
	v_add_f32_e32 v61, v141, v8
	v_add_f32_e32 v64, v144, v9
	v_add_f32_e32 v9, v65, v45
	v_max3_f32 v8, v74, v60, v61
	v_add_f32_e32 v65, v145, v9
	s_waitcnt lgkmcnt(0)
	v_add_f32_e32 v9, v66, v46
	v_max3_f32 v8, v8, v62, v63
	v_add_f32_e32 v66, v146, v9
	v_add_f32_e32 v9, v67, v47
	v_max3_f32 v8, v8, v64, v65
	v_add_f32_e32 v67, v147, v9
	v_max3_f32 v74, v8, v66, v67
	v_add_u32_e32 v8, 0x514, v76
	ds_read2_b32 v[8:9], v8 offset1:1
	v_add_u32_e32 v10, 0x51c, v76
	v_add_u32_e32 v44, 0x554, v76
	v_add_u32_e32 v46, 0x55c, v76
	ds_read2_b32 v[10:11], v10 offset1:1
	ds_read2_b32 v[44:45], v44 offset1:1
	ds_read2_b32 v[46:47], v46 offset1:1
	s_waitcnt lgkmcnt(3)
	v_add_f32_e32 v8, v68, v8
	v_add_f32_e32 v68, v140, v8
	v_add_f32_e32 v8, v69, v9
	s_waitcnt lgkmcnt(2)
	v_add_f32_e32 v9, v70, v10
	v_add_f32_e32 v70, v142, v9
	v_add_f32_e32 v9, v71, v11
	v_add_f32_e32 v71, v143, v9
	s_waitcnt lgkmcnt(1)
	v_add_f32_e32 v9, v40, v44
	v_add_f32_e32 v69, v141, v8
	v_add_f32_e32 v44, v144, v9
	v_add_f32_e32 v9, v41, v45
	v_max3_f32 v8, v74, v68, v69
	v_add_f32_e32 v45, v145, v9
	s_waitcnt lgkmcnt(0)
	v_add_f32_e32 v9, v42, v46
	v_max3_f32 v8, v8, v70, v71
	v_add_f32_e32 v46, v146, v9
	v_add_f32_e32 v9, v43, v47
	v_max3_f32 v8, v8, v44, v45
	v_add_f32_e32 v47, v147, v9
	v_max3_f32 v74, v8, v46, v47
	v_add_u32_e32 v8, 0x590, v76
	ds_read2_b32 v[8:9], v8 offset1:1
	v_add_u32_e32 v10, 0x598, v76
	v_add_u32_e32 v40, 0x5d0, v76
	v_add_u32_e32 v42, 0x5d8, v76
	ds_read2_b32 v[10:11], v10 offset1:1
	ds_read2_b32 v[40:41], v40 offset1:1
	ds_read2_b32 v[42:43], v42 offset1:1
	s_waitcnt lgkmcnt(3)
	v_add_f32_e32 v8, v36, v8
	v_add_f32_e32 v36, v140, v8
	v_add_f32_e32 v8, v37, v9
	s_waitcnt lgkmcnt(2)
	v_add_f32_e32 v9, v38, v10
	v_add_f32_e32 v38, v142, v9
	v_add_f32_e32 v9, v39, v11
	v_add_f32_e32 v39, v143, v9
	s_waitcnt lgkmcnt(1)
	v_add_f32_e32 v9, v32, v40
	v_add_f32_e32 v37, v141, v8
	v_add_f32_e32 v40, v144, v9
	v_add_f32_e32 v9, v33, v41
	v_max3_f32 v8, v74, v36, v37
	v_add_f32_e32 v41, v145, v9
	s_waitcnt lgkmcnt(0)
	v_add_f32_e32 v9, v34, v42
	v_max3_f32 v8, v8, v38, v39
	v_add_f32_e32 v42, v146, v9
	v_add_f32_e32 v9, v35, v43
	v_max3_f32 v8, v8, v40, v41
	v_add_f32_e32 v43, v147, v9
	v_max3_f32 v74, v8, v42, v43
	v_add_u32_e32 v8, 0x60c, v76
	ds_read2_b32 v[8:9], v8 offset1:1
	v_add_u32_e32 v10, 0x614, v76
	v_add_u32_e32 v32, 0x64c, v76
	v_add_u32_e32 v34, 0x654, v76
	ds_read2_b32 v[10:11], v10 offset1:1
	ds_read2_b32 v[32:33], v32 offset1:1
	ds_read2_b32 v[34:35], v34 offset1:1
	s_waitcnt lgkmcnt(3)
	v_add_f32_e32 v8, v28, v8
	v_add_f32_e32 v28, v140, v8
	v_add_f32_e32 v8, v29, v9
	s_waitcnt lgkmcnt(2)
	v_add_f32_e32 v9, v30, v10
	v_add_f32_e32 v30, v142, v9
	v_add_f32_e32 v9, v31, v11
	v_add_f32_e32 v31, v143, v9
	s_waitcnt lgkmcnt(1)
	v_add_f32_e32 v9, v24, v32
	v_add_f32_e32 v29, v141, v8
	v_add_f32_e32 v32, v144, v9
	v_add_f32_e32 v9, v25, v33
	v_max3_f32 v8, v74, v28, v29
	v_add_f32_e32 v33, v145, v9
	s_waitcnt lgkmcnt(0)
	v_add_f32_e32 v9, v26, v34
	v_max3_f32 v8, v8, v30, v31
	v_add_f32_e32 v34, v146, v9
	v_add_f32_e32 v9, v27, v35
	v_max3_f32 v8, v8, v32, v33
	v_add_f32_e32 v35, v147, v9
	v_max3_f32 v74, v8, v34, v35
	v_add_u32_e32 v8, 0x688, v76
	ds_read2_b32 v[8:9], v8 offset1:1
	v_add_u32_e32 v10, 0x690, v76
	v_add_u32_e32 v24, 0x6c8, v76
	v_add_u32_e32 v26, 0x6d0, v76
	ds_read2_b32 v[10:11], v10 offset1:1
	ds_read2_b32 v[24:25], v24 offset1:1
	ds_read2_b32 v[26:27], v26 offset1:1
	s_waitcnt lgkmcnt(3)
	v_add_f32_e32 v8, v20, v8
	v_add_f32_e32 v20, v140, v8
	v_add_f32_e32 v8, v21, v9
	s_waitcnt lgkmcnt(2)
	v_add_f32_e32 v9, v22, v10
	v_add_f32_e32 v22, v142, v9
	v_add_f32_e32 v9, v23, v11
	v_add_f32_e32 v23, v143, v9
	s_waitcnt lgkmcnt(1)
	v_add_f32_e32 v9, v16, v24
	v_add_f32_e32 v21, v141, v8
	v_add_f32_e32 v24, v144, v9
	v_add_f32_e32 v9, v17, v25
	v_max3_f32 v8, v74, v20, v21
	v_add_f32_e32 v25, v145, v9
	s_waitcnt lgkmcnt(0)
	v_add_f32_e32 v9, v18, v26
	v_max3_f32 v8, v8, v22, v23
	v_add_f32_e32 v26, v146, v9
	v_add_f32_e32 v9, v19, v27
	v_max3_f32 v8, v8, v24, v25
	v_add_f32_e32 v27, v147, v9
	v_max3_f32 v74, v8, v26, v27
	v_add_u32_e32 v8, 0x704, v76
	ds_read2_b32 v[8:9], v8 offset1:1
	v_add_u32_e32 v10, 0x70c, v76
	v_add_u32_e32 v16, 0x744, v76
	v_add_u32_e32 v18, 0x74c, v76
	ds_read2_b32 v[10:11], v10 offset1:1
	ds_read2_b32 v[16:17], v16 offset1:1
	ds_read2_b32 v[18:19], v18 offset1:1
	s_waitcnt lgkmcnt(3)
	v_add_f32_e32 v8, v12, v8
	v_add_f32_e32 v75, v140, v8
	v_add_f32_e32 v8, v13, v9
	v_add_f32_e32 v76, v141, v8
	s_waitcnt lgkmcnt(2)
	v_add_f32_e32 v9, v14, v10
	s_waitcnt lgkmcnt(1)
	v_add_f32_e32 v4, v4, v16
	v_max3_f32 v8, v74, v75, v76
	v_add_f32_e32 v74, v142, v9
	v_add_f32_e32 v9, v15, v11
	v_add_f32_e32 v80, v144, v4
	v_add_f32_e32 v4, v5, v17
	v_add_f32_e32 v79, v143, v9
	v_add_f32_e32 v81, v145, v4
	s_waitcnt lgkmcnt(0)
	v_add_f32_e32 v4, v6, v18
	v_max3_f32 v8, v8, v74, v79
	v_add_f32_e32 v6, v146, v4
	v_add_f32_e32 v4, v7, v19
	v_max3_f32 v5, v8, v80, v81
	v_add_f32_e32 v4, v147, v4
	v_max3_f32 v5, v5, v6, v4
	v_mov_b32_e32 v7, v5
	s_nop 1
	v_permlane16_swap_b32 v5, v7
	v_add_u32_e32 v10, s29, v136
	s_waitcnt lgkmcnt(0)
	v_max_f32_e32 v7, v7, v7
	v_max_f32_e32 v5, v5, v7
	v_mov_b32_e32 v7, v5
	s_nop 1
	v_permlane32_swap_b32 v5, v7
	s_waitcnt lgkmcnt(0)
	v_max_f32_e32 v7, v7, v7
	v_max_f32_e32 v5, v5, v7
	v_pk_mul_f32 v[4:5], v[4:5], s[20:21] op_sel_hi:[1,0]
	s_nop 0
	v_fma_f32 v7, v72, s20, -v5
	v_exp_f32_e32 v7, v7
	v_fma_f32 v8, v73, s20, -v5
	v_exp_f32_e32 v12, v8
	v_fma_f32 v9, v77, s20, -v5
	v_exp_f32_e32 v13, v9
	v_fma_f32 v9, v78, s20, -v5
	v_exp_f32_e32 v14, v9
	v_fma_f32 v9, v48, s20, -v5
	v_add_f32_e32 v8, 0, v7
	v_exp_f32_e32 v15, v9
	v_fma_f32 v9, v49, s20, -v5
	v_add_f32_e32 v8, v12, v8
	v_exp_f32_e32 v48, v9
	v_fma_f32 v9, v50, s20, -v5
	v_add_f32_e32 v8, v13, v8
	v_exp_f32_e32 v49, v9
	v_fma_f32 v9, v51, s20, -v5
	v_add_f32_e32 v8, v14, v8
	v_exp_f32_e32 v50, v9
	v_fma_f32 v9, v52, s20, -v5
	v_add_f32_e32 v8, v15, v8
	v_exp_f32_e32 v51, v9
	v_fma_f32 v9, v53, s20, -v5
	v_add_f32_e32 v8, v48, v8
	v_exp_f32_e32 v52, v9
	v_fma_f32 v9, v54, s20, -v5
	v_add_f32_e32 v8, v49, v8
	v_exp_f32_e32 v53, v9
	v_fma_f32 v9, v55, s20, -v5
	v_add_f32_e32 v8, v50, v8
	v_exp_f32_e32 v54, v9
	v_fma_f32 v9, v56, s20, -v5
	v_add_f32_e32 v8, v51, v8
	v_exp_f32_e32 v55, v9
	v_fma_f32 v9, v57, s20, -v5
	v_add_f32_e32 v8, v52, v8
	v_exp_f32_e32 v56, v9
	v_fma_f32 v9, v58, s20, -v5
	v_add_f32_e32 v8, v53, v8
	v_exp_f32_e32 v57, v9
	v_fma_f32 v9, v59, s20, -v5
	v_add_f32_e32 v8, v54, v8
	v_exp_f32_e32 v58, v9
	v_fma_f32 v9, v60, s20, -v5
	v_add_f32_e32 v8, v55, v8
	v_exp_f32_e32 v59, v9
	v_fma_f32 v9, v61, s20, -v5
	v_add_f32_e32 v8, v56, v8
	v_exp_f32_e32 v60, v9
	v_fma_f32 v9, v62, s20, -v5
	v_add_f32_e32 v8, v57, v8
	v_exp_f32_e32 v61, v9
	v_fma_f32 v9, v63, s20, -v5
	v_add_f32_e32 v8, v58, v8
	v_exp_f32_e32 v62, v9
	v_fma_f32 v9, v64, s20, -v5
	v_add_f32_e32 v8, v59, v8
	v_exp_f32_e32 v63, v9
	v_fma_f32 v9, v65, s20, -v5
	v_add_f32_e32 v8, v60, v8
	v_exp_f32_e32 v64, v9
	v_fma_f32 v9, v66, s20, -v5
	v_add_f32_e32 v8, v61, v8
	v_exp_f32_e32 v65, v9
	v_fma_f32 v9, v67, s20, -v5
	v_add_f32_e32 v8, v62, v8
	v_exp_f32_e32 v66, v9
	v_fma_f32 v9, v68, s20, -v5
	v_add_f32_e32 v8, v63, v8
	v_exp_f32_e32 v67, v9
	v_fma_f32 v9, v69, s20, -v5
	v_add_f32_e32 v8, v64, v8
	v_exp_f32_e32 v68, v9
	v_fma_f32 v9, v70, s20, -v5
	v_add_f32_e32 v8, v65, v8
	v_exp_f32_e32 v69, v9
	v_fma_f32 v9, v71, s20, -v5
	v_add_f32_e32 v8, v66, v8
	v_exp_f32_e32 v70, v9
	v_fma_f32 v9, v44, s20, -v5
	v_add_f32_e32 v8, v67, v8
	v_exp_f32_e32 v44, v9
	v_fma_f32 v9, v45, s20, -v5
	v_add_f32_e32 v8, v68, v8
	v_exp_f32_e32 v45, v9
	v_fma_f32 v9, v46, s20, -v5
	v_add_f32_e32 v8, v69, v8
	v_exp_f32_e32 v46, v9
	v_fma_f32 v9, v47, s20, -v5
	v_add_f32_e32 v8, v70, v8
	v_exp_f32_e32 v47, v9
	v_fma_f32 v9, v36, s20, -v5
	v_add_f32_e32 v8, v44, v8
	v_exp_f32_e32 v36, v9
	v_fma_f32 v9, v37, s20, -v5
	v_add_f32_e32 v8, v45, v8
	v_exp_f32_e32 v37, v9
	v_fma_f32 v9, v38, s20, -v5
	v_add_f32_e32 v8, v46, v8
	v_exp_f32_e32 v38, v9
	v_fma_f32 v9, v39, s20, -v5
	v_add_f32_e32 v8, v47, v8
	v_exp_f32_e32 v39, v9
	v_fma_f32 v9, v40, s20, -v5
	v_add_f32_e32 v8, v36, v8
	v_exp_f32_e32 v40, v9
	v_fma_f32 v9, v41, s20, -v5
	v_add_f32_e32 v8, v37, v8
	v_exp_f32_e32 v41, v9
	v_fma_f32 v9, v42, s20, -v5
	v_add_f32_e32 v8, v38, v8
	v_exp_f32_e32 v42, v9
	v_fma_f32 v9, v43, s20, -v5
	v_add_f32_e32 v8, v39, v8
	v_exp_f32_e32 v43, v9
	v_fma_f32 v9, v28, s20, -v5
	v_add_f32_e32 v8, v40, v8
	v_exp_f32_e32 v71, v9
	v_fma_f32 v9, v29, s20, -v5
	v_add_f32_e32 v8, v41, v8
	v_exp_f32_e32 v72, v9
	v_fma_f32 v9, v30, s20, -v5
	v_add_f32_e32 v8, v42, v8
	v_exp_f32_e32 v73, v9
	v_fma_f32 v9, v31, s20, -v5
	v_add_f32_e32 v8, v43, v8
	v_exp_f32_e32 v77, v9
	v_fma_f32 v9, v32, s20, -v5
	v_add_f32_e32 v8, v71, v8
	v_exp_f32_e32 v78, v9
	v_fma_f32 v9, v33, s20, -v5
	v_add_f32_e32 v8, v72, v8
	v_exp_f32_e32 v82, v9
	v_fma_f32 v9, v34, s20, -v5
	v_add_f32_e32 v8, v73, v8
	v_exp_f32_e32 v83, v9
	v_fma_f32 v9, v35, s20, -v5
	v_add_f32_e32 v8, v77, v8
	v_exp_f32_e32 v84, v9
	v_fma_f32 v9, v20, s20, -v5
	v_add_f32_e32 v8, v78, v8
	v_exp_f32_e32 v85, v9
	v_fma_f32 v9, v21, s20, -v5
	v_add_f32_e32 v8, v82, v8
	v_exp_f32_e32 v86, v9
	v_fma_f32 v9, v22, s20, -v5
	v_add_f32_e32 v8, v83, v8
	v_exp_f32_e32 v87, v9
	v_fma_f32 v9, v23, s20, -v5
	v_add_f32_e32 v8, v84, v8
	v_exp_f32_e32 v88, v9
	v_fma_f32 v9, v24, s20, -v5
	v_add_f32_e32 v8, v85, v8
	v_exp_f32_e32 v89, v9
	v_fma_f32 v9, v25, s20, -v5
	v_add_f32_e32 v8, v86, v8
	v_exp_f32_e32 v90, v9
	v_add_f32_e32 v8, v87, v8
	v_add_f32_e32 v8, v88, v8
	v_add_f32_e32 v8, v89, v8
	v_add_f32_e32 v28, v90, v8
	v_fma_f32 v8, v26, s20, -v5
	v_cvt_pk_bf16_f32 v12, v7, v12
	v_add_u32_e32 v7, s29, v137
	v_exp_f32_e32 v91, v8
	ds_read_b64_tr_b16 v[8:9], v10
	ds_read_b64_tr_b16 v[10:11], v10 offset:2048
	ds_read_b64_tr_b16 v[16:17], v7
	ds_read_b64_tr_b16 v[18:19], v7 offset:2048
	v_add_u32_e32 v7, s29, v138
	v_fma_f32 v24, v27, s20, -v5
	ds_read_b64_tr_b16 v[20:21], v7
	ds_read_b64_tr_b16 v[22:23], v7 offset:2048
	v_add_u32_e32 v7, s29, v139
	v_cvt_pk_bf16_f32 v13, v13, v14
	v_cvt_pk_bf16_f32 v14, v15, v48
	v_exp_f32_e32 v48, v24
	ds_read_b64_tr_b16 v[24:25], v7
	ds_read_b64_tr_b16 v[26:27], v7 offset:2048
	v_add_u32_e32 v30, s28, v136
	v_cvt_pk_bf16_f32 v15, v49, v50
	v_add_f32_e32 v7, v91, v28
	ds_read_b64_tr_b16 v[28:29], v30
	ds_read_b64_tr_b16 v[30:31], v30 offset:2048
	s_waitcnt lgkmcnt(8)
	v_mfma_f32_16x16x32_bf16 v[8:11], v[8:11], v[12:15], 0
	v_fma_f32 v49, v75, s20, -v5
	v_exp_f32_e32 v49, v49
	v_fma_f32 v50, v76, s20, -v5
	s_waitcnt lgkmcnt(6)
	v_mfma_f32_16x16x32_bf16 v[16:19], v[16:19], v[12:15], 0
	v_exp_f32_e32 v50, v50
	v_add_f32_e32 v7, v48, v7
	v_add_f32_e32 v7, v49, v7
	s_waitcnt lgkmcnt(4)
	v_mfma_f32_16x16x32_bf16 v[20:23], v[20:23], v[12:15], 0
	v_add_f32_e32 v7, v50, v7
	v_fma_f32 v6, v6, s20, -v5
	s_waitcnt lgkmcnt(2)
	v_mfma_f32_16x16x32_bf16 v[12:15], v[24:27], v[12:15], 0
	v_add_u32_e32 v25, s28, v137
	v_cvt_pk_bf16_f32 v24, v51, v52
	ds_read_b64_tr_b16 v[32:33], v25
	ds_read_b64_tr_b16 v[34:35], v25 offset:2048
	v_cvt_pk_bf16_f32 v25, v53, v54
	v_cvt_pk_bf16_f32 v26, v55, v56
	v_cvt_pk_bf16_f32 v27, v57, v58
	v_fma_f32 v51, v74, s20, -v5
	v_exp_f32_e32 v51, v51
	s_waitcnt lgkmcnt(2)
	v_mfma_f32_16x16x32_bf16 v[8:11], v[28:31], v[24:27], v[8:11]
	v_add_u32_e32 v30, s28, v138
	ds_read_b64_tr_b16 v[28:29], v30
	ds_read_b64_tr_b16 v[30:31], v30 offset:2048
	v_fma_f32 v52, v79, s20, -v5
	s_waitcnt lgkmcnt(2)
	v_mfma_f32_16x16x32_bf16 v[16:19], v[32:35], v[24:27], v[16:19]
	v_add_u32_e32 v34, s28, v139
	ds_read_b64_tr_b16 v[32:33], v34
	ds_read_b64_tr_b16 v[34:35], v34 offset:2048
	v_add_f32_e32 v7, v51, v7
	s_waitcnt lgkmcnt(2)
	v_mfma_f32_16x16x32_bf16 v[20:23], v[28:31], v[24:27], v[20:23]
	v_add_u32_e32 v30, s27, v136
	ds_read_b64_tr_b16 v[28:29], v30
	ds_read_b64_tr_b16 v[30:31], v30 offset:2048
	s_waitcnt lgkmcnt(2)
	v_mfma_f32_16x16x32_bf16 v[12:15], v[32:35], v[24:27], v[12:15]
	v_add_u32_e32 v25, s27, v137
	v_cvt_pk_bf16_f32 v24, v59, v60
	ds_read_b64_tr_b16 v[32:33], v25
	ds_read_b64_tr_b16 v[34:35], v25 offset:2048
	v_cvt_pk_bf16_f32 v25, v61, v62
	v_cvt_pk_bf16_f32 v26, v63, v64
	v_cvt_pk_bf16_f32 v27, v65, v66
	s_waitcnt lgkmcnt(2)
	s_nop 0
	v_mfma_f32_16x16x32_bf16 v[8:11], v[28:31], v[24:27], v[8:11]
	v_add_u32_e32 v30, s27, v138
	ds_read_b64_tr_b16 v[28:29], v30
	ds_read_b64_tr_b16 v[30:31], v30 offset:2048
	s_waitcnt lgkmcnt(2)
	v_mfma_f32_16x16x32_bf16 v[16:19], v[32:35], v[24:27], v[16:19]
	v_add_u32_e32 v34, s27, v139
	ds_read_b64_tr_b16 v[32:33], v34
	ds_read_b64_tr_b16 v[34:35], v34 offset:2048
	s_waitcnt lgkmcnt(2)
	v_mfma_f32_16x16x32_bf16 v[20:23], v[28:31], v[24:27], v[20:23]
	v_add_u32_e32 v30, s25, v136
	ds_read_b64_tr_b16 v[28:29], v30
	ds_read_b64_tr_b16 v[30:31], v30 offset:2048
	s_waitcnt lgkmcnt(2)
	v_mfma_f32_16x16x32_bf16 v[12:15], v[32:35], v[24:27], v[12:15]
	v_add_u32_e32 v25, s25, v137
	v_cvt_pk_bf16_f32 v24, v67, v68
	ds_read_b64_tr_b16 v[32:33], v25
	ds_read_b64_tr_b16 v[34:35], v25 offset:2048
	v_cvt_pk_bf16_f32 v25, v69, v70
	v_cvt_pk_bf16_f32 v26, v44, v45
	v_cvt_pk_bf16_f32 v27, v46, v47
	v_exp_f32_e32 v44, v52
	v_fma_f32 v45, v80, s20, -v5
	s_waitcnt lgkmcnt(2)
	v_mfma_f32_16x16x32_bf16 v[8:11], v[28:31], v[24:27], v[8:11]
	v_add_u32_e32 v30, s25, v138
	ds_read_b64_tr_b16 v[28:29], v30
	ds_read_b64_tr_b16 v[30:31], v30 offset:2048
	v_add_f32_e32 v7, v44, v7
	s_waitcnt lgkmcnt(2)
	v_mfma_f32_16x16x32_bf16 v[16:19], v[32:35], v[24:27], v[16:19]
	v_add_u32_e32 v34, s25, v139
	ds_read_b64_tr_b16 v[32:33], v34
	ds_read_b64_tr_b16 v[34:35], v34 offset:2048
	s_waitcnt lgkmcnt(2)
	v_mfma_f32_16x16x32_bf16 v[20:23], v[28:31], v[24:27], v[20:23]
	v_add_u32_e32 v30, s24, v136
	ds_read_b64_tr_b16 v[28:29], v30
	ds_read_b64_tr_b16 v[30:31], v30 offset:2048
	s_waitcnt lgkmcnt(2)
	v_mfma_f32_16x16x32_bf16 v[12:15], v[32:35], v[24:27], v[12:15]
	v_add_u32_e32 v25, s24, v137
	v_cvt_pk_bf16_f32 v24, v36, v37
	ds_read_b64_tr_b16 v[32:33], v25
	ds_read_b64_tr_b16 v[34:35], v25 offset:2048
	v_cvt_pk_bf16_f32 v25, v38, v39
	v_cvt_pk_bf16_f32 v26, v40, v41
	v_cvt_pk_bf16_f32 v27, v42, v43
	v_exp_f32_e32 v36, v45
	v_fma_f32 v37, v81, s20, -v5
	s_waitcnt lgkmcnt(2)
	v_mfma_f32_16x16x32_bf16 v[8:11], v[28:31], v[24:27], v[8:11]
	v_add_u32_e32 v30, s24, v138
	ds_read_b64_tr_b16 v[28:29], v30
	ds_read_b64_tr_b16 v[30:31], v30 offset:2048
	v_exp_f32_e32 v37, v37
	s_waitcnt lgkmcnt(2)
	v_mfma_f32_16x16x32_bf16 v[16:19], v[32:35], v[24:27], v[16:19]
	v_add_u32_e32 v34, s24, v139
	ds_read_b64_tr_b16 v[32:33], v34
	ds_read_b64_tr_b16 v[34:35], v34 offset:2048
	v_add_f32_e32 v7, v36, v7
	s_waitcnt lgkmcnt(2)
	v_mfma_f32_16x16x32_bf16 v[20:23], v[28:31], v[24:27], v[20:23]
	v_add_u32_e32 v30, s23, v136
	ds_read_b64_tr_b16 v[28:29], v30
	ds_read_b64_tr_b16 v[30:31], v30 offset:2048
	v_add_f32_e32 v38, v37, v7
	s_waitcnt lgkmcnt(2)
	v_mfma_f32_16x16x32_bf16 v[12:15], v[32:35], v[24:27], v[12:15]
	v_add_u32_e32 v25, s23, v137
	v_cvt_pk_bf16_f32 v24, v71, v72
	ds_read_b64_tr_b16 v[32:33], v25
	ds_read_b64_tr_b16 v[34:35], v25 offset:2048
	v_cvt_pk_bf16_f32 v25, v73, v77
	v_cvt_pk_bf16_f32 v26, v78, v82
	v_cvt_pk_bf16_f32 v27, v83, v84
	v_add_u32_e32 v7, s23, v139
	v_exp_f32_e32 v39, v6
	s_waitcnt lgkmcnt(2)
	v_mfma_f32_16x16x32_bf16 v[8:11], v[28:31], v[24:27], v[8:11]
	v_add_u32_e32 v30, s23, v138
	ds_read_b64_tr_b16 v[28:29], v30
	ds_read_b64_tr_b16 v[30:31], v30 offset:2048
	v_sub_f32_e32 v40, v4, v5
	s_waitcnt lgkmcnt(2)
	v_mfma_f32_16x16x32_bf16 v[16:19], v[32:35], v[24:27], v[16:19]
	ds_read_b64_tr_b16 v[32:33], v7
	ds_read_b64_tr_b16 v[34:35], v7 offset:2048
	s_waitcnt lgkmcnt(2)
	v_mfma_f32_16x16x32_bf16 v[4:7], v[28:31], v[24:27], v[20:23]
	s_nop 2
	v_add_u32_e32 v22, s22, v136
	ds_read_b64_tr_b16 v[20:21], v22
	ds_read_b64_tr_b16 v[22:23], v22 offset:2048
	s_waitcnt lgkmcnt(2)
	v_mfma_f32_16x16x32_bf16 v[12:15], v[32:35], v[24:27], v[12:15]
	v_add_u32_e32 v25, s22, v137
	v_cvt_pk_bf16_f32 v24, v85, v86
	ds_read_b64_tr_b16 v[28:29], v25
	ds_read_b64_tr_b16 v[30:31], v25 offset:2048
	v_cvt_pk_bf16_f32 v25, v87, v88
	v_cvt_pk_bf16_f32 v26, v89, v90
	v_cvt_pk_bf16_f32 v27, v91, v48
	v_exp_f32_e32 v32, v40
	v_add_f32_e32 v33, v39, v38
	s_waitcnt lgkmcnt(2)
	v_mfma_f32_16x16x32_bf16 v[8:11], v[20:23], v[24:27], v[8:11]
	v_add_u32_e32 v22, s22, v138
	ds_read_b64_tr_b16 v[20:21], v22
	ds_read_b64_tr_b16 v[22:23], v22 offset:2048
	v_add_f32_e32 v33, v32, v33
	s_waitcnt lgkmcnt(2)
	v_mfma_f32_16x16x32_bf16 v[16:19], v[28:31], v[24:27], v[16:19]
	v_add_u32_e32 v30, s22, v139
	ds_read_b64_tr_b16 v[28:29], v30
	ds_read_b64_tr_b16 v[30:31], v30 offset:2048
	v_mov_b32_e32 v34, v33
	s_nop 1
	v_permlane16_swap_b32 v33, v34
	s_waitcnt lgkmcnt(3)
	v_mfma_f32_16x16x32_bf16 v[4:7], v[20:23], v[24:27], v[4:7]
	v_add_u32_e32 v22, s18, v136
	ds_read_b64_tr_b16 v[20:21], v22
	ds_read_b64_tr_b16 v[22:23], v22 offset:2048
	s_waitcnt lgkmcnt(3)
	v_mfma_f32_16x16x32_bf16 v[12:15], v[28:31], v[24:27], v[12:15]
	v_add_u32_e32 v27, s18, v137
	v_cvt_pk_bf16_f32 v24, v49, v50
	v_cvt_pk_bf16_f32 v25, v51, v44
	v_cvt_pk_bf16_f32 v26, v36, v37
	ds_read_b64_tr_b16 v[28:29], v27
	ds_read_b64_tr_b16 v[30:31], v27 offset:2048
	v_cvt_pk_bf16_f32 v27, v39, v32
	s_waitcnt lgkmcnt(4)
	v_add_f32_e32 v32, v33, v34
	ds_bpermute_b32 v33, v94, v32
	s_waitcnt lgkmcnt(3)
	v_mfma_f32_16x16x32_bf16 v[8:11], v[20:23], v[24:27], v[8:11]
	v_add_u32_e32 v22, s18, v138
	ds_read_b64_tr_b16 v[20:21], v22
	ds_read_b64_tr_b16 v[22:23], v22 offset:2048
	s_waitcnt lgkmcnt(0)
	v_mfma_f32_16x16x32_bf16 v[4:7], v[20:23], v[24:27], v[4:7]
	v_add_f32_e32 v20, v32, v33
	v_div_scale_f32 v21, s[22:23], v20, v20, 1.0
	v_mfma_f32_16x16x32_bf16 v[16:19], v[28:31], v[24:27], v[16:19]
	v_add_u32_e32 v30, s18, v139
	v_rcp_f32_e32 v22, v21
	ds_read_b64_tr_b16 v[28:29], v30
	ds_read_b64_tr_b16 v[30:31], v30 offset:2048
	s_waitcnt lgkmcnt(0)
	v_mfma_f32_16x16x32_bf16 v[12:15], v[28:31], v[24:27], v[12:15]
	v_fma_f32 v23, -v21, v22, 1.0
	v_fmac_f32_e32 v22, v23, v22
	v_div_scale_f32 v23, vcc, 1.0, v20, 1.0
	v_mul_f32_e32 v24, v23, v22
	v_fma_f32 v25, -v21, v24, v23
	v_fmac_f32_e32 v24, v25, v22
	v_fma_f32 v21, -v21, v24, v23
	v_div_fmas_f32 v21, v21, v22, v24
	s_lshl_b32 s18, s26, 6
	v_div_fixup_f32 v20, v21, v20, 1.0
	v_lshl_add_u64 v[22:23], v[130:131], 0, s[18:19]
	v_mad_u64_u32 v[24:25], s[22:23], v22, s55, v[92:93]
	v_pk_mul_f32 v[8:9], v[20:21], v[8:9] op_sel_hi:[0,1]
	v_pk_mul_f32 v[10:11], v[20:21], v[10:11] op_sel_hi:[0,1]
	v_pk_mul_f32 v[4:5], v[20:21], v[4:5] op_sel_hi:[0,1]
	v_pk_mul_f32 v[6:7], v[20:21], v[6:7] op_sel_hi:[0,1]
	v_mad_i32_i24 v25, v23, s55, v25
	v_cvt_pk_bf16_f32 v8, v8, v9
	v_cvt_pk_bf16_f32 v9, v10, v11
	v_cvt_pk_bf16_f32 v4, v4, v5
	v_cvt_pk_bf16_f32 v5, v6, v7
	global_store_dwordx2 v[24:25], v[8:9], off
	v_pk_mul_f32 v[8:9], v[20:21], v[16:17] op_sel_hi:[0,1]
	v_pk_mul_f32 v[10:11], v[20:21], v[18:19] op_sel_hi:[0,1]
	global_store_dwordx2 v[24:25], v[4:5], off offset:64
	v_pk_mul_f32 v[4:5], v[20:21], v[12:13] op_sel_hi:[0,1]
	v_pk_mul_f32 v[6:7], v[20:21], v[14:15] op_sel_hi:[0,1]
	v_cvt_pk_bf16_f32 v8, v8, v9
	v_cvt_pk_bf16_f32 v9, v10, v11
	v_cvt_pk_bf16_f32 v4, v4, v5
	v_cvt_pk_bf16_f32 v5, v6, v7
	s_cmpk_gt_i32 s60, 0xff
	global_store_dwordx2 v[24:25], v[8:9], off offset:32
	global_store_dwordx2 v[24:25], v[4:5], off offset:96
	s_cbranch_scc1 .LBB0_596

.LBB0_584:
	s_or_b64 exec, exec, s[22:23]
	s_ashr_i32 s26, s60, 5
	s_lshl_b32 s18, s26, 3
	s_or_b32 s22, s18, s38
	s_lshl_b32 s18, s60, 3
	s_ashr_i32 s23, s22, 31
	s_and_b32 s28, s18, 24
	s_lshl_b64 s[22:23], s[22:23], 18
	v_sub_u32_e64 v42, s28, 4 clamp
	v_lshl_add_u64 v[6:7], v[118:119], 0, s[22:23]
	v_lshl_add_u64 v[4:5], v[120:121], 0, s[22:23]
	s_max_u32 s35, s28, 4
	v_lshlrev_b32_e32 v124, 13, v42
	v_lshl_add_u64 v[8:9], v[6:7], 0, v[124:125]
	v_lshl_add_u64 v[12:13], v[4:5], 0, v[124:125]
	s_add_i32 s18, s35, -3
	global_load_dwordx4 v[8:11], v[8:9], off
	s_nop 0
	global_load_dwordx4 v[12:15], v[12:13], off
	s_lshl_b64 s[22:23], s[18:19], 13
	v_lshl_add_u64 v[16:17], v[6:7], 0, s[22:23]
	global_load_dwordx4 v[16:19], v[16:17], off
	s_add_i32 s24, s35, -2
	s_mov_b32 s25, s19
	v_lshl_add_u64 v[20:21], v[4:5], 0, s[22:23]
	s_lshl_b64 s[22:23], s[24:25], 13
	global_load_dwordx4 v[20:23], v[20:21], off
	v_lshl_add_u64 v[24:25], v[6:7], 0, s[22:23]
	global_load_dwordx4 v[24:27], v[24:25], off
	v_lshl_add_u64 v[28:29], v[4:5], 0, s[22:23]
	s_add_i32 s22, s35, -1
	s_mov_b32 s23, s19
	s_lshl_b64 s[50:51], s[22:23], 13
	global_load_dwordx4 v[28:31], v[28:29], off
	v_lshl_add_u64 v[32:33], v[6:7], 0, s[50:51]
	global_load_dwordx4 v[32:35], v[32:33], off
	v_lshl_add_u64 v[36:37], v[4:5], 0, s[50:51]
	global_load_dwordx4 v[36:39], v[36:37], off
	v_mul_lo_u32 v40, v42, 57
	s_mul_i32 s39, s18, 57
	v_lshrrev_b32_e32 v40, 9, v40
	s_bfe_u32 s39, s39, 0x70009
	v_mul_lo_u32 v43, v40, 9
	s_mul_i32 s39, s39, 9
	s_or_b32 s25, s35, 1
	s_or_b32 s27, s35, 2
	s_or_b32 s29, s35, 3
	s_add_i32 s34, s35, 4
	v_sub_u32_e32 v80, v42, v43
	s_sub_i32 s18, s18, s39
	s_mov_b32 s51, s19
	s_mov_b32 s63, s19
	s_mov_b32 s65, s19
	s_mov_b32 s67, s19
	s_mov_b32 s69, s19
	s_lshl_b32 s50, s35, 13
	s_lshl_b32 s62, s25, 13
	s_lshl_b32 s64, s27, 13
	s_lshl_b32 s66, s29, 13
	s_lshl_b32 s68, s34, 13
	v_lshlrev_b32_sdwa v80, v155, v80 dst_sel:DWORD dst_unused:UNUSED_PAD src0_sel:DWORD src1_sel:BYTE_0
	s_and_b32 s18, s18, 0xff
	s_mul_i32 s23, s35, 57
	v_lshl_add_u64 v[40:41], v[6:7], 0, s[50:51]
	v_lshl_add_u64 v[44:45], v[4:5], 0, s[50:51]
	v_lshl_add_u64 v[48:49], v[6:7], 0, s[62:63]
	v_lshl_add_u64 v[52:53], v[4:5], 0, s[62:63]
	v_lshl_add_u64 v[56:57], v[6:7], 0, s[64:65]
	v_lshl_add_u64 v[60:61], v[4:5], 0, s[64:65]
	v_lshl_add_u64 v[64:65], v[6:7], 0, s[66:67]
	v_lshl_add_u64 v[68:69], v[4:5], 0, s[66:67]
	v_lshl_add_u64 v[72:73], v[6:7], 0, s[68:69]
	v_lshl_add_u64 v[76:77], v[4:5], 0, s[68:69]
	v_add_u32_e32 v81, v1, v80
	s_lshl_b32 s18, s18, 13
	global_load_dwordx4 v[40:43], v[40:41], off
	s_nop 0
	global_load_dwordx4 v[44:47], v[44:45], off
	s_nop 0
	global_load_dwordx4 v[48:51], v[48:49], off
	s_nop 0
	global_load_dwordx4 v[52:55], v[52:53], off
	s_nop 0
	global_load_dwordx4 v[56:59], v[56:57], off
	s_nop 0
	global_load_dwordx4 v[60:63], v[60:61], off
	s_nop 0
	global_load_dwordx4 v[64:67], v[64:65], off
	s_nop 0
	global_load_dwordx4 v[68:71], v[68:69], off
	s_nop 0
	global_load_dwordx4 v[72:75], v[72:73], off
	s_nop 0
	global_load_dwordx4 v[76:79], v[76:77], off
	v_add_u32_e32 v80, v123, v80
	v_add_u32_e32 v82, s18, v1
	v_mov_b32_e32 v127, v125
	v_xor_b32_e32 v129, 16, v159
	s_waitcnt vmcnt(17)
	ds_write_b128 v81, v[8:11]
	s_waitcnt vmcnt(16)
	ds_write_b128 v80, v[12:15]
	s_waitcnt vmcnt(15)
	ds_write_b128 v82, v[16:19]
	v_add_u32_e32 v8, s18, v123
	s_add_i32 s18, s23, 0xffffff8e
	s_bfe_u32 s18, s18, 0x70009
	s_mul_i32 s18, s18, 9
	s_sub_i32 s18, s24, s18
	s_and_b32 s18, s18, 0xff
	s_lshl_b32 s18, s18, 13
	s_waitcnt vmcnt(14)
	ds_write_b128 v8, v[20:23]
	v_add_u32_e32 v8, s18, v1
	s_waitcnt vmcnt(13)
	ds_write_b128 v8, v[24:27]
	v_add_u32_e32 v8, s18, v123
	s_sub_i32 s18, s23, 57
	s_bfe_u32 s18, s18, 0x70009
	s_mul_i32 s18, s18, 9
	s_sub_i32 s18, s22, s18
	s_and_b32 s18, s18, 0xff
	s_lshl_b32 s18, s18, 13
	s_waitcnt vmcnt(12)
	ds_write_b128 v8, v[28:31]
	v_add_u32_e32 v8, s18, v1
	s_waitcnt vmcnt(11)
	ds_write_b128 v8, v[32:35]
	v_add_u32_e32 v8, s18, v123
	s_mul_i32 s18, s35, 29
	s_lshr_b32 s18, s18, 8
	s_mul_i32 s18, s18, 9
	s_sub_i32 s18, s35, s18
	s_and_b32 s18, s18, 0xff
	s_lshl_b32 s65, s18, 13
	s_mul_i32 s18, s25, 29
	s_lshr_b32 s18, s18, 8
	s_mul_i32 s18, s18, 9
	s_sub_i32 s18, s25, s18
	s_and_b32 s18, s18, 0xff
	s_lshl_b32 s68, s18, 13
	s_mul_i32 s18, s27, 29
	s_lshr_b32 s18, s18, 8
	s_mul_i32 s18, s18, 9
	s_sub_i32 s18, s27, s18
	s_and_b32 s18, s18, 0xff
	s_lshl_b32 s69, s18, 13
	s_mul_i32 s18, s29, 29
	s_lshr_b32 s18, s18, 8
	s_mul_i32 s18, s18, 9
	s_sub_i32 s18, s29, s18
	s_and_b32 s18, s18, 0xff
	s_addk_i32 s23, 0xe4
	s_lshl_b32 s70, s18, 13
	s_lshr_b32 s18, s23, 9
	s_mul_i32 s18, s18, 9
	s_sub_i32 s18, s34, s18
	s_waitcnt vmcnt(10)
	ds_write_b128 v8, v[36:39]
	s_and_b32 s18, s18, 0xff
	v_sub_u32_e64 v8, s28, 1 clamp
	s_lshl_b32 s71, s18, 13
	v_readfirstlane_b32 s18, v8
	s_ashr_i32 s27, s26, 31
	s_add_i32 s18, s18, 7
	s_cmp_lt_u32 s34, s18
	s_cselect_b64 s[24:25], -1, 0
	v_cndmask_b32_e64 v8, 0, 1, s[24:25]
	s_add_i32 s35, s35, 5
	v_readfirstlane_b32 s22, v8
	s_or_b32 s29, s34, s22
	s_cmp_lt_u32 s29, s18
	s_cselect_b64 s[22:23], -1, 0
	s_add_i32 s34, s29, 1
	s_cmp_lg_u64 s[22:23], 0
	s_addc_u32 s18, s29, 0
	s_or_b32 s39, s28, 1
	s_min_u32 s39, s39, 24
	s_add_i32 s39, s39, 7
	s_cmp_lt_u32 s18, s39
	s_cselect_b64 s[50:51], -1, 0
	s_cmp_lg_u64 s[22:23], 0
	v_cndmask_b32_e64 v162, 0, 1, s[22:23]
	s_addc_u32 s64, s29, 1
	v_readfirstlane_b32 s22, v162
	s_cmp_lg_u64 s[50:51], 0
	s_addc_u32 s29, s29, s22
	s_cmp_lt_u32 s29, s39
	s_cselect_b64 s[22:23], -1, 0
	s_min_u32 s63, s29, 30
	v_cndmask_b32_e64 v161, 0, 1, s[50:51]
	s_add_i32 s63, s63, 1
	v_readfirstlane_b32 s39, v161
	s_cmp_lg_u64 s[22:23], 0
	v_cndmask_b32_e64 v160, 0, 1, s[22:23]
	s_addc_u32 s18, s18, s39
	s_or_b32 s22, s28, 3
	s_min_u32 s50, s22, 24
	s_add_i32 s50, s50, 7
	s_cmp_lt_u32 s18, s50
	s_cselect_b64 s[22:23], -1, 0
	s_min_u32 s62, s18, 30
	s_add_i32 s62, s62, 1
	v_readfirstlane_b32 s18, v160
	s_cmp_lg_u64 s[22:23], 0
	s_addc_u32 s61, s29, s18
	s_lshl_b32 s18, s35, 13
	v_lshl_add_u64 v[8:9], v[6:7], 0, s[18:19]
	v_lshl_add_u64 v[10:11], v[4:5], 0, s[18:19]
	s_lshl_b32 s18, s34, 13
	v_lshl_add_u64 v[12:13], v[6:7], 0, s[18:19]
	v_lshl_add_u64 v[14:15], v[4:5], 0, s[18:19]
	s_lshl_b32 s18, s64, 13
	s_min_u32 s51, s61, 30
	v_lshl_add_u64 v[16:17], v[6:7], 0, s[18:19]
	v_lshl_add_u64 v[18:19], v[4:5], 0, s[18:19]
	s_lshl_b32 s18, s63, 13
	s_add_i32 s51, s51, 1
	v_lshl_add_u64 v[20:21], v[6:7], 0, s[18:19]
	v_lshl_add_u64 v[22:23], v[4:5], 0, s[18:19]
	s_lshl_b32 s18, s62, 13
	v_lshl_add_u64 v[24:25], v[6:7], 0, s[18:19]
	v_lshl_add_u64 v[28:29], v[4:5], 0, s[18:19]
	s_lshl_b32 s18, s51, 13
	s_lshl_b64 s[66:67], s[26:27], 11
	v_lshl_add_u64 v[6:7], v[6:7], 0, s[18:19]
	v_lshl_add_u64 v[4:5], v[4:5], 0, s[18:19]
	s_add_i32 s26, s28, s3
	s_lshl_b32 s18, s38, 7
	s_add_u32 s28, s30, s18
	v_mov_b32_e32 v131, s67
	v_or_b32_e32 v130, s66, v122
	s_addc_u32 s29, s31, 0
	s_lshl_b32 s18, s26, 6
	v_lshl_add_u64 v[30:31], s[28:29], 0, v[126:127]
	v_lshl_add_u64 v[132:133], v[130:131], 0, s[18:19]
	v_mad_u64_u32 v[26:27], s[38:39], v132, s55, v[30:31]
	v_mad_i32_i24 v27, v133, s55, v27
	global_load_dwordx4 v[80:83], v[26:27], off
	global_load_dwordx4 v[164:167], v[26:27], off offset:64
	v_add_u32_e32 v32, s65, v1
	s_waitcnt vmcnt(11)
	ds_write_b128 v32, v[40:43]
	v_add_u32_e32 v32, s65, v123
	s_waitcnt vmcnt(10)
	ds_write_b128 v32, v[44:47]
	v_add_u32_e32 v32, s68, v1
	s_waitcnt vmcnt(9)
	ds_write_b128 v32, v[48:51]
	v_add_u32_e32 v32, s68, v123
	v_add_u32_e32 v26, s69, v123
	s_waitcnt vmcnt(8)
	ds_write_b128 v32, v[52:55]
	v_add_u32_e32 v32, s69, v1
	s_waitcnt vmcnt(6)
	ds_write_b128 v26, v[60:63]
	v_add_u32_e32 v26, s70, v1
	ds_write_b128 v32, v[56:59]
	s_waitcnt vmcnt(5)
	ds_write_b128 v26, v[64:67]
	v_add_u32_e32 v26, s70, v123
	s_waitcnt vmcnt(4)
	ds_write_b128 v26, v[68:71]
	v_add_u32_e32 v26, s71, v1
	s_waitcnt vmcnt(3)
	ds_write_b128 v26, v[72:75]
	v_add_u32_e32 v26, s71, v123
	s_waitcnt vmcnt(2)
	ds_write_b128 v26, v[76:79]
	s_add_i32 s38, s18, 0x80
	s_mov_b32 s39, s19
	global_load_dwordx4 v[72:75], v[8:9], off
	global_load_dwordx4 v[68:71], v[10:11], off
	global_load_dwordx4 v[64:67], v[12:13], off
	global_load_dwordx4 v[60:63], v[14:15], off
	global_load_dwordx4 v[48:51], v[16:17], off
	global_load_dwordx4 v[44:47], v[18:19], off
	global_load_dwordx4 v[40:43], v[20:21], off
	global_load_dwordx4 v[36:39], v[22:23], off
	s_nop 0
	global_load_dwordx4 v[24:27], v[24:25], off
	s_nop 0
	global_load_dwordx4 v[20:23], v[28:29], off
	global_load_dwordx4 v[16:19], v[6:7], off
	global_load_dwordx4 v[12:15], v[4:5], off
	v_lshl_add_u64 v[4:5], v[130:131], 0, s[38:39]
	v_mad_u64_u32 v[6:7], s[38:39], v4, s55, v[30:31]
	s_add_i32 s38, s18, 0x100
	s_mov_b32 s39, s19
	v_mad_i32_i24 v7, v5, s55, v7
	v_lshl_add_u64 v[4:5], v[130:131], 0, s[38:39]
	v_mad_u64_u32 v[8:9], s[38:39], v4, s55, v[30:31]
	s_addk_i32 s18, 0x180
	v_mad_i32_i24 v9, v5, s55, v9
	v_lshl_add_u64 v[4:5], v[130:131], 0, s[18:19]
	s_max_i32 s18, s26, 4
	s_add_i32 s18, s18, -4
	s_min_u32 s69, s18, 24
	s_mul_i32 s18, s69, 29
	s_lshr_b32 s18, s18, 8
	s_mul_i32 s18, s18, 9
	s_sub_i32 s18, s69, s18
	s_and_b32 s18, s18, 0xff
	v_mad_u64_u32 v[10:11], s[38:39], v4, s55, v[30:31]
	s_lshl_b32 s68, s18, 13
	v_mad_i32_i24 v11, v5, s55, v11
	s_add_i32 s18, s68, 0x100
	global_load_dwordx4 v[52:55], v[6:7], off offset:64
	global_load_dwordx4 v[56:59], v[6:7], off
	global_load_dwordx4 v[28:31], v[8:9], off offset:64
	global_load_dwordx4 v[32:35], v[8:9], off
	s_nop 0
	global_load_dwordx4 v[4:7], v[10:11], off offset:64
	s_nop 0
	global_load_dwordx4 v[8:11], v[10:11], off
	s_waitcnt lgkmcnt(0)
	s_barrier
	v_add_u32_e32 v84, s18, v134
	ds_read_b128 v[76:79], v84
	ds_read_b128 v[84:87], v84 offset:2048
	v_add_u32_e32 v92, s18, v135
	s_mul_i32 s18, s69, 57
	s_add_i32 s27, s18, 57
	s_waitcnt vmcnt(19) lgkmcnt(1)
	v_mfma_f32_16x16x32_bf16 v[76:79], v[76:79], v[80:83], 0
	ds_read_b128 v[88:91], v92
	ds_read_b128 v[92:95], v92 offset:2048
	s_bfe_u32 s27, s27, 0x30009
	s_mul_i32 s27, s27, 9
	s_sub_i32 s27, s69, s27
	s_add_i32 s27, s27, 1
	s_waitcnt vmcnt(18) lgkmcnt(1)
	v_mfma_f32_16x16x32_bf16 v[168:171], v[88:91], v[164:167], v[76:79]
	s_and_b32 s27, s27, 0xff
	s_lshl_b32 s67, s27, 13
	s_add_i32 s27, s67, 0x100
	v_mfma_f32_16x16x32_bf16 v[76:79], v[84:87], v[80:83], 0
	v_add_u32_e32 v84, s27, v134
	s_add_i32 s68, s53, s68
	s_add_i32 s67, s53, s67
	s_waitcnt lgkmcnt(0)
	v_mfma_f32_16x16x32_bf16 v[172:175], v[92:95], v[164:167], v[76:79]
	v_add_u32_e32 v92, s27, v135
	s_add_i32 s27, s18, 0x72
	s_bfe_u32 s27, s27, 0x30009
	ds_read_b128 v[76:79], v84
	ds_read_b128 v[84:87], v84 offset:2048
	s_waitcnt lgkmcnt(1)
	v_mfma_f32_16x16x32_bf16 v[76:79], v[76:79], v[80:83], 0
	ds_read_b128 v[88:91], v92
	ds_read_b128 v[92:95], v92 offset:2048
	s_mul_i32 s27, s27, 9
	s_sub_i32 s27, s69, s27
	s_add_i32 s27, s27, 2
	s_waitcnt lgkmcnt(1)
	v_mfma_f32_16x16x32_bf16 v[176:179], v[88:91], v[164:167], v[76:79]
	s_and_b32 s27, s27, 0xff
	s_lshl_b32 s66, s27, 13
	s_add_i32 s27, s66, 0x100
	v_mfma_f32_16x16x32_bf16 v[76:79], v[84:87], v[80:83], 0
	v_add_u32_e32 v84, s27, v134
	s_add_i32 s66, s53, s66
	s_waitcnt lgkmcnt(0)
	v_mfma_f32_16x16x32_bf16 v[180:183], v[92:95], v[164:167], v[76:79]
	v_add_u32_e32 v92, s27, v135
	s_add_i32 s27, s18, 0xab
	s_bfe_u32 s27, s27, 0x30009
	s_nop 0
	ds_read_b128 v[76:79], v84
	ds_read_b128 v[84:87], v84 offset:2048
	s_waitcnt lgkmcnt(1)
	v_mfma_f32_16x16x32_bf16 v[76:79], v[76:79], v[80:83], 0
	ds_read_b128 v[88:91], v92
	ds_read_b128 v[92:95], v92 offset:2048
	s_mul_i32 s27, s27, 9
	s_sub_i32 s27, s69, s27
	s_add_i32 s27, s27, 3
	s_waitcnt lgkmcnt(1)
	v_mfma_f32_16x16x32_bf16 v[198:201], v[88:91], v[164:167], v[76:79]
	s_and_b32 s27, s27, 0xff
	s_lshl_b32 s65, s27, 13
	s_add_i32 s27, s65, 0x100
	v_mfma_f32_16x16x32_bf16 v[76:79], v[84:87], v[80:83], 0
	v_add_u32_e32 v84, s27, v134
	s_add_i32 s65, s53, s65
	s_waitcnt lgkmcnt(0)
	v_mfma_f32_16x16x32_bf16 v[202:205], v[92:95], v[164:167], v[76:79]
	v_add_u32_e32 v92, s27, v135
	s_add_i32 s27, s18, 0xe4
	s_bfe_u32 s27, s27, 0x30009
	s_nop 0
	ds_read_b128 v[76:79], v84
	ds_read_b128 v[84:87], v84 offset:2048
	s_waitcnt lgkmcnt(1)
	v_mfma_f32_16x16x32_bf16 v[76:79], v[76:79], v[80:83], 0
	ds_read_b128 v[88:91], v92
	ds_read_b128 v[92:95], v92 offset:2048
	s_mul_i32 s27, s27, 9
	s_sub_i32 s27, s69, s27
	s_add_i32 s27, s27, 4
	s_waitcnt lgkmcnt(1)
	v_mfma_f32_16x16x32_bf16 v[112:115], v[88:91], v[164:167], v[76:79]
	s_and_b32 s27, s27, 0xff
	s_lshl_b32 s39, s27, 13
	s_add_i32 s27, s39, 0x100
	v_mfma_f32_16x16x32_bf16 v[76:79], v[84:87], v[80:83], 0
	v_add_u32_e32 v84, s27, v134
	s_add_i32 s39, s53, s39
	s_waitcnt lgkmcnt(0)
	v_mfma_f32_16x16x32_bf16 v[108:111], v[92:95], v[164:167], v[76:79]
	v_add_u32_e32 v92, s27, v135
	s_add_i32 s27, s18, 0x11d
	s_bfe_u32 s27, s27, 0x30009
	s_nop 0
	ds_read_b128 v[76:79], v84
	ds_read_b128 v[84:87], v84 offset:2048
	s_waitcnt lgkmcnt(1)
	v_mfma_f32_16x16x32_bf16 v[76:79], v[76:79], v[80:83], 0
	ds_read_b128 v[88:91], v92
	ds_read_b128 v[92:95], v92 offset:2048
	s_mul_i32 s27, s27, 9
	s_sub_i32 s27, s69, s27
	s_add_i32 s27, s27, 5
	s_waitcnt lgkmcnt(1)
	v_mfma_f32_16x16x32_bf16 v[104:107], v[88:91], v[164:167], v[76:79]
	s_and_b32 s27, s27, 0xff
	s_lshl_b32 s38, s27, 13
	s_add_i32 s27, s38, 0x100
	v_mfma_f32_16x16x32_bf16 v[76:79], v[84:87], v[80:83], 0
	v_add_u32_e32 v84, s27, v134
	s_add_i32 s38, s53, s38
	s_waitcnt lgkmcnt(0)
	v_mfma_f32_16x16x32_bf16 v[100:103], v[92:95], v[164:167], v[76:79]
	v_add_u32_e32 v92, s27, v135
	s_add_i32 s27, s18, 0x156
	s_bfe_u32 s27, s27, 0x30009
	s_nop 0
	ds_read_b128 v[76:79], v84
	ds_read_b128 v[84:87], v84 offset:2048
	s_waitcnt lgkmcnt(1)
	v_mfma_f32_16x16x32_bf16 v[76:79], v[76:79], v[80:83], 0
	ds_read_b128 v[88:91], v92
	ds_read_b128 v[92:95], v92 offset:2048
	s_mul_i32 s27, s27, 9
	s_sub_i32 s27, s69, s27
	s_add_i32 s27, s27, 6
	s_waitcnt lgkmcnt(1)
	v_mfma_f32_16x16x32_bf16 v[96:99], v[88:91], v[164:167], v[76:79]
	s_and_b32 s27, s27, 0xff
	s_lshl_b32 s27, s27, 13
	s_add_i32 s70, s27, 0x100
	v_mfma_f32_16x16x32_bf16 v[76:79], v[84:87], v[80:83], 0
	v_add_u32_e32 v84, s70, v134
	ds_read_b128 v[88:91], v84 offset:2048
	v_add_u32_e32 v124, s70, v135
	s_waitcnt lgkmcnt(1)
	v_mfma_f32_16x16x32_bf16 v[92:95], v[92:95], v[164:167], v[76:79]
	s_addk_i32 s18, 0x18f
	s_bfe_u32 s18, s18, 0x30009
	s_mul_i32 s18, s18, 9
	ds_read_b128 v[76:79], v84
	s_waitcnt lgkmcnt(0)
	v_mfma_f32_16x16x32_bf16 v[76:79], v[76:79], v[80:83], 0
	ds_read_b128 v[84:87], v124
	ds_read_b128 v[206:209], v124 offset:2048
	s_sub_i32 s18, s69, s18
	s_add_i32 s18, s18, 7
	s_waitcnt lgkmcnt(1)
	v_mfma_f32_16x16x32_bf16 v[84:87], v[84:87], v[164:167], v[76:79]
	s_and_b32 s18, s18, 0xff
	s_lshl_b32 s18, s18, 13
	s_add_i32 s70, s18, 0x100
	v_mfma_f32_16x16x32_bf16 v[76:79], v[88:91], v[80:83], 0
	v_add_u32_e32 v124, s70, v134
	ds_read_b128 v[210:213], v124
	v_add_u32_e32 v127, s70, v135
	s_waitcnt lgkmcnt(1)
	v_mfma_f32_16x16x32_bf16 v[88:91], v[206:209], v[164:167], v[76:79]
	ds_read_b128 v[206:209], v124 offset:2048
	ds_read_b128 v[214:217], v127 offset:2048
	s_sub_i32 s69, s69, s26
	ds_read_b128 v[76:79], v127
	s_waitcnt lgkmcnt(3)
	v_mfma_f32_16x16x32_bf16 v[210:213], v[210:213], v[80:83], 0
	s_mulk_i32 s69, 0x7c
	v_add_u32_e32 v127, s69, v148
	ds_read2_b32 v[184:185], v127 offset0:232 offset1:233
	s_waitcnt lgkmcnt(3)
	v_mfma_f32_16x16x32_bf16 v[80:83], v[206:209], v[80:83], 0
	v_and_b32_e32 v124, 64, v159
	v_add_u32_e32 v163, 64, v124
	v_cmp_lt_i32_e32 vcc, v129, v163
	s_waitcnt lgkmcnt(1)
	v_mfma_f32_16x16x32_bf16 v[76:79], v[76:79], v[164:167], v[210:213]
	s_add_i32 s27, s53, s27
	v_cndmask_b32_e32 v124, v159, v129, vcc
	s_waitcnt lgkmcnt(0)
	v_add_f32_e32 v129, v168, v184
	v_mfma_f32_16x16x32_bf16 v[80:83], v[214:217], v[164:167], v[80:83]
	ds_read2_b32 v[164:165], v127 offset0:234 offset1:235
	ds_read2_b32 v[166:167], v127 offset0:248 offset1:249
	ds_read2_b32 v[206:207], v127 offset0:250 offset1:251
	v_add_f32_e32 v168, v169, v185
	v_add_f32_e32 v129, v140, v129
	s_waitcnt lgkmcnt(2)
	v_add_f32_e32 v164, v170, v164
	v_add_f32_e32 v185, v142, v164
	v_add_f32_e32 v164, v171, v165
	s_waitcnt lgkmcnt(1)
	v_add_f32_e32 v165, v172, v166
	v_add_f32_e32 v184, v141, v168
	v_add_f32_e32 v172, v144, v165
	v_add_f32_e32 v165, v173, v167
	v_max3_f32 v168, v129, s59, v184
	v_add_f32_e32 v197, v143, v164
	v_add_f32_e32 v173, v145, v165
	s_waitcnt lgkmcnt(0)
	v_add_f32_e32 v165, v174, v206
	v_max3_f32 v164, v168, v185, v197
	v_add_f32_e32 v174, v146, v165
	v_add_f32_e32 v165, v175, v207
	v_max3_f32 v164, v164, v172, v173
	v_add_f32_e32 v175, v147, v165
	v_max3_f32 v206, v164, v174, v175
	v_add_u32_e32 v164, 0x41c, v127
	ds_read2_b32 v[164:165], v164 offset1:1
	v_add_u32_e32 v166, 0x424, v127
	v_add_u32_e32 v168, 0x45c, v127
	v_add_u32_e32 v170, 0x464, v127
	ds_read2_b32 v[166:167], v166 offset1:1
	ds_read2_b32 v[168:169], v168 offset1:1
	ds_read2_b32 v[170:171], v170 offset1:1
	s_waitcnt lgkmcnt(3)
	v_add_f32_e32 v164, v176, v164
	v_add_f32_e32 v176, v140, v164
	v_add_f32_e32 v164, v177, v165
	s_waitcnt lgkmcnt(2)
	v_add_f32_e32 v165, v178, v166
	v_add_f32_e32 v178, v142, v165
	v_add_f32_e32 v165, v179, v167
	v_add_f32_e32 v179, v143, v165
	s_waitcnt lgkmcnt(1)
	v_add_f32_e32 v165, v180, v168
	v_add_f32_e32 v177, v141, v164
	v_add_f32_e32 v180, v144, v165
	v_add_f32_e32 v165, v181, v169
	v_max3_f32 v164, v206, v176, v177
	v_add_f32_e32 v181, v145, v165
	s_waitcnt lgkmcnt(0)
	v_add_f32_e32 v165, v182, v170
	v_max3_f32 v164, v164, v178, v179
	v_add_f32_e32 v182, v146, v165
	v_add_f32_e32 v165, v183, v171
	v_max3_f32 v164, v164, v180, v181
	v_add_f32_e32 v183, v147, v165
	v_max3_f32 v206, v164, v182, v183
	v_add_u32_e32 v164, 0x498, v127
	ds_read2_b32 v[164:165], v164 offset1:1
	v_add_u32_e32 v166, 0x4a0, v127
	v_add_u32_e32 v168, 0x4d8, v127
	v_add_u32_e32 v170, 0x4e0, v127
	ds_read2_b32 v[166:167], v166 offset1:1
	ds_read2_b32 v[168:169], v168 offset1:1
	ds_read2_b32 v[170:171], v170 offset1:1
	s_waitcnt lgkmcnt(3)
	v_add_f32_e32 v164, v198, v164
	v_add_f32_e32 v198, v140, v164
	v_add_f32_e32 v164, v199, v165
	s_waitcnt lgkmcnt(2)
	v_add_f32_e32 v165, v200, v166
	v_add_f32_e32 v200, v142, v165
	v_add_f32_e32 v165, v201, v167
	v_add_f32_e32 v201, v143, v165
	s_waitcnt lgkmcnt(1)
	v_add_f32_e32 v165, v202, v168
	v_add_f32_e32 v199, v141, v164
	v_add_f32_e32 v202, v144, v165
	v_add_f32_e32 v165, v203, v169
	v_max3_f32 v164, v206, v198, v199
	v_add_f32_e32 v203, v145, v165
	s_waitcnt lgkmcnt(0)
	v_add_f32_e32 v165, v204, v170
	v_max3_f32 v164, v164, v200, v201
	v_add_f32_e32 v204, v146, v165
	v_add_f32_e32 v165, v205, v171
	v_max3_f32 v164, v164, v202, v203
	v_add_f32_e32 v205, v147, v165
	v_max3_f32 v206, v164, v204, v205
	v_add_u32_e32 v164, 0x514, v127
	ds_read2_b32 v[164:165], v164 offset1:1
	v_add_u32_e32 v166, 0x51c, v127
	v_add_u32_e32 v168, 0x554, v127
	v_add_u32_e32 v170, 0x55c, v127
	ds_read2_b32 v[166:167], v166 offset1:1
	ds_read2_b32 v[168:169], v168 offset1:1
	ds_read2_b32 v[170:171], v170 offset1:1
	s_waitcnt lgkmcnt(3)
	v_add_f32_e32 v112, v112, v164
	v_add_f32_e32 v164, v140, v112
	v_add_f32_e32 v112, v113, v165
	s_waitcnt lgkmcnt(2)
	v_add_f32_e32 v113, v114, v166
	v_add_f32_e32 v165, v141, v112
	v_add_f32_e32 v166, v142, v113
	v_add_f32_e32 v113, v115, v167
	s_waitcnt lgkmcnt(1)
	v_add_f32_e32 v108, v108, v168
	v_max3_f32 v112, v206, v164, v165
	v_add_f32_e32 v167, v143, v113
	v_add_f32_e32 v168, v144, v108
	v_add_f32_e32 v108, v109, v169
	s_waitcnt lgkmcnt(0)
	v_add_f32_e32 v109, v110, v170
	v_max3_f32 v112, v112, v166, v167
	v_add_f32_e32 v169, v145, v108
	v_add_f32_e32 v170, v146, v109
	v_add_f32_e32 v109, v111, v171
	v_max3_f32 v108, v112, v168, v169
	v_add_f32_e32 v171, v147, v109
	v_max3_f32 v206, v108, v170, v171
	v_add_u32_e32 v108, 0x590, v127
	ds_read2_b32 v[108:109], v108 offset1:1
	v_add_u32_e32 v110, 0x598, v127
	v_add_u32_e32 v112, 0x5d0, v127
	v_add_u32_e32 v114, 0x5d8, v127
	ds_read2_b32 v[110:111], v110 offset1:1
	ds_read2_b32 v[112:113], v112 offset1:1
	ds_read2_b32 v[114:115], v114 offset1:1
	s_waitcnt lgkmcnt(3)
	v_add_f32_e32 v104, v104, v108
	v_add_f32_e32 v108, v140, v104
	v_add_f32_e32 v104, v105, v109
	s_waitcnt lgkmcnt(2)
	v_add_f32_e32 v105, v106, v110
	v_add_f32_e32 v109, v141, v104
	v_add_f32_e32 v110, v142, v105
	v_add_f32_e32 v105, v107, v111
	s_waitcnt lgkmcnt(1)
	v_add_f32_e32 v100, v100, v112
	v_max3_f32 v104, v206, v108, v109
	v_add_f32_e32 v111, v143, v105
	v_add_f32_e32 v112, v144, v100
	v_add_f32_e32 v100, v101, v113
	s_waitcnt lgkmcnt(0)
	v_add_f32_e32 v101, v102, v114
	v_max3_f32 v104, v104, v110, v111
	v_add_f32_e32 v113, v145, v100
	v_add_f32_e32 v114, v146, v101
	v_add_f32_e32 v101, v103, v115
	v_max3_f32 v100, v104, v112, v113
	v_add_f32_e32 v115, v147, v101
	v_max3_f32 v206, v100, v114, v115
	v_add_u32_e32 v100, 0x60c, v127
	ds_read2_b32 v[100:101], v100 offset1:1
	v_add_u32_e32 v102, 0x614, v127
	v_add_u32_e32 v104, 0x64c, v127
	v_add_u32_e32 v106, 0x654, v127
	ds_read2_b32 v[102:103], v102 offset1:1
	ds_read2_b32 v[104:105], v104 offset1:1
	ds_read2_b32 v[106:107], v106 offset1:1
	s_waitcnt lgkmcnt(3)
	v_add_f32_e32 v96, v96, v100
	v_add_f32_e32 v100, v140, v96
	v_add_f32_e32 v96, v97, v101
	s_waitcnt lgkmcnt(2)
	v_add_f32_e32 v97, v98, v102
	v_add_f32_e32 v101, v141, v96
	v_add_f32_e32 v102, v142, v97
	v_add_f32_e32 v97, v99, v103
	s_waitcnt lgkmcnt(1)
	v_add_f32_e32 v92, v92, v104
	v_max3_f32 v96, v206, v100, v101
	v_add_f32_e32 v103, v143, v97
	v_add_f32_e32 v104, v144, v92
	v_add_f32_e32 v92, v93, v105
	s_waitcnt lgkmcnt(0)
	v_add_f32_e32 v93, v94, v106
	v_max3_f32 v96, v96, v102, v103
	v_add_f32_e32 v105, v145, v92
	v_add_f32_e32 v106, v146, v93
	v_add_f32_e32 v93, v95, v107
	v_max3_f32 v92, v96, v104, v105
	v_add_f32_e32 v107, v147, v93
	v_max3_f32 v206, v92, v106, v107
	v_add_u32_e32 v92, 0x688, v127
	ds_read2_b32 v[92:93], v92 offset1:1
	v_add_u32_e32 v94, 0x690, v127
	v_add_u32_e32 v96, 0x6c8, v127
	v_add_u32_e32 v98, 0x6d0, v127
	ds_read2_b32 v[94:95], v94 offset1:1
	ds_read2_b32 v[96:97], v96 offset1:1
	ds_read2_b32 v[98:99], v98 offset1:1
	s_waitcnt lgkmcnt(3)
	v_add_f32_e32 v84, v84, v92
	v_add_f32_e32 v92, v140, v84
	v_add_f32_e32 v84, v85, v93
	v_add_f32_e32 v93, v141, v84
	s_waitcnt lgkmcnt(2)
	v_add_f32_e32 v85, v86, v94
	v_max3_f32 v84, v206, v92, v93
	v_add_f32_e32 v206, v142, v85
	v_add_f32_e32 v85, v87, v95
	v_add_f32_e32 v95, v143, v85
	s_waitcnt lgkmcnt(1)
	v_add_f32_e32 v85, v88, v96
	v_add_f32_e32 v96, v144, v85
	v_add_f32_e32 v85, v89, v97
	v_add_f32_e32 v97, v145, v85
	s_waitcnt lgkmcnt(0)
	v_add_f32_e32 v85, v90, v98
	v_max3_f32 v84, v84, v206, v95
	v_add_f32_e32 v98, v146, v85
	v_add_f32_e32 v85, v91, v99
	v_max3_f32 v84, v84, v96, v97
	v_add_f32_e32 v207, v147, v85
	v_max3_f32 v94, v84, v98, v207
	v_add_u32_e32 v84, 0x704, v127
	ds_read2_b32 v[84:85], v84 offset1:1
	v_add_u32_e32 v86, 0x70c, v127
	v_add_u32_e32 v88, 0x744, v127
	v_add_u32_e32 v90, 0x74c, v127
	ds_read2_b32 v[86:87], v86 offset1:1
	ds_read2_b32 v[88:89], v88 offset1:1
	ds_read2_b32 v[90:91], v90 offset1:1
	s_waitcnt lgkmcnt(3)
	v_add_f32_e32 v76, v76, v84
	v_add_f32_e32 v127, v140, v76
	v_add_f32_e32 v76, v77, v85
	s_waitcnt lgkmcnt(2)
	v_add_f32_e32 v77, v78, v86
	v_add_f32_e32 v209, v142, v77
	v_add_f32_e32 v77, v79, v87
	v_add_f32_e32 v208, v141, v76
	v_add_f32_e32 v210, v143, v77
	s_waitcnt lgkmcnt(1)
	v_add_f32_e32 v77, v80, v88
	v_max3_f32 v76, v94, v127, v208
	v_add_f32_e32 v211, v144, v77
	v_add_f32_e32 v77, v81, v89
	v_max3_f32 v76, v76, v209, v210
	v_add_f32_e32 v79, v145, v77
	v_max3_f32 v77, v76, v211, v79
	s_waitcnt lgkmcnt(0)
	v_add_f32_e32 v76, v82, v90
	v_add_f32_e32 v78, v146, v76
	v_add_f32_e32 v76, v83, v91
	v_add_f32_e32 v76, v147, v76
	v_lshlrev_b32_e32 v124, 2, v124
	v_max3_f32 v77, v77, v78, v76
	v_mov_b32_e32 v80, v77
	s_nop 1
	v_permlane16_swap_b32 v77, v80
	v_xor_b32_e32 v81, 32, v159
	v_cmp_lt_i32_e32 vcc, v81, v163
	v_add_u32_e32 v82, s68, v136
	s_add_i32 s18, s53, s18
	v_cndmask_b32_e32 v81, v159, v81, vcc
	s_waitcnt lgkmcnt(0)
	v_max_f32_e32 v80, v80, v80
	v_lshlrev_b32_e32 v94, 2, v81
	v_max_f32_e32 v77, v77, v80
	v_mov_b32_e32 v80, v77
	s_nop 1
	v_permlane32_swap_b32 v77, v80
	s_waitcnt lgkmcnt(0)
	v_max_f32_e32 v80, v80, v80
	v_max_f32_e32 v77, v77, v80
	v_pk_mul_f32 v[76:77], v[76:77], s[20:21] op_sel_hi:[1,0]
	s_nop 0
	v_fma_f32 v80, v129, s20, -v77
	v_exp_f32_e32 v84, v80
	v_fma_f32 v80, v184, s20, -v77
	v_exp_f32_e32 v85, v80
	v_fma_f32 v81, v185, s20, -v77
	v_exp_f32_e32 v86, v81
	v_fma_f32 v81, v197, s20, -v77
	v_exp_f32_e32 v87, v81
	v_fma_f32 v81, v172, s20, -v77
	v_add_f32_e32 v80, 0, v84
	v_exp_f32_e32 v99, v81
	v_fma_f32 v81, v173, s20, -v77
	v_add_f32_e32 v80, v85, v80
	v_exp_f32_e32 v129, v81
	v_fma_f32 v81, v174, s20, -v77
	v_add_f32_e32 v80, v86, v80
	v_exp_f32_e32 v163, v81
	v_fma_f32 v81, v175, s20, -v77
	v_add_f32_e32 v80, v87, v80
	v_exp_f32_e32 v172, v81
	v_fma_f32 v81, v176, s20, -v77
	v_add_f32_e32 v80, v99, v80
	v_exp_f32_e32 v173, v81
	v_fma_f32 v81, v177, s20, -v77
	v_add_f32_e32 v80, v129, v80
	v_exp_f32_e32 v174, v81
	v_fma_f32 v81, v178, s20, -v77
	v_add_f32_e32 v80, v163, v80
	v_exp_f32_e32 v175, v81
	v_fma_f32 v81, v179, s20, -v77
	v_add_f32_e32 v80, v172, v80
	v_exp_f32_e32 v176, v81
	v_fma_f32 v81, v180, s20, -v77
	v_add_f32_e32 v80, v173, v80
	v_exp_f32_e32 v177, v81
	v_fma_f32 v81, v181, s20, -v77
	v_add_f32_e32 v80, v174, v80
	v_exp_f32_e32 v178, v81
	v_fma_f32 v81, v182, s20, -v77
	v_add_f32_e32 v80, v175, v80
	v_exp_f32_e32 v179, v81
	v_fma_f32 v81, v183, s20, -v77
	v_add_f32_e32 v80, v176, v80
	v_exp_f32_e32 v180, v81
	v_fma_f32 v81, v198, s20, -v77
	v_add_f32_e32 v80, v177, v80
	v_exp_f32_e32 v181, v81
	v_fma_f32 v81, v199, s20, -v77
	v_add_f32_e32 v80, v178, v80
	v_exp_f32_e32 v182, v81
	v_fma_f32 v81, v200, s20, -v77
	v_add_f32_e32 v80, v179, v80
	v_exp_f32_e32 v183, v81
	v_fma_f32 v81, v201, s20, -v77
	v_add_f32_e32 v80, v180, v80
	v_exp_f32_e32 v184, v81
	v_fma_f32 v81, v202, s20, -v77
	v_add_f32_e32 v80, v181, v80
	v_exp_f32_e32 v185, v81
	v_fma_f32 v81, v203, s20, -v77
	v_add_f32_e32 v80, v182, v80
	v_exp_f32_e32 v197, v81
	v_fma_f32 v81, v204, s20, -v77
	v_add_f32_e32 v80, v183, v80
	v_exp_f32_e32 v198, v81
	v_fma_f32 v81, v205, s20, -v77
	v_add_f32_e32 v80, v184, v80
	v_exp_f32_e32 v199, v81
	v_fma_f32 v81, v164, s20, -v77
	v_add_f32_e32 v80, v185, v80
	v_exp_f32_e32 v164, v81
	v_fma_f32 v81, v165, s20, -v77
	v_add_f32_e32 v80, v197, v80
	v_exp_f32_e32 v165, v81
	v_fma_f32 v81, v166, s20, -v77
	v_add_f32_e32 v80, v198, v80
	v_exp_f32_e32 v166, v81
	v_fma_f32 v81, v167, s20, -v77
	v_add_f32_e32 v80, v199, v80
	v_exp_f32_e32 v167, v81
	v_fma_f32 v81, v168, s20, -v77
	v_add_f32_e32 v80, v164, v80
	v_exp_f32_e32 v168, v81
	v_fma_f32 v81, v169, s20, -v77
	v_add_f32_e32 v80, v165, v80
	v_exp_f32_e32 v169, v81
	v_fma_f32 v81, v170, s20, -v77
	v_add_f32_e32 v80, v166, v80
	v_exp_f32_e32 v170, v81
	v_fma_f32 v81, v171, s20, -v77
	v_add_f32_e32 v80, v167, v80
	v_exp_f32_e32 v171, v81
	v_fma_f32 v81, v108, s20, -v77
	v_add_f32_e32 v80, v168, v80
	v_exp_f32_e32 v200, v81
	v_fma_f32 v81, v109, s20, -v77
	v_add_f32_e32 v80, v169, v80
	v_exp_f32_e32 v201, v81
	v_fma_f32 v81, v110, s20, -v77
	v_add_f32_e32 v80, v170, v80
	v_exp_f32_e32 v202, v81
	v_fma_f32 v81, v111, s20, -v77
	v_add_f32_e32 v80, v171, v80
	v_exp_f32_e32 v203, v81
	v_fma_f32 v81, v112, s20, -v77
	v_add_f32_e32 v80, v200, v80
	v_exp_f32_e32 v112, v81
	v_fma_f32 v81, v113, s20, -v77
	v_add_f32_e32 v80, v201, v80
	v_exp_f32_e32 v113, v81
	v_fma_f32 v81, v114, s20, -v77
	v_add_f32_e32 v80, v202, v80
	v_exp_f32_e32 v114, v81
	v_fma_f32 v81, v115, s20, -v77
	v_add_f32_e32 v80, v203, v80
	v_exp_f32_e32 v115, v81
	v_fma_f32 v81, v100, s20, -v77
	v_add_f32_e32 v80, v112, v80
	v_exp_f32_e32 v204, v81
	v_fma_f32 v81, v101, s20, -v77
	v_add_f32_e32 v80, v113, v80
	v_exp_f32_e32 v205, v81
	v_fma_f32 v81, v102, s20, -v77
	v_add_f32_e32 v80, v114, v80
	v_exp_f32_e32 v212, v81
	v_fma_f32 v81, v103, s20, -v77
	v_add_f32_e32 v80, v115, v80
	v_exp_f32_e32 v213, v81
	v_fma_f32 v81, v104, s20, -v77
	v_add_f32_e32 v80, v204, v80
	v_exp_f32_e32 v214, v81
	v_fma_f32 v81, v105, s20, -v77
	v_add_f32_e32 v80, v205, v80
	v_exp_f32_e32 v215, v81
	v_fma_f32 v81, v106, s20, -v77
	v_add_f32_e32 v80, v212, v80
	v_exp_f32_e32 v216, v81
	v_fma_f32 v81, v107, s20, -v77
	v_add_f32_e32 v80, v213, v80
	v_exp_f32_e32 v217, v81
	v_fma_f32 v81, v92, s20, -v77
	v_add_f32_e32 v80, v214, v80
	v_exp_f32_e32 v92, v81
	v_fma_f32 v81, v93, s20, -v77
	v_add_f32_e32 v80, v215, v80
	v_exp_f32_e32 v93, v81
	v_fma_f32 v81, v206, s20, -v77
	v_add_f32_e32 v80, v216, v80
	v_exp_f32_e32 v206, v81
	v_fma_f32 v81, v95, s20, -v77
	v_add_f32_e32 v80, v217, v80
	v_exp_f32_e32 v95, v81
	v_fma_f32 v81, v96, s20, -v77
	v_add_f32_e32 v80, v92, v80
	v_exp_f32_e32 v218, v81
	v_fma_f32 v81, v97, s20, -v77
	v_add_f32_e32 v80, v93, v80
	v_exp_f32_e32 v219, v81
	v_add_f32_e32 v80, v206, v80
	v_fma_f32 v88, v98, s20, -v77
	v_add_f32_e32 v80, v95, v80
	v_exp_f32_e32 v220, v88
	v_add_f32_e32 v80, v218, v80
	v_add_f32_e32 v100, v219, v80
	ds_read_b64_tr_b16 v[80:81], v82
	ds_read_b64_tr_b16 v[82:83], v82 offset:2048
	v_cvt_pk_bf16_f32 v84, v84, v85
	v_add_u32_e32 v85, s68, v137
	v_add_u32_e32 v98, s68, v138
	v_add_u32_e32 v102, s68, v139
	ds_read_b64_tr_b16 v[88:89], v85
	ds_read_b64_tr_b16 v[90:91], v85 offset:2048
	v_cvt_pk_bf16_f32 v85, v86, v87
	v_cvt_pk_bf16_f32 v86, v99, v129
	ds_read_b64_tr_b16 v[96:97], v98
	ds_read_b64_tr_b16 v[98:99], v98 offset:2048
	v_add_f32_e32 v129, v220, v100
	ds_read_b64_tr_b16 v[100:101], v102
	ds_read_b64_tr_b16 v[102:103], v102 offset:2048
	v_fma_f32 v104, v207, s20, -v77
	v_add_u32_e32 v106, s67, v136
	v_cvt_pk_bf16_f32 v87, v163, v172
	v_exp_f32_e32 v163, v104
	ds_read_b64_tr_b16 v[104:105], v106
	ds_read_b64_tr_b16 v[106:107], v106 offset:2048
	s_waitcnt lgkmcnt(8)
	v_mfma_f32_16x16x32_bf16 v[80:83], v[80:83], v[84:87], 0
	v_fma_f32 v127, v127, s20, -v77
	v_exp_f32_e32 v127, v127
	v_fma_f32 v172, v208, s20, -v77
	s_waitcnt lgkmcnt(6)
	v_mfma_f32_16x16x32_bf16 v[88:91], v[88:91], v[84:87], 0
	v_exp_f32_e32 v172, v172
	v_add_f32_e32 v129, v163, v129
	v_add_f32_e32 v129, v127, v129
	s_waitcnt lgkmcnt(4)
	v_mfma_f32_16x16x32_bf16 v[96:99], v[96:99], v[84:87], 0
	v_fma_f32 v79, v79, s20, -v77
	v_add_f32_e32 v129, v172, v129
	v_fma_f32 v78, v78, s20, -v77
	s_waitcnt lgkmcnt(2)
	v_mfma_f32_16x16x32_bf16 v[84:87], v[100:103], v[84:87], 0
	v_add_u32_e32 v101, s67, v137
	v_cvt_pk_bf16_f32 v100, v173, v174
	ds_read_b64_tr_b16 v[108:109], v101
	ds_read_b64_tr_b16 v[110:111], v101 offset:2048
	v_cvt_pk_bf16_f32 v101, v175, v176
	v_cvt_pk_bf16_f32 v102, v177, v178
	v_cvt_pk_bf16_f32 v103, v179, v180
	v_fma_f32 v173, v209, s20, -v77
	v_exp_f32_e32 v173, v173
	s_waitcnt lgkmcnt(2)
	v_mfma_f32_16x16x32_bf16 v[80:83], v[104:107], v[100:103], v[80:83]
	v_add_u32_e32 v106, s67, v138
	ds_read_b64_tr_b16 v[104:105], v106
	ds_read_b64_tr_b16 v[106:107], v106 offset:2048
	v_add_f32_e32 v129, v173, v129
	s_waitcnt lgkmcnt(2)
	v_mfma_f32_16x16x32_bf16 v[88:91], v[108:111], v[100:103], v[88:91]
	v_add_u32_e32 v110, s67, v139
	ds_read_b64_tr_b16 v[108:109], v110
	ds_read_b64_tr_b16 v[110:111], v110 offset:2048
	s_waitcnt lgkmcnt(2)
	v_mfma_f32_16x16x32_bf16 v[96:99], v[104:107], v[100:103], v[96:99]
	v_add_u32_e32 v106, s66, v136
	ds_read_b64_tr_b16 v[104:105], v106
	ds_read_b64_tr_b16 v[106:107], v106 offset:2048
	s_waitcnt lgkmcnt(2)
	v_mfma_f32_16x16x32_bf16 v[84:87], v[108:111], v[100:103], v[84:87]
	v_add_u32_e32 v101, s66, v137
	v_cvt_pk_bf16_f32 v100, v181, v182
	ds_read_b64_tr_b16 v[108:109], v101
	ds_read_b64_tr_b16 v[110:111], v101 offset:2048
	v_cvt_pk_bf16_f32 v101, v183, v184
	v_cvt_pk_bf16_f32 v102, v185, v197
	v_cvt_pk_bf16_f32 v103, v198, v199
	s_waitcnt lgkmcnt(2)
	s_nop 0
	v_mfma_f32_16x16x32_bf16 v[80:83], v[104:107], v[100:103], v[80:83]
	v_add_u32_e32 v106, s66, v138
	ds_read_b64_tr_b16 v[104:105], v106
	ds_read_b64_tr_b16 v[106:107], v106 offset:2048
	s_waitcnt lgkmcnt(2)
	v_mfma_f32_16x16x32_bf16 v[88:91], v[108:111], v[100:103], v[88:91]
	v_add_u32_e32 v110, s66, v139
	ds_read_b64_tr_b16 v[108:109], v110
	ds_read_b64_tr_b16 v[110:111], v110 offset:2048
	s_waitcnt lgkmcnt(2)
	v_mfma_f32_16x16x32_bf16 v[96:99], v[104:107], v[100:103], v[96:99]
	v_add_u32_e32 v106, s65, v136
	ds_read_b64_tr_b16 v[104:105], v106
	ds_read_b64_tr_b16 v[106:107], v106 offset:2048
	s_waitcnt lgkmcnt(2)
	v_mfma_f32_16x16x32_bf16 v[84:87], v[108:111], v[100:103], v[84:87]
	v_add_u32_e32 v101, s65, v137
	v_cvt_pk_bf16_f32 v100, v164, v165
	ds_read_b64_tr_b16 v[108:109], v101
	ds_read_b64_tr_b16 v[110:111], v101 offset:2048
	v_cvt_pk_bf16_f32 v101, v166, v167
	v_cvt_pk_bf16_f32 v102, v168, v169
	v_cvt_pk_bf16_f32 v103, v170, v171
	v_fma_f32 v164, v210, s20, -v77
	v_exp_f32_e32 v164, v164
	s_waitcnt lgkmcnt(2)
	v_mfma_f32_16x16x32_bf16 v[80:83], v[104:107], v[100:103], v[80:83]
	v_add_u32_e32 v106, s65, v138
	ds_read_b64_tr_b16 v[104:105], v106
	ds_read_b64_tr_b16 v[106:107], v106 offset:2048
	v_fma_f32 v165, v211, s20, -v77
	s_waitcnt lgkmcnt(2)
	v_mfma_f32_16x16x32_bf16 v[88:91], v[108:111], v[100:103], v[88:91]
	v_add_u32_e32 v110, s65, v139
	ds_read_b64_tr_b16 v[108:109], v110
	ds_read_b64_tr_b16 v[110:111], v110 offset:2048
	s_waitcnt lgkmcnt(2)
	v_mfma_f32_16x16x32_bf16 v[96:99], v[104:107], v[100:103], v[96:99]
	v_add_u32_e32 v106, s39, v136
	ds_read_b64_tr_b16 v[104:105], v106
	ds_read_b64_tr_b16 v[106:107], v106 offset:2048
	s_waitcnt lgkmcnt(2)
	v_mfma_f32_16x16x32_bf16 v[84:87], v[108:111], v[100:103], v[84:87]
	v_add_u32_e32 v101, s39, v137
	v_cvt_pk_bf16_f32 v100, v200, v201
	ds_read_b64_tr_b16 v[108:109], v101
	ds_read_b64_tr_b16 v[110:111], v101 offset:2048
	v_cvt_pk_bf16_f32 v101, v202, v203
	v_cvt_pk_bf16_f32 v102, v112, v113
	v_cvt_pk_bf16_f32 v103, v114, v115
	v_exp_f32_e32 v114, v79
	v_add_u32_e32 v79, s38, v139
	s_waitcnt lgkmcnt(2)
	v_mfma_f32_16x16x32_bf16 v[80:83], v[104:107], v[100:103], v[80:83]
	v_add_u32_e32 v106, s39, v138
	ds_read_b64_tr_b16 v[104:105], v106
	ds_read_b64_tr_b16 v[106:107], v106 offset:2048
	v_add_f32_e32 v113, v164, v129
	s_waitcnt lgkmcnt(2)
	v_mfma_f32_16x16x32_bf16 v[88:91], v[108:111], v[100:103], v[88:91]
	v_add_u32_e32 v110, s39, v139
	ds_read_b64_tr_b16 v[108:109], v110
	ds_read_b64_tr_b16 v[110:111], v110 offset:2048
	v_exp_f32_e32 v115, v78
	s_waitcnt lgkmcnt(2)
	v_mfma_f32_16x16x32_bf16 v[96:99], v[104:107], v[100:103], v[96:99]
	v_add_u32_e32 v106, s38, v136
	ds_read_b64_tr_b16 v[104:105], v106
	ds_read_b64_tr_b16 v[106:107], v106 offset:2048
	v_sub_f32_e32 v129, v76, v77
	s_waitcnt lgkmcnt(2)
	v_mfma_f32_16x16x32_bf16 v[84:87], v[108:111], v[100:103], v[84:87]
	v_add_u32_e32 v101, s38, v137
	v_cvt_pk_bf16_f32 v100, v204, v205
	ds_read_b64_tr_b16 v[108:109], v101
	ds_read_b64_tr_b16 v[110:111], v101 offset:2048
	v_cvt_pk_bf16_f32 v101, v212, v213
	v_cvt_pk_bf16_f32 v102, v214, v215
	v_cvt_pk_bf16_f32 v103, v216, v217
	v_exp_f32_e32 v112, v165
	s_waitcnt lgkmcnt(2)
	v_mfma_f32_16x16x32_bf16 v[80:83], v[104:107], v[100:103], v[80:83]
	v_add_u32_e32 v106, s38, v138
	ds_read_b64_tr_b16 v[104:105], v106
	ds_read_b64_tr_b16 v[106:107], v106 offset:2048
	v_add_f32_e32 v113, v112, v113
	s_waitcnt lgkmcnt(2)
	v_mfma_f32_16x16x32_bf16 v[88:91], v[108:111], v[100:103], v[88:91]
	ds_read_b64_tr_b16 v[108:109], v79
	ds_read_b64_tr_b16 v[110:111], v79 offset:2048
	s_waitcnt lgkmcnt(2)
	v_mfma_f32_16x16x32_bf16 v[76:79], v[104:107], v[100:103], v[96:99]
	s_nop 2
	v_add_u32_e32 v98, s27, v136
	ds_read_b64_tr_b16 v[96:97], v98
	ds_read_b64_tr_b16 v[98:99], v98 offset:2048
	s_waitcnt lgkmcnt(2)
	v_mfma_f32_16x16x32_bf16 v[84:87], v[108:111], v[100:103], v[84:87]
	v_cvt_pk_bf16_f32 v100, v92, v93
	v_add_u32_e32 v92, s27, v137
	ds_read_b64_tr_b16 v[104:105], v92
	ds_read_b64_tr_b16 v[106:107], v92 offset:2048
	v_cvt_pk_bf16_f32 v101, v206, v95
	v_cvt_pk_bf16_f32 v102, v218, v219
	v_cvt_pk_bf16_f32 v103, v220, v163
	v_add_u32_e32 v92, s27, v138
	v_add_u32_e32 v93, s27, v139
	s_waitcnt lgkmcnt(2)
	v_mfma_f32_16x16x32_bf16 v[80:83], v[96:99], v[100:103], v[80:83]
	ds_read_b64_tr_b16 v[96:97], v92
	ds_read_b64_tr_b16 v[98:99], v92 offset:2048
	v_add_u32_e32 v95, s18, v136
	v_exp_f32_e32 v92, v129
	s_waitcnt lgkmcnt(2)
	v_mfma_f32_16x16x32_bf16 v[88:91], v[104:107], v[100:103], v[88:91]
	ds_read_b64_tr_b16 v[104:105], v93
	ds_read_b64_tr_b16 v[106:107], v93 offset:2048
	v_add_f32_e32 v93, v114, v113
	v_add_f32_e32 v93, v115, v93
	s_waitcnt lgkmcnt(2)
	v_mfma_f32_16x16x32_bf16 v[76:79], v[96:99], v[100:103], v[76:79]
	ds_read_b64_tr_b16 v[96:97], v95
	ds_read_b64_tr_b16 v[98:99], v95 offset:2048
	v_add_f32_e32 v93, v92, v93
	v_add_u32_e32 v95, s18, v137
	s_waitcnt lgkmcnt(2)
	v_mfma_f32_16x16x32_bf16 v[84:87], v[104:107], v[100:103], v[84:87]
	v_cvt_pk_bf16_f32 v100, v127, v172
	v_cvt_pk_bf16_f32 v101, v173, v164
	v_cvt_pk_bf16_f32 v102, v112, v114
	v_cvt_pk_bf16_f32 v103, v115, v92
	v_add_u32_e32 v92, s18, v138
	ds_read_b64_tr_b16 v[104:105], v95
	ds_read_b64_tr_b16 v[106:107], v95 offset:2048
	s_waitcnt lgkmcnt(2)
	v_mfma_f32_16x16x32_bf16 v[80:83], v[96:99], v[100:103], v[80:83]
	ds_read_b64_tr_b16 v[96:97], v92
	ds_read_b64_tr_b16 v[98:99], v92 offset:2048
	v_mov_b32_e32 v92, v93
	s_nop 1
	v_permlane16_swap_b32 v93, v92
	v_add_u32_e32 v95, s18, v139
	s_waitcnt lgkmcnt(3)
	v_mfma_f32_16x16x32_bf16 v[88:91], v[104:107], v[100:103], v[88:91]
	ds_read_b64_tr_b16 v[104:105], v95
	ds_read_b64_tr_b16 v[106:107], v95 offset:2048
	v_mov_b32_e32 v129, v125
	s_waitcnt lgkmcnt(2)
	v_add_f32_e32 v95, v93, v92
	v_mfma_f32_16x16x32_bf16 v[76:79], v[96:99], v[100:103], v[76:79]
	v_mov_b32_e32 v96, v95
	s_nop 1
	v_permlane32_swap_b32 v95, v96
	v_lshl_add_u64 v[92:93], s[28:29], 0, v[128:129]
	s_waitcnt vmcnt(16)
	s_waitcnt lgkmcnt(1)
	v_mfma_f32_16x16x32_bf16 v[84:87], v[104:107], v[100:103], v[84:87]
	s_waitcnt vmcnt(14)
	s_waitcnt lgkmcnt(0)
	v_add_f32_e32 v95, v95, v96
	v_div_scale_f32 v96, s[28:29], v95, v95, 1.0
	v_rcp_f32_e32 v97, v96
	s_waitcnt vmcnt(12)
	s_waitcnt vmcnt(10)
	s_waitcnt vmcnt(8)
	s_waitcnt vmcnt(6)
	s_waitcnt vmcnt(4)
	v_fma_f32 v98, -v96, v97, 1.0
	v_fmac_f32_e32 v97, v98, v97
	v_div_scale_f32 v98, vcc, 1.0, v95, 1.0
	v_mul_f32_e32 v99, v98, v97
	v_fma_f32 v100, -v96, v99, v98
	v_fmac_f32_e32 v99, v100, v97
	v_fma_f32 v96, -v96, v99, v98
	v_div_fmas_f32 v96, v96, v97, v99
	v_div_fixup_f32 v96, v96, v95, 1.0
	v_mad_u64_u32 v[98:99], s[28:29], v132, s55, v[92:93]
	v_pk_mul_f32 v[80:81], v[96:97], v[80:81] op_sel_hi:[0,1]
	v_pk_mul_f32 v[82:83], v[96:97], v[82:83] op_sel_hi:[0,1]
	v_pk_mul_f32 v[76:77], v[96:97], v[76:77] op_sel_hi:[0,1]
	v_pk_mul_f32 v[78:79], v[96:97], v[78:79] op_sel_hi:[0,1]
	v_mad_i32_i24 v99, v133, s55, v99
	v_cvt_pk_bf16_f32 v80, v80, v81
	v_cvt_pk_bf16_f32 v81, v82, v83
	v_cvt_pk_bf16_f32 v76, v76, v77
	v_cvt_pk_bf16_f32 v77, v78, v79
	s_waitcnt vmcnt(2)
	s_waitcnt vmcnt(0)
	global_store_dwordx2 v[98:99], v[80:81], off
	v_pk_mul_f32 v[80:81], v[96:97], v[88:89] op_sel_hi:[0,1]
	v_pk_mul_f32 v[82:83], v[96:97], v[90:91] op_sel_hi:[0,1]
	global_store_dwordx2 v[98:99], v[76:77], off offset:64
	v_pk_mul_f32 v[76:77], v[96:97], v[84:85] op_sel_hi:[0,1]
	v_pk_mul_f32 v[78:79], v[96:97], v[86:87] op_sel_hi:[0,1]
	v_cvt_pk_bf16_f32 v80, v80, v81
	v_cvt_pk_bf16_f32 v81, v82, v83
	v_cvt_pk_bf16_f32 v76, v76, v77
	v_cvt_pk_bf16_f32 v77, v78, v79
	global_store_dwordx2 v[98:99], v[80:81], off offset:32
	global_store_dwordx2 v[98:99], v[76:77], off offset:96
	s_waitcnt lgkmcnt(0)
	s_barrier
	s_and_b64 vcc, exec, s[24:25]
	s_cbranch_vccz .LBB0_586
	s_mul_i32 s18, s35, 57
	s_lshr_b32 s18, s18, 9
	s_mul_i32 s18, s18, 9
	s_sub_i32 s18, s35, s18
	s_and_b32 s18, s18, 0xff
	s_lshl_b32 s18, s18, 13
	v_add_u32_e32 v76, s18, v1
	ds_write_b128 v76, v[72:75]
	v_add_u32_e32 v72, s18, v123
	ds_write_b128 v72, v[68:71]

.LBB0_588:
	s_add_i32 s18, s26, 2
	s_max_i32 s24, s18, 4
	s_add_i32 s24, s24, -4
	s_min_u32 s39, s24, 24
	s_mul_i32 s24, s39, 29
	s_lshr_b32 s24, s24, 8
	s_mul_i32 s24, s24, 9
	s_sub_i32 s24, s39, s24
	s_and_b32 s24, s24, 0xff
	s_lshl_b32 s38, s24, 13
	s_add_i32 s24, s38, 0x100
	s_waitcnt lgkmcnt(0)
	s_barrier
	v_add_u32_e32 v64, s24, v134
	v_add_u32_e32 v72, s24, v135
	ds_read_b128 v[60:63], v64
	ds_read_b128 v[64:67], v64 offset:2048
	ds_read_b128 v[68:71], v72
	ds_read_b128 v[72:75], v72 offset:2048
	s_mul_i32 s24, s39, 57
	s_add_i32 s25, s24, 57
	s_bfe_u32 s25, s25, 0x30009
	s_mul_i32 s25, s25, 9
	s_sub_i32 s25, s39, s25
	s_waitcnt lgkmcnt(2)
	v_mfma_f32_16x16x32_bf16 v[64:67], v[64:67], v[56:59], 0
	s_add_i32 s25, s25, 1
	s_and_b32 s25, s25, 0xff
	s_lshl_b32 s35, s25, 13
	v_mfma_f32_16x16x32_bf16 v[60:63], v[60:63], v[56:59], 0
	s_add_i32 s25, s35, 0x100
	s_add_i32 s38, s53, s38
	s_add_i32 s35, s53, s35
	s_waitcnt lgkmcnt(0)
	v_mfma_f32_16x16x32_bf16 v[100:103], v[72:75], v[52:55], v[64:67]
	v_add_u32_e32 v72, s25, v135
	s_nop 1
	v_add_u32_e32 v64, s25, v134
	v_mfma_f32_16x16x32_bf16 v[96:99], v[68:71], v[52:55], v[60:63]
	s_add_i32 s25, s24, 0x72
	s_bfe_u32 s25, s25, 0x30009
	s_mul_i32 s25, s25, 9
	ds_read_b128 v[60:63], v64
	ds_read_b128 v[64:67], v64 offset:2048
	s_waitcnt lgkmcnt(1)
	v_mfma_f32_16x16x32_bf16 v[60:63], v[60:63], v[56:59], 0
	ds_read_b128 v[68:71], v72
	ds_read_b128 v[72:75], v72 offset:2048
	s_sub_i32 s25, s39, s25
	s_add_i32 s25, s25, 2
	s_waitcnt lgkmcnt(1)
	v_mfma_f32_16x16x32_bf16 v[104:107], v[68:71], v[52:55], v[60:63]
	s_and_b32 s25, s25, 0xff
	s_lshl_b32 s34, s25, 13
	s_add_i32 s25, s34, 0x100
	v_mfma_f32_16x16x32_bf16 v[60:63], v[64:67], v[56:59], 0
	v_add_u32_e32 v64, s25, v134
	s_add_i32 s34, s53, s34
	s_waitcnt lgkmcnt(0)
	v_mfma_f32_16x16x32_bf16 v[108:111], v[72:75], v[52:55], v[60:63]
	v_add_u32_e32 v72, s25, v135
	s_add_i32 s25, s24, 0xab
	s_bfe_u32 s25, s25, 0x30009
	s_nop 0
	ds_read_b128 v[60:63], v64
	ds_read_b128 v[64:67], v64 offset:2048
	s_waitcnt lgkmcnt(1)
	v_mfma_f32_16x16x32_bf16 v[60:63], v[60:63], v[56:59], 0
	ds_read_b128 v[68:71], v72
	ds_read_b128 v[72:75], v72 offset:2048
	s_mul_i32 s25, s25, 9
	s_sub_i32 s25, s39, s25
	s_add_i32 s25, s25, 3
	s_waitcnt lgkmcnt(1)
	v_mfma_f32_16x16x32_bf16 v[112:115], v[68:71], v[52:55], v[60:63]
	s_and_b32 s25, s25, 0xff
	s_lshl_b32 s29, s25, 13
	s_add_i32 s25, s29, 0x100
	v_mfma_f32_16x16x32_bf16 v[60:63], v[64:67], v[56:59], 0
	v_add_u32_e32 v64, s25, v134
	s_add_i32 s29, s53, s29
	s_waitcnt lgkmcnt(0)
	v_mfma_f32_16x16x32_bf16 v[162:165], v[72:75], v[52:55], v[60:63]
	v_add_u32_e32 v72, s25, v135
	s_add_i32 s25, s24, 0xe4
	s_bfe_u32 s25, s25, 0x30009
	s_nop 0
	ds_read_b128 v[60:63], v64
	ds_read_b128 v[64:67], v64 offset:2048
	s_waitcnt lgkmcnt(1)
	v_mfma_f32_16x16x32_bf16 v[60:63], v[60:63], v[56:59], 0
	ds_read_b128 v[68:71], v72
	ds_read_b128 v[72:75], v72 offset:2048
	s_mul_i32 s25, s25, 9
	s_sub_i32 s25, s39, s25
	s_add_i32 s25, s25, 4
	s_waitcnt lgkmcnt(1)
	v_mfma_f32_16x16x32_bf16 v[166:169], v[68:71], v[52:55], v[60:63]
	s_and_b32 s25, s25, 0xff
	s_lshl_b32 s28, s25, 13
	s_add_i32 s25, s28, 0x100
	v_mfma_f32_16x16x32_bf16 v[60:63], v[64:67], v[56:59], 0
	v_add_u32_e32 v64, s25, v134
	s_add_i32 s28, s53, s28
	s_waitcnt lgkmcnt(0)
	v_mfma_f32_16x16x32_bf16 v[88:91], v[72:75], v[52:55], v[60:63]
	v_add_u32_e32 v72, s25, v135
	s_add_i32 s25, s24, 0x11d
	s_bfe_u32 s25, s25, 0x30009
	s_nop 0
	ds_read_b128 v[60:63], v64
	ds_read_b128 v[64:67], v64 offset:2048
	s_waitcnt lgkmcnt(1)
	v_mfma_f32_16x16x32_bf16 v[60:63], v[60:63], v[56:59], 0
	ds_read_b128 v[68:71], v72
	ds_read_b128 v[72:75], v72 offset:2048
	s_mul_i32 s25, s25, 9
	s_sub_i32 s25, s39, s25
	s_add_i32 s25, s25, 5
	s_waitcnt lgkmcnt(1)
	v_mfma_f32_16x16x32_bf16 v[84:87], v[68:71], v[52:55], v[60:63]
	s_and_b32 s25, s25, 0xff
	s_lshl_b32 s27, s25, 13
	s_add_i32 s25, s27, 0x100
	v_mfma_f32_16x16x32_bf16 v[60:63], v[64:67], v[56:59], 0
	v_add_u32_e32 v64, s25, v134
	s_add_i32 s27, s53, s27
	s_waitcnt lgkmcnt(0)
	v_mfma_f32_16x16x32_bf16 v[80:83], v[72:75], v[52:55], v[60:63]
	v_add_u32_e32 v72, s25, v135
	s_add_i32 s25, s24, 0x156
	s_bfe_u32 s25, s25, 0x30009
	s_nop 0
	ds_read_b128 v[60:63], v64
	ds_read_b128 v[64:67], v64 offset:2048
	s_waitcnt lgkmcnt(1)
	v_mfma_f32_16x16x32_bf16 v[60:63], v[60:63], v[56:59], 0
	ds_read_b128 v[68:71], v72
	ds_read_b128 v[72:75], v72 offset:2048
	s_mul_i32 s25, s25, 9
	s_sub_i32 s25, s39, s25
	s_add_i32 s25, s25, 6
	s_waitcnt lgkmcnt(1)
	v_mfma_f32_16x16x32_bf16 v[76:79], v[68:71], v[52:55], v[60:63]
	s_and_b32 s25, s25, 0xff
	s_lshl_b32 s25, s25, 13
	s_add_i32 s65, s25, 0x100
	v_mfma_f32_16x16x32_bf16 v[60:63], v[64:67], v[56:59], 0
	v_add_u32_e32 v64, s65, v134
	v_add_u32_e32 v95, s65, v135
	s_addk_i32 s24, 0x18f
	s_waitcnt lgkmcnt(0)
	v_mfma_f32_16x16x32_bf16 v[72:75], v[72:75], v[52:55], v[60:63]
	s_bfe_u32 s24, s24, 0x30009
	s_mul_i32 s24, s24, 9
	s_sub_i32 s24, s39, s24
	ds_read_b128 v[60:63], v64
	ds_read_b128 v[64:67], v64 offset:2048
	s_waitcnt lgkmcnt(1)
	v_mfma_f32_16x16x32_bf16 v[60:63], v[60:63], v[56:59], 0
	ds_read_b128 v[68:71], v95
	ds_read_b128 v[170:173], v95 offset:2048
	s_add_i32 s24, s24, 7
	s_and_b32 s24, s24, 0xff
	s_waitcnt lgkmcnt(1)
	v_mfma_f32_16x16x32_bf16 v[68:71], v[68:71], v[52:55], v[60:63]
	s_lshl_b32 s24, s24, 13
	s_add_i32 s65, s24, 0x100
	v_add_u32_e32 v95, s65, v134
	v_mfma_f32_16x16x32_bf16 v[60:63], v[64:67], v[56:59], 0
	v_add_u32_e32 v127, s65, v135
	s_sub_i32 s39, s39, s18
	s_mulk_i32 s39, 0x7c
	s_waitcnt lgkmcnt(0)
	v_mfma_f32_16x16x32_bf16 v[64:67], v[170:173], v[52:55], v[60:63]
	ds_read_b128 v[170:173], v95 offset:2048
	s_add_i32 s25, s53, s25
	s_add_i32 s24, s53, s24
	ds_read_b128 v[60:63], v95
	ds_read_b128 v[174:177], v127
	ds_read_b128 v[178:181], v127 offset:2048
	s_waitcnt lgkmcnt(2)
	v_mfma_f32_16x16x32_bf16 v[60:63], v[60:63], v[56:59], 0
	v_add_u32_e32 v95, s39, v148
	ds_read2_b32 v[132:133], v95 offset0:232 offset1:233
	s_lshl_b32 s18, s18, 6
	v_mfma_f32_16x16x32_bf16 v[56:59], v[170:173], v[56:59], 0
	s_waitcnt lgkmcnt(0)
	v_add_f32_e32 v96, v96, v132
	v_mfma_f32_16x16x32_bf16 v[60:63], v[174:177], v[52:55], v[60:63]
	v_add_f32_e32 v127, v140, v96
	v_add_f32_e32 v96, v97, v133
	v_add_f32_e32 v129, v141, v96
	v_mfma_f32_16x16x32_bf16 v[52:55], v[178:181], v[52:55], v[56:59]
	s_nop 2
	ds_read2_b32 v[56:57], v95 offset0:234 offset1:235
	ds_read2_b32 v[58:59], v95 offset0:248 offset1:249
	ds_read2_b32 v[170:171], v95 offset0:250 offset1:251
	v_max3_f32 v96, v127, s59, v129
	s_waitcnt lgkmcnt(2)
	v_add_f32_e32 v56, v98, v56
	v_add_f32_e32 v132, v142, v56
	v_add_f32_e32 v56, v99, v57
	s_waitcnt lgkmcnt(1)
	v_add_f32_e32 v57, v100, v58
	v_add_f32_e32 v100, v144, v57
	v_add_f32_e32 v57, v101, v59
	v_add_f32_e32 v133, v143, v56
	v_add_f32_e32 v101, v145, v57
	s_waitcnt lgkmcnt(0)
	v_add_f32_e32 v57, v102, v170
	v_max3_f32 v56, v96, v132, v133
	v_add_f32_e32 v102, v146, v57
	v_add_f32_e32 v57, v103, v171
	v_max3_f32 v56, v56, v100, v101
	v_add_f32_e32 v103, v147, v57
	v_max3_f32 v170, v56, v102, v103
	v_add_u32_e32 v56, 0x41c, v95
	ds_read2_b32 v[56:57], v56 offset1:1
	v_add_u32_e32 v58, 0x424, v95
	v_add_u32_e32 v96, 0x45c, v95
	v_add_u32_e32 v98, 0x464, v95
	ds_read2_b32 v[58:59], v58 offset1:1
	ds_read2_b32 v[96:97], v96 offset1:1
	ds_read2_b32 v[98:99], v98 offset1:1
	s_waitcnt lgkmcnt(3)
	v_add_f32_e32 v56, v104, v56
	v_add_f32_e32 v104, v140, v56
	v_add_f32_e32 v56, v105, v57
	s_waitcnt lgkmcnt(2)
	v_add_f32_e32 v57, v106, v58
	v_add_f32_e32 v106, v142, v57
	v_add_f32_e32 v57, v107, v59
	v_add_f32_e32 v107, v143, v57
	s_waitcnt lgkmcnt(1)
	v_add_f32_e32 v57, v108, v96
	v_add_f32_e32 v105, v141, v56
	v_add_f32_e32 v108, v144, v57
	v_add_f32_e32 v57, v109, v97
	v_max3_f32 v56, v170, v104, v105
	v_add_f32_e32 v109, v145, v57
	s_waitcnt lgkmcnt(0)
	v_add_f32_e32 v57, v110, v98
	v_max3_f32 v56, v56, v106, v107
	v_add_f32_e32 v110, v146, v57
	v_add_f32_e32 v57, v111, v99
	v_max3_f32 v56, v56, v108, v109
	v_add_f32_e32 v111, v147, v57
	v_max3_f32 v170, v56, v110, v111
	v_add_u32_e32 v56, 0x498, v95
	ds_read2_b32 v[56:57], v56 offset1:1
	v_add_u32_e32 v58, 0x4a0, v95
	v_add_u32_e32 v96, 0x4d8, v95
	v_add_u32_e32 v98, 0x4e0, v95
	ds_read2_b32 v[58:59], v58 offset1:1
	ds_read2_b32 v[96:97], v96 offset1:1
	ds_read2_b32 v[98:99], v98 offset1:1
	s_waitcnt lgkmcnt(3)
	v_add_f32_e32 v56, v112, v56
	v_add_f32_e32 v112, v140, v56
	v_add_f32_e32 v56, v113, v57
	s_waitcnt lgkmcnt(2)
	v_add_f32_e32 v57, v114, v58
	v_add_f32_e32 v114, v142, v57
	v_add_f32_e32 v57, v115, v59
	v_add_f32_e32 v115, v143, v57
	s_waitcnt lgkmcnt(1)
	v_add_f32_e32 v57, v162, v96
	v_add_f32_e32 v113, v141, v56
	v_add_f32_e32 v162, v144, v57
	v_add_f32_e32 v57, v163, v97
	v_max3_f32 v56, v170, v112, v113
	v_add_f32_e32 v163, v145, v57
	s_waitcnt lgkmcnt(0)
	v_add_f32_e32 v57, v164, v98
	v_max3_f32 v56, v56, v114, v115
	v_add_f32_e32 v164, v146, v57
	v_add_f32_e32 v57, v165, v99
	v_max3_f32 v56, v56, v162, v163
	v_add_f32_e32 v165, v147, v57
	v_max3_f32 v170, v56, v164, v165
	v_add_u32_e32 v56, 0x514, v95
	ds_read2_b32 v[56:57], v56 offset1:1
	v_add_u32_e32 v58, 0x51c, v95
	v_add_u32_e32 v96, 0x554, v95
	v_add_u32_e32 v98, 0x55c, v95
	ds_read2_b32 v[58:59], v58 offset1:1
	ds_read2_b32 v[96:97], v96 offset1:1
	ds_read2_b32 v[98:99], v98 offset1:1
	s_waitcnt lgkmcnt(3)
	v_add_f32_e32 v56, v166, v56
	v_add_f32_e32 v166, v140, v56
	v_add_f32_e32 v56, v167, v57
	s_waitcnt lgkmcnt(2)
	v_add_f32_e32 v57, v168, v58
	v_add_f32_e32 v168, v142, v57
	v_add_f32_e32 v57, v169, v59
	v_add_f32_e32 v169, v143, v57
	s_waitcnt lgkmcnt(1)
	v_add_f32_e32 v57, v88, v96
	v_add_f32_e32 v167, v141, v56
	v_add_f32_e32 v96, v144, v57
	v_add_f32_e32 v57, v89, v97
	v_max3_f32 v56, v170, v166, v167
	v_add_f32_e32 v97, v145, v57
	s_waitcnt lgkmcnt(0)
	v_add_f32_e32 v57, v90, v98
	v_max3_f32 v56, v56, v168, v169
	v_add_f32_e32 v98, v146, v57
	v_add_f32_e32 v57, v91, v99
	v_max3_f32 v56, v56, v96, v97
	v_add_f32_e32 v99, v147, v57
	v_max3_f32 v170, v56, v98, v99
	v_add_u32_e32 v56, 0x590, v95
	ds_read2_b32 v[56:57], v56 offset1:1
	v_add_u32_e32 v58, 0x598, v95
	v_add_u32_e32 v88, 0x5d0, v95
	v_add_u32_e32 v90, 0x5d8, v95
	ds_read2_b32 v[58:59], v58 offset1:1
	ds_read2_b32 v[88:89], v88 offset1:1
	ds_read2_b32 v[90:91], v90 offset1:1
	s_waitcnt lgkmcnt(3)
	v_add_f32_e32 v56, v84, v56
	v_add_f32_e32 v84, v140, v56
	v_add_f32_e32 v56, v85, v57
	s_waitcnt lgkmcnt(2)
	v_add_f32_e32 v57, v86, v58
	v_add_f32_e32 v86, v142, v57
	v_add_f32_e32 v57, v87, v59
	v_add_f32_e32 v87, v143, v57
	s_waitcnt lgkmcnt(1)
	v_add_f32_e32 v57, v80, v88
	v_add_f32_e32 v85, v141, v56
	v_add_f32_e32 v88, v144, v57
	v_add_f32_e32 v57, v81, v89
	v_max3_f32 v56, v170, v84, v85
	v_add_f32_e32 v89, v145, v57
	s_waitcnt lgkmcnt(0)
	v_add_f32_e32 v57, v82, v90
	v_max3_f32 v56, v56, v86, v87
	v_add_f32_e32 v90, v146, v57
	v_add_f32_e32 v57, v83, v91
	v_max3_f32 v56, v56, v88, v89
	v_add_f32_e32 v91, v147, v57
	v_max3_f32 v170, v56, v90, v91
	v_add_u32_e32 v56, 0x60c, v95
	ds_read2_b32 v[56:57], v56 offset1:1
	v_add_u32_e32 v58, 0x614, v95
	v_add_u32_e32 v80, 0x64c, v95
	v_add_u32_e32 v82, 0x654, v95
	ds_read2_b32 v[58:59], v58 offset1:1
	ds_read2_b32 v[80:81], v80 offset1:1
	ds_read2_b32 v[82:83], v82 offset1:1
	s_waitcnt lgkmcnt(3)
	v_add_f32_e32 v56, v76, v56
	v_add_f32_e32 v76, v140, v56
	v_add_f32_e32 v56, v77, v57
	s_waitcnt lgkmcnt(2)
	v_add_f32_e32 v57, v78, v58
	v_add_f32_e32 v78, v142, v57
	v_add_f32_e32 v57, v79, v59
	v_add_f32_e32 v79, v143, v57
	s_waitcnt lgkmcnt(1)
	v_add_f32_e32 v57, v72, v80
	v_add_f32_e32 v77, v141, v56
	v_add_f32_e32 v80, v144, v57
	v_add_f32_e32 v57, v73, v81
	v_max3_f32 v56, v170, v76, v77
	v_add_f32_e32 v81, v145, v57
	s_waitcnt lgkmcnt(0)
	v_add_f32_e32 v57, v74, v82
	v_max3_f32 v56, v56, v78, v79
	v_add_f32_e32 v82, v146, v57
	v_add_f32_e32 v57, v75, v83
	v_max3_f32 v56, v56, v80, v81
	v_add_f32_e32 v83, v147, v57
	v_max3_f32 v170, v56, v82, v83
	v_add_u32_e32 v56, 0x688, v95
	ds_read2_b32 v[56:57], v56 offset1:1
	v_add_u32_e32 v58, 0x690, v95
	v_add_u32_e32 v72, 0x6c8, v95
	v_add_u32_e32 v74, 0x6d0, v95
	ds_read2_b32 v[58:59], v58 offset1:1
	ds_read2_b32 v[72:73], v72 offset1:1
	ds_read2_b32 v[74:75], v74 offset1:1
	s_waitcnt lgkmcnt(3)
	v_add_f32_e32 v56, v68, v56
	v_add_f32_e32 v68, v140, v56
	v_add_f32_e32 v56, v69, v57
	s_waitcnt lgkmcnt(2)
	v_add_f32_e32 v57, v70, v58
	v_add_f32_e32 v70, v142, v57
	v_add_f32_e32 v57, v71, v59
	v_add_f32_e32 v71, v143, v57
	s_waitcnt lgkmcnt(1)
	v_add_f32_e32 v57, v64, v72
	v_add_f32_e32 v69, v141, v56
	v_add_f32_e32 v72, v144, v57
	v_add_f32_e32 v57, v65, v73
	v_max3_f32 v56, v170, v68, v69
	v_add_f32_e32 v73, v145, v57
	s_waitcnt lgkmcnt(0)
	v_add_f32_e32 v57, v66, v74
	v_max3_f32 v56, v56, v70, v71
	v_add_f32_e32 v74, v146, v57
	v_add_f32_e32 v57, v67, v75
	v_max3_f32 v56, v56, v72, v73
	v_add_f32_e32 v75, v147, v57
	v_max3_f32 v170, v56, v74, v75
	v_add_u32_e32 v56, 0x704, v95
	ds_read2_b32 v[56:57], v56 offset1:1
	v_add_u32_e32 v58, 0x70c, v95
	v_add_u32_e32 v64, 0x744, v95
	v_add_u32_e32 v66, 0x74c, v95
	ds_read2_b32 v[58:59], v58 offset1:1
	ds_read2_b32 v[64:65], v64 offset1:1
	ds_read2_b32 v[66:67], v66 offset1:1
	s_waitcnt lgkmcnt(3)
	v_add_f32_e32 v56, v60, v56
	v_add_f32_e32 v95, v140, v56
	v_add_f32_e32 v56, v61, v57
	v_add_f32_e32 v171, v141, v56
	s_waitcnt lgkmcnt(2)
	v_add_f32_e32 v57, v62, v58
	s_waitcnt lgkmcnt(1)
	v_add_f32_e32 v52, v52, v64
	v_max3_f32 v56, v170, v95, v171
	v_add_f32_e32 v170, v142, v57
	v_add_f32_e32 v57, v63, v59
	v_add_f32_e32 v173, v144, v52
	v_add_f32_e32 v52, v53, v65
	v_add_f32_e32 v172, v143, v57
	v_add_f32_e32 v174, v145, v52
	s_waitcnt lgkmcnt(0)
	v_add_f32_e32 v52, v54, v66
	v_max3_f32 v56, v56, v170, v172
	v_add_f32_e32 v54, v146, v52
	v_add_f32_e32 v52, v55, v67
	v_max3_f32 v53, v56, v173, v174
	v_add_f32_e32 v52, v147, v52
	v_max3_f32 v53, v53, v54, v52
	v_mov_b32_e32 v55, v53
	s_nop 1
	v_permlane16_swap_b32 v53, v55
	v_add_u32_e32 v58, s38, v136
	s_waitcnt lgkmcnt(0)
	v_max_f32_e32 v55, v55, v55
	v_max_f32_e32 v53, v53, v55
	v_mov_b32_e32 v55, v53
	s_nop 1
	v_permlane32_swap_b32 v53, v55
	s_waitcnt lgkmcnt(0)
	v_max_f32_e32 v55, v55, v55
	v_max_f32_e32 v53, v53, v55
	v_pk_mul_f32 v[52:53], v[52:53], s[20:21] op_sel_hi:[1,0]
	s_nop 0
	v_fma_f32 v55, v127, s20, -v53
	v_exp_f32_e32 v55, v55
	v_fma_f32 v56, v129, s20, -v53
	v_exp_f32_e32 v60, v56
	v_fma_f32 v57, v132, s20, -v53
	v_exp_f32_e32 v61, v57
	v_fma_f32 v57, v133, s20, -v53
	v_exp_f32_e32 v62, v57
	v_fma_f32 v57, v100, s20, -v53
	v_add_f32_e32 v56, 0, v55
	v_exp_f32_e32 v63, v57
	v_fma_f32 v57, v101, s20, -v53
	v_add_f32_e32 v56, v60, v56
	v_exp_f32_e32 v100, v57
	v_fma_f32 v57, v102, s20, -v53
	v_add_f32_e32 v56, v61, v56
	v_exp_f32_e32 v101, v57
	v_fma_f32 v57, v103, s20, -v53
	v_add_f32_e32 v56, v62, v56
	v_exp_f32_e32 v102, v57
	v_fma_f32 v57, v104, s20, -v53
	v_add_f32_e32 v56, v63, v56
	v_exp_f32_e32 v103, v57
	v_fma_f32 v57, v105, s20, -v53
	v_add_f32_e32 v56, v100, v56
	v_exp_f32_e32 v104, v57
	v_fma_f32 v57, v106, s20, -v53
	v_add_f32_e32 v56, v101, v56
	v_exp_f32_e32 v105, v57
	v_fma_f32 v57, v107, s20, -v53
	v_add_f32_e32 v56, v102, v56
	v_exp_f32_e32 v106, v57
	v_fma_f32 v57, v108, s20, -v53
	v_add_f32_e32 v56, v103, v56
	v_exp_f32_e32 v107, v57
	v_fma_f32 v57, v109, s20, -v53
	v_add_f32_e32 v56, v104, v56
	v_exp_f32_e32 v108, v57
	v_fma_f32 v57, v110, s20, -v53
	v_add_f32_e32 v56, v105, v56
	v_exp_f32_e32 v109, v57
	v_fma_f32 v57, v111, s20, -v53
	v_add_f32_e32 v56, v106, v56
	v_exp_f32_e32 v110, v57
	v_fma_f32 v57, v112, s20, -v53
	v_add_f32_e32 v56, v107, v56
	v_exp_f32_e32 v111, v57
	v_fma_f32 v57, v113, s20, -v53
	v_add_f32_e32 v56, v108, v56
	v_exp_f32_e32 v112, v57
	v_fma_f32 v57, v114, s20, -v53
	v_add_f32_e32 v56, v109, v56
	v_exp_f32_e32 v113, v57
	v_fma_f32 v57, v115, s20, -v53
	v_add_f32_e32 v56, v110, v56
	v_exp_f32_e32 v114, v57
	v_fma_f32 v57, v162, s20, -v53
	v_add_f32_e32 v56, v111, v56
	v_exp_f32_e32 v115, v57
	v_fma_f32 v57, v163, s20, -v53
	v_add_f32_e32 v56, v112, v56
	v_exp_f32_e32 v127, v57
	v_fma_f32 v57, v164, s20, -v53
	v_add_f32_e32 v56, v113, v56
	v_exp_f32_e32 v129, v57
	v_fma_f32 v57, v165, s20, -v53
	v_add_f32_e32 v56, v114, v56
	v_exp_f32_e32 v132, v57
	v_fma_f32 v57, v166, s20, -v53
	v_add_f32_e32 v56, v115, v56
	v_exp_f32_e32 v133, v57
	v_fma_f32 v57, v167, s20, -v53
	v_add_f32_e32 v56, v127, v56
	v_exp_f32_e32 v162, v57
	v_fma_f32 v57, v168, s20, -v53
	v_add_f32_e32 v56, v129, v56
	v_exp_f32_e32 v163, v57
	v_fma_f32 v57, v169, s20, -v53
	v_add_f32_e32 v56, v132, v56
	v_exp_f32_e32 v164, v57
	v_fma_f32 v57, v96, s20, -v53
	v_add_f32_e32 v56, v133, v56
	v_exp_f32_e32 v96, v57
	v_fma_f32 v57, v97, s20, -v53
	v_add_f32_e32 v56, v162, v56
	v_exp_f32_e32 v97, v57
	v_fma_f32 v57, v98, s20, -v53
	v_add_f32_e32 v56, v163, v56
	v_exp_f32_e32 v98, v57
	v_fma_f32 v57, v99, s20, -v53
	v_add_f32_e32 v56, v164, v56
	v_exp_f32_e32 v99, v57
	v_fma_f32 v57, v84, s20, -v53
	v_add_f32_e32 v56, v96, v56
	v_exp_f32_e32 v84, v57
	v_fma_f32 v57, v85, s20, -v53
	v_add_f32_e32 v56, v97, v56
	v_exp_f32_e32 v85, v57
	v_fma_f32 v57, v86, s20, -v53
	v_add_f32_e32 v56, v98, v56
	v_exp_f32_e32 v86, v57
	v_fma_f32 v57, v87, s20, -v53
	v_add_f32_e32 v56, v99, v56
	v_exp_f32_e32 v87, v57
	v_fma_f32 v57, v88, s20, -v53
	v_add_f32_e32 v56, v84, v56
	v_exp_f32_e32 v88, v57
	v_fma_f32 v57, v89, s20, -v53
	v_add_f32_e32 v56, v85, v56
	v_exp_f32_e32 v89, v57
	v_fma_f32 v57, v90, s20, -v53
	v_add_f32_e32 v56, v86, v56
	v_exp_f32_e32 v90, v57
	v_fma_f32 v57, v91, s20, -v53
	v_add_f32_e32 v56, v87, v56
	v_exp_f32_e32 v91, v57
	v_fma_f32 v57, v76, s20, -v53
	v_add_f32_e32 v56, v88, v56
	v_exp_f32_e32 v165, v57
	v_fma_f32 v57, v77, s20, -v53
	v_add_f32_e32 v56, v89, v56
	v_exp_f32_e32 v166, v57
	v_fma_f32 v57, v78, s20, -v53
	v_add_f32_e32 v56, v90, v56
	v_exp_f32_e32 v167, v57
	v_fma_f32 v57, v79, s20, -v53
	v_add_f32_e32 v56, v91, v56
	v_exp_f32_e32 v168, v57
	v_fma_f32 v57, v80, s20, -v53
	v_add_f32_e32 v56, v165, v56
	v_exp_f32_e32 v169, v57
	v_fma_f32 v57, v81, s20, -v53
	v_add_f32_e32 v56, v166, v56
	v_exp_f32_e32 v175, v57
	v_fma_f32 v57, v82, s20, -v53
	v_add_f32_e32 v56, v167, v56
	v_exp_f32_e32 v176, v57
	v_fma_f32 v57, v83, s20, -v53
	v_add_f32_e32 v56, v168, v56
	v_exp_f32_e32 v177, v57
	v_fma_f32 v57, v68, s20, -v53
	v_add_f32_e32 v56, v169, v56
	v_exp_f32_e32 v178, v57
	v_fma_f32 v57, v69, s20, -v53
	v_add_f32_e32 v56, v175, v56
	v_exp_f32_e32 v179, v57
	v_fma_f32 v57, v70, s20, -v53
	v_add_f32_e32 v56, v176, v56
	v_exp_f32_e32 v180, v57
	v_fma_f32 v57, v71, s20, -v53
	v_add_f32_e32 v56, v177, v56
	v_exp_f32_e32 v181, v57
	v_fma_f32 v57, v72, s20, -v53
	v_add_f32_e32 v56, v178, v56
	v_exp_f32_e32 v182, v57
	v_fma_f32 v57, v73, s20, -v53
	v_add_f32_e32 v56, v179, v56
	v_exp_f32_e32 v183, v57
	v_add_f32_e32 v56, v180, v56
	v_add_f32_e32 v56, v181, v56
	v_add_f32_e32 v56, v182, v56
	v_add_f32_e32 v76, v183, v56
	v_fma_f32 v56, v74, s20, -v53
	v_cvt_pk_bf16_f32 v60, v55, v60
	v_add_u32_e32 v55, s38, v137
	v_exp_f32_e32 v184, v56
	ds_read_b64_tr_b16 v[56:57], v58
	ds_read_b64_tr_b16 v[58:59], v58 offset:2048
	ds_read_b64_tr_b16 v[64:65], v55
	ds_read_b64_tr_b16 v[66:67], v55 offset:2048
	v_add_u32_e32 v55, s38, v138
	v_fma_f32 v72, v75, s20, -v53
	ds_read_b64_tr_b16 v[68:69], v55
	ds_read_b64_tr_b16 v[70:71], v55 offset:2048
	v_add_u32_e32 v55, s38, v139
	v_cvt_pk_bf16_f32 v61, v61, v62
	v_cvt_pk_bf16_f32 v62, v63, v100
	v_exp_f32_e32 v100, v72
	ds_read_b64_tr_b16 v[72:73], v55
	ds_read_b64_tr_b16 v[74:75], v55 offset:2048
	v_add_u32_e32 v78, s35, v136
	v_cvt_pk_bf16_f32 v63, v101, v102
	v_add_f32_e32 v55, v184, v76
	ds_read_b64_tr_b16 v[76:77], v78
	ds_read_b64_tr_b16 v[78:79], v78 offset:2048
	s_waitcnt lgkmcnt(8)
	v_mfma_f32_16x16x32_bf16 v[56:59], v[56:59], v[60:63], 0
	v_fma_f32 v95, v95, s20, -v53
	v_exp_f32_e32 v95, v95
	v_fma_f32 v101, v171, s20, -v53
	s_waitcnt lgkmcnt(6)
	v_mfma_f32_16x16x32_bf16 v[64:67], v[64:67], v[60:63], 0
	v_exp_f32_e32 v101, v101
	v_fma_f32 v102, v170, s20, -v53
	v_exp_f32_e32 v102, v102
	s_waitcnt lgkmcnt(4)
	v_mfma_f32_16x16x32_bf16 v[68:71], v[68:71], v[60:63], 0
	v_add_f32_e32 v55, v100, v55
	v_add_f32_e32 v55, v95, v55
	v_add_f32_e32 v55, v101, v55
	s_waitcnt lgkmcnt(2)
	v_mfma_f32_16x16x32_bf16 v[60:63], v[72:75], v[60:63], 0
	v_add_u32_e32 v73, s35, v137
	v_cvt_pk_bf16_f32 v72, v103, v104
	ds_read_b64_tr_b16 v[80:81], v73
	ds_read_b64_tr_b16 v[82:83], v73 offset:2048
	v_cvt_pk_bf16_f32 v73, v105, v106
	v_cvt_pk_bf16_f32 v74, v107, v108
	v_cvt_pk_bf16_f32 v75, v109, v110
	v_fma_f32 v103, v172, s20, -v53
	v_add_f32_e32 v55, v102, v55
	s_waitcnt lgkmcnt(2)
	v_mfma_f32_16x16x32_bf16 v[56:59], v[76:79], v[72:75], v[56:59]
	v_add_u32_e32 v78, s35, v138
	ds_read_b64_tr_b16 v[76:77], v78
	ds_read_b64_tr_b16 v[78:79], v78 offset:2048
	v_fma_f32 v54, v54, s20, -v53
	s_waitcnt lgkmcnt(2)
	v_mfma_f32_16x16x32_bf16 v[64:67], v[80:83], v[72:75], v[64:67]
	v_add_u32_e32 v82, s35, v139
	ds_read_b64_tr_b16 v[80:81], v82
	ds_read_b64_tr_b16 v[82:83], v82 offset:2048
	s_waitcnt lgkmcnt(2)
	v_mfma_f32_16x16x32_bf16 v[68:71], v[76:79], v[72:75], v[68:71]
	v_add_u32_e32 v78, s34, v136
	ds_read_b64_tr_b16 v[76:77], v78
	ds_read_b64_tr_b16 v[78:79], v78 offset:2048
	s_waitcnt lgkmcnt(2)
	v_mfma_f32_16x16x32_bf16 v[60:63], v[80:83], v[72:75], v[60:63]
	v_add_u32_e32 v73, s34, v137
	v_cvt_pk_bf16_f32 v72, v111, v112
	ds_read_b64_tr_b16 v[80:81], v73
	ds_read_b64_tr_b16 v[82:83], v73 offset:2048
	v_cvt_pk_bf16_f32 v73, v113, v114
	v_cvt_pk_bf16_f32 v74, v115, v127
	v_cvt_pk_bf16_f32 v75, v129, v132
	s_waitcnt lgkmcnt(2)
	s_nop 0
	v_mfma_f32_16x16x32_bf16 v[56:59], v[76:79], v[72:75], v[56:59]
	v_add_u32_e32 v78, s34, v138
	ds_read_b64_tr_b16 v[76:77], v78
	ds_read_b64_tr_b16 v[78:79], v78 offset:2048
	s_waitcnt lgkmcnt(2)
	v_mfma_f32_16x16x32_bf16 v[64:67], v[80:83], v[72:75], v[64:67]
	v_add_u32_e32 v82, s34, v139
	ds_read_b64_tr_b16 v[80:81], v82
	ds_read_b64_tr_b16 v[82:83], v82 offset:2048
	s_waitcnt lgkmcnt(2)
	v_mfma_f32_16x16x32_bf16 v[68:71], v[76:79], v[72:75], v[68:71]
	v_add_u32_e32 v78, s29, v136
	ds_read_b64_tr_b16 v[76:77], v78
	ds_read_b64_tr_b16 v[78:79], v78 offset:2048
	s_waitcnt lgkmcnt(2)
	v_mfma_f32_16x16x32_bf16 v[60:63], v[80:83], v[72:75], v[60:63]
	v_add_u32_e32 v73, s29, v137
	v_cvt_pk_bf16_f32 v72, v133, v162
	ds_read_b64_tr_b16 v[80:81], v73
	ds_read_b64_tr_b16 v[82:83], v73 offset:2048
	v_cvt_pk_bf16_f32 v73, v163, v164
	v_cvt_pk_bf16_f32 v74, v96, v97
	v_cvt_pk_bf16_f32 v75, v98, v99
	v_exp_f32_e32 v96, v103
	v_fma_f32 v97, v173, s20, -v53
	s_waitcnt lgkmcnt(2)
	v_mfma_f32_16x16x32_bf16 v[56:59], v[76:79], v[72:75], v[56:59]
	v_add_u32_e32 v78, s29, v138
	ds_read_b64_tr_b16 v[76:77], v78
	ds_read_b64_tr_b16 v[78:79], v78 offset:2048
	v_add_f32_e32 v55, v96, v55
	s_waitcnt lgkmcnt(2)
	v_mfma_f32_16x16x32_bf16 v[64:67], v[80:83], v[72:75], v[64:67]
	v_add_u32_e32 v82, s29, v139
	ds_read_b64_tr_b16 v[80:81], v82
	ds_read_b64_tr_b16 v[82:83], v82 offset:2048
	s_waitcnt lgkmcnt(2)
	v_mfma_f32_16x16x32_bf16 v[68:71], v[76:79], v[72:75], v[68:71]
	v_add_u32_e32 v78, s28, v136
	ds_read_b64_tr_b16 v[76:77], v78
	ds_read_b64_tr_b16 v[78:79], v78 offset:2048
	s_waitcnt lgkmcnt(2)
	v_mfma_f32_16x16x32_bf16 v[60:63], v[80:83], v[72:75], v[60:63]
	v_add_u32_e32 v73, s28, v137
	v_cvt_pk_bf16_f32 v72, v84, v85
	ds_read_b64_tr_b16 v[80:81], v73
	ds_read_b64_tr_b16 v[82:83], v73 offset:2048
	v_cvt_pk_bf16_f32 v73, v86, v87
	v_cvt_pk_bf16_f32 v74, v88, v89
	v_cvt_pk_bf16_f32 v75, v90, v91
	v_exp_f32_e32 v84, v97
	v_fma_f32 v85, v174, s20, -v53
	s_waitcnt lgkmcnt(2)
	v_mfma_f32_16x16x32_bf16 v[56:59], v[76:79], v[72:75], v[56:59]
	v_add_u32_e32 v78, s28, v138
	ds_read_b64_tr_b16 v[76:77], v78
	ds_read_b64_tr_b16 v[78:79], v78 offset:2048
	v_exp_f32_e32 v85, v85
	s_waitcnt lgkmcnt(2)
	v_mfma_f32_16x16x32_bf16 v[64:67], v[80:83], v[72:75], v[64:67]
	v_add_u32_e32 v82, s28, v139
	ds_read_b64_tr_b16 v[80:81], v82
	ds_read_b64_tr_b16 v[82:83], v82 offset:2048
	v_add_f32_e32 v55, v84, v55
	s_waitcnt lgkmcnt(2)
	v_mfma_f32_16x16x32_bf16 v[68:71], v[76:79], v[72:75], v[68:71]
	v_add_u32_e32 v78, s27, v136
	ds_read_b64_tr_b16 v[76:77], v78
	ds_read_b64_tr_b16 v[78:79], v78 offset:2048
	v_add_f32_e32 v86, v85, v55
	s_waitcnt lgkmcnt(2)
	v_mfma_f32_16x16x32_bf16 v[60:63], v[80:83], v[72:75], v[60:63]
	v_add_u32_e32 v73, s27, v137
	v_cvt_pk_bf16_f32 v72, v165, v166
	ds_read_b64_tr_b16 v[80:81], v73
	ds_read_b64_tr_b16 v[82:83], v73 offset:2048
	v_cvt_pk_bf16_f32 v73, v167, v168
	v_cvt_pk_bf16_f32 v74, v169, v175
	v_cvt_pk_bf16_f32 v75, v176, v177
	v_add_u32_e32 v55, s27, v139
	v_exp_f32_e32 v87, v54
	s_waitcnt lgkmcnt(2)
	v_mfma_f32_16x16x32_bf16 v[56:59], v[76:79], v[72:75], v[56:59]
	v_add_u32_e32 v78, s27, v138
	ds_read_b64_tr_b16 v[76:77], v78
	ds_read_b64_tr_b16 v[78:79], v78 offset:2048
	v_sub_f32_e32 v88, v52, v53
	s_waitcnt lgkmcnt(2)
	v_mfma_f32_16x16x32_bf16 v[64:67], v[80:83], v[72:75], v[64:67]
	ds_read_b64_tr_b16 v[80:81], v55
	ds_read_b64_tr_b16 v[82:83], v55 offset:2048
	s_waitcnt lgkmcnt(2)
	v_mfma_f32_16x16x32_bf16 v[52:55], v[76:79], v[72:75], v[68:71]
	s_nop 2
	v_add_u32_e32 v70, s25, v136
	ds_read_b64_tr_b16 v[68:69], v70
	ds_read_b64_tr_b16 v[70:71], v70 offset:2048
	s_waitcnt lgkmcnt(2)
	v_mfma_f32_16x16x32_bf16 v[60:63], v[80:83], v[72:75], v[60:63]
	v_add_u32_e32 v73, s25, v137
	v_cvt_pk_bf16_f32 v72, v178, v179
	ds_read_b64_tr_b16 v[76:77], v73
	ds_read_b64_tr_b16 v[78:79], v73 offset:2048
	v_cvt_pk_bf16_f32 v73, v180, v181
	v_cvt_pk_bf16_f32 v74, v182, v183
	v_cvt_pk_bf16_f32 v75, v184, v100
	v_exp_f32_e32 v80, v88
	v_add_f32_e32 v81, v87, v86
	s_waitcnt lgkmcnt(2)
	v_mfma_f32_16x16x32_bf16 v[56:59], v[68:71], v[72:75], v[56:59]
	v_add_u32_e32 v70, s25, v138
	ds_read_b64_tr_b16 v[68:69], v70
	ds_read_b64_tr_b16 v[70:71], v70 offset:2048
	v_add_f32_e32 v81, v80, v81
	s_waitcnt lgkmcnt(2)
	v_mfma_f32_16x16x32_bf16 v[64:67], v[76:79], v[72:75], v[64:67]
	v_add_u32_e32 v78, s25, v139
	ds_read_b64_tr_b16 v[76:77], v78
	ds_read_b64_tr_b16 v[78:79], v78 offset:2048
	v_mov_b32_e32 v82, v81
	s_nop 1
	v_permlane16_swap_b32 v81, v82
	s_waitcnt lgkmcnt(3)
	v_mfma_f32_16x16x32_bf16 v[52:55], v[68:71], v[72:75], v[52:55]
	v_add_u32_e32 v70, s24, v136
	ds_read_b64_tr_b16 v[68:69], v70
	ds_read_b64_tr_b16 v[70:71], v70 offset:2048
	s_waitcnt lgkmcnt(3)
	v_mfma_f32_16x16x32_bf16 v[60:63], v[76:79], v[72:75], v[60:63]
	v_add_u32_e32 v75, s24, v137
	v_cvt_pk_bf16_f32 v72, v95, v101
	v_cvt_pk_bf16_f32 v73, v102, v96
	v_cvt_pk_bf16_f32 v74, v84, v85
	ds_read_b64_tr_b16 v[76:77], v75
	ds_read_b64_tr_b16 v[78:79], v75 offset:2048
	v_cvt_pk_bf16_f32 v75, v87, v80
	s_waitcnt lgkmcnt(4)
	v_add_f32_e32 v80, v81, v82
	ds_bpermute_b32 v81, v94, v80
	s_waitcnt lgkmcnt(3)
	v_mfma_f32_16x16x32_bf16 v[56:59], v[68:71], v[72:75], v[56:59]
	v_add_u32_e32 v70, s24, v138
	ds_read_b64_tr_b16 v[68:69], v70
	ds_read_b64_tr_b16 v[70:71], v70 offset:2048
	s_waitcnt lgkmcnt(0)
	v_mfma_f32_16x16x32_bf16 v[52:55], v[68:71], v[72:75], v[52:55]
	v_add_f32_e32 v68, v80, v81
	v_mfma_f32_16x16x32_bf16 v[64:67], v[76:79], v[72:75], v[64:67]
	v_add_u32_e32 v78, s24, v139
	v_div_scale_f32 v69, s[24:25], v68, v68, 1.0
	v_rcp_f32_e32 v70, v69
	ds_read_b64_tr_b16 v[76:77], v78
	ds_read_b64_tr_b16 v[78:79], v78 offset:2048
	s_waitcnt lgkmcnt(0)
	v_mfma_f32_16x16x32_bf16 v[60:63], v[76:79], v[72:75], v[60:63]
	v_fma_f32 v71, -v69, v70, 1.0
	v_fmac_f32_e32 v70, v71, v70
	v_div_scale_f32 v71, vcc, 1.0, v68, 1.0
	v_mul_f32_e32 v72, v71, v70
	v_fma_f32 v73, -v69, v72, v71
	v_fmac_f32_e32 v72, v73, v70
	v_fma_f32 v69, -v69, v72, v71
	v_div_fmas_f32 v69, v69, v70, v72
	v_div_fixup_f32 v68, v69, v68, 1.0
	v_lshl_add_u64 v[70:71], v[130:131], 0, s[18:19]
	v_mad_u64_u32 v[72:73], s[24:25], v70, s55, v[92:93]
	v_pk_mul_f32 v[56:57], v[68:69], v[56:57] op_sel_hi:[0,1]
	v_pk_mul_f32 v[58:59], v[68:69], v[58:59] op_sel_hi:[0,1]
	v_pk_mul_f32 v[52:53], v[68:69], v[52:53] op_sel_hi:[0,1]
	v_pk_mul_f32 v[54:55], v[68:69], v[54:55] op_sel_hi:[0,1]
	v_mad_i32_i24 v73, v71, s55, v73
	v_cvt_pk_bf16_f32 v56, v56, v57
	v_cvt_pk_bf16_f32 v57, v58, v59
	v_cvt_pk_bf16_f32 v52, v52, v53
	v_cvt_pk_bf16_f32 v53, v54, v55
	global_store_dwordx2 v[72:73], v[56:57], off
	v_pk_mul_f32 v[56:57], v[68:69], v[64:65] op_sel_hi:[0,1]
	v_pk_mul_f32 v[58:59], v[68:69], v[66:67] op_sel_hi:[0,1]
	global_store_dwordx2 v[72:73], v[52:53], off offset:64
	v_pk_mul_f32 v[52:53], v[68:69], v[60:61] op_sel_hi:[0,1]
	v_pk_mul_f32 v[54:55], v[68:69], v[62:63] op_sel_hi:[0,1]
	v_cvt_pk_bf16_f32 v56, v56, v57
	v_cvt_pk_bf16_f32 v57, v58, v59
	v_cvt_pk_bf16_f32 v52, v52, v53
	v_cvt_pk_bf16_f32 v53, v54, v55
	global_store_dwordx2 v[72:73], v[56:57], off offset:32
	global_store_dwordx2 v[72:73], v[52:53], off offset:96
	s_waitcnt lgkmcnt(0)
	s_barrier
	v_cmp_ne_u32_e32 vcc, 1, v161
	s_cbranch_vccnz .LBB0_590
	s_mul_i32 s18, s64, 57
	s_lshr_b32 s18, s18, 9
	s_mul_i32 s18, s18, 9
	s_sub_i32 s18, s64, s18
	s_and_b32 s18, s18, 0xff
	s_lshl_b32 s18, s18, 13
	v_add_u32_e32 v52, s18, v1
	ds_write_b128 v52, v[48:51]
	v_add_u32_e32 v48, s18, v123
	ds_write_b128 v48, v[44:47]

.LBB0_592:
	s_add_i32 s18, s26, 4
	s_max_i32 s24, s18, 4
	s_add_i32 s24, s24, -4
	s_min_u32 s39, s24, 24
	s_mul_i32 s24, s39, 29
	s_lshr_b32 s24, s24, 8
	s_mul_i32 s24, s24, 9
	s_sub_i32 s24, s39, s24
	s_and_b32 s24, s24, 0xff
	s_lshl_b32 s38, s24, 13
	s_add_i32 s24, s38, 0x100
	s_waitcnt lgkmcnt(0)
	s_barrier
	v_add_u32_e32 v40, s24, v134
	v_add_u32_e32 v48, s24, v135
	ds_read_b128 v[36:39], v40
	ds_read_b128 v[40:43], v40 offset:2048
	ds_read_b128 v[44:47], v48
	ds_read_b128 v[48:51], v48 offset:2048
	s_mul_i32 s24, s39, 57
	s_add_i32 s25, s24, 57
	s_bfe_u32 s25, s25, 0x30009
	s_mul_i32 s25, s25, 9
	s_sub_i32 s25, s39, s25
	s_waitcnt lgkmcnt(2)
	v_mfma_f32_16x16x32_bf16 v[40:43], v[40:43], v[32:35], 0
	s_add_i32 s25, s25, 1
	s_and_b32 s25, s25, 0xff
	s_lshl_b32 s35, s25, 13
	v_mfma_f32_16x16x32_bf16 v[36:39], v[36:39], v[32:35], 0
	s_add_i32 s25, s35, 0x100
	s_add_i32 s38, s53, s38
	s_add_i32 s35, s53, s35
	s_waitcnt lgkmcnt(0)
	v_mfma_f32_16x16x32_bf16 v[72:75], v[48:51], v[28:31], v[40:43]
	v_add_u32_e32 v48, s25, v135
	s_nop 1
	v_add_u32_e32 v40, s25, v134
	v_mfma_f32_16x16x32_bf16 v[68:71], v[44:47], v[28:31], v[36:39]
	s_add_i32 s25, s24, 0x72
	s_bfe_u32 s25, s25, 0x30009
	s_mul_i32 s25, s25, 9
	ds_read_b128 v[36:39], v40
	ds_read_b128 v[40:43], v40 offset:2048
	s_waitcnt lgkmcnt(1)
	v_mfma_f32_16x16x32_bf16 v[36:39], v[36:39], v[32:35], 0
	ds_read_b128 v[44:47], v48
	ds_read_b128 v[48:51], v48 offset:2048
	s_sub_i32 s25, s39, s25
	s_add_i32 s25, s25, 2
	s_waitcnt lgkmcnt(1)
	v_mfma_f32_16x16x32_bf16 v[76:79], v[44:47], v[28:31], v[36:39]
	s_and_b32 s25, s25, 0xff
	s_lshl_b32 s34, s25, 13
	s_add_i32 s25, s34, 0x100
	v_mfma_f32_16x16x32_bf16 v[36:39], v[40:43], v[32:35], 0
	v_add_u32_e32 v40, s25, v134
	s_add_i32 s34, s53, s34
	s_waitcnt lgkmcnt(0)
	v_mfma_f32_16x16x32_bf16 v[80:83], v[48:51], v[28:31], v[36:39]
	v_add_u32_e32 v48, s25, v135
	s_add_i32 s25, s24, 0xab
	s_bfe_u32 s25, s25, 0x30009
	s_nop 0
	ds_read_b128 v[36:39], v40
	ds_read_b128 v[40:43], v40 offset:2048
	s_waitcnt lgkmcnt(1)
	v_mfma_f32_16x16x32_bf16 v[36:39], v[36:39], v[32:35], 0
	ds_read_b128 v[44:47], v48
	ds_read_b128 v[48:51], v48 offset:2048
	s_mul_i32 s25, s25, 9
	s_sub_i32 s25, s39, s25
	s_add_i32 s25, s25, 3
	s_waitcnt lgkmcnt(1)
	v_mfma_f32_16x16x32_bf16 v[84:87], v[44:47], v[28:31], v[36:39]
	s_and_b32 s25, s25, 0xff
	s_lshl_b32 s29, s25, 13
	s_add_i32 s25, s29, 0x100
	v_mfma_f32_16x16x32_bf16 v[36:39], v[40:43], v[32:35], 0
	v_add_u32_e32 v40, s25, v134
	s_add_i32 s29, s53, s29
	s_waitcnt lgkmcnt(0)
	v_mfma_f32_16x16x32_bf16 v[88:91], v[48:51], v[28:31], v[36:39]
	v_add_u32_e32 v48, s25, v135
	s_add_i32 s25, s24, 0xe4
	s_bfe_u32 s25, s25, 0x30009
	s_nop 0
	ds_read_b128 v[36:39], v40
	ds_read_b128 v[40:43], v40 offset:2048
	s_waitcnt lgkmcnt(1)
	v_mfma_f32_16x16x32_bf16 v[36:39], v[36:39], v[32:35], 0
	ds_read_b128 v[44:47], v48
	ds_read_b128 v[48:51], v48 offset:2048
	s_mul_i32 s25, s25, 9
	s_sub_i32 s25, s39, s25
	s_add_i32 s25, s25, 4
	s_waitcnt lgkmcnt(1)
	v_mfma_f32_16x16x32_bf16 v[96:99], v[44:47], v[28:31], v[36:39]
	s_and_b32 s25, s25, 0xff
	s_lshl_b32 s28, s25, 13
	s_add_i32 s25, s28, 0x100
	v_mfma_f32_16x16x32_bf16 v[36:39], v[40:43], v[32:35], 0
	v_add_u32_e32 v40, s25, v134
	s_add_i32 s28, s53, s28
	s_waitcnt lgkmcnt(0)
	v_mfma_f32_16x16x32_bf16 v[64:67], v[48:51], v[28:31], v[36:39]
	v_add_u32_e32 v48, s25, v135
	s_add_i32 s25, s24, 0x11d
	s_bfe_u32 s25, s25, 0x30009
	s_nop 0
	ds_read_b128 v[36:39], v40
	ds_read_b128 v[40:43], v40 offset:2048
	s_waitcnt lgkmcnt(1)
	v_mfma_f32_16x16x32_bf16 v[36:39], v[36:39], v[32:35], 0
	ds_read_b128 v[44:47], v48
	ds_read_b128 v[48:51], v48 offset:2048
	s_mul_i32 s25, s25, 9
	s_sub_i32 s25, s39, s25
	s_add_i32 s25, s25, 5
	s_waitcnt lgkmcnt(1)
	v_mfma_f32_16x16x32_bf16 v[60:63], v[44:47], v[28:31], v[36:39]
	s_and_b32 s25, s25, 0xff
	s_lshl_b32 s27, s25, 13
	s_add_i32 s25, s27, 0x100
	v_mfma_f32_16x16x32_bf16 v[36:39], v[40:43], v[32:35], 0
	v_add_u32_e32 v40, s25, v134
	s_add_i32 s27, s53, s27
	s_waitcnt lgkmcnt(0)
	v_mfma_f32_16x16x32_bf16 v[56:59], v[48:51], v[28:31], v[36:39]
	v_add_u32_e32 v48, s25, v135
	s_add_i32 s25, s24, 0x156
	s_bfe_u32 s25, s25, 0x30009
	s_nop 0
	ds_read_b128 v[36:39], v40
	ds_read_b128 v[40:43], v40 offset:2048
	s_waitcnt lgkmcnt(1)
	v_mfma_f32_16x16x32_bf16 v[36:39], v[36:39], v[32:35], 0
	ds_read_b128 v[44:47], v48
	ds_read_b128 v[48:51], v48 offset:2048
	s_mul_i32 s25, s25, 9
	s_sub_i32 s25, s39, s25
	s_add_i32 s25, s25, 6
	s_waitcnt lgkmcnt(1)
	v_mfma_f32_16x16x32_bf16 v[52:55], v[44:47], v[28:31], v[36:39]
	s_and_b32 s25, s25, 0xff
	s_lshl_b32 s25, s25, 13
	s_add_i32 s63, s25, 0x100
	v_mfma_f32_16x16x32_bf16 v[36:39], v[40:43], v[32:35], 0
	v_add_u32_e32 v40, s63, v134
	v_add_u32_e32 v95, s63, v135
	s_addk_i32 s24, 0x18f
	s_waitcnt lgkmcnt(0)
	v_mfma_f32_16x16x32_bf16 v[48:51], v[48:51], v[28:31], v[36:39]
	s_bfe_u32 s24, s24, 0x30009
	s_mul_i32 s24, s24, 9
	s_sub_i32 s24, s39, s24
	ds_read_b128 v[36:39], v40
	ds_read_b128 v[40:43], v40 offset:2048
	s_waitcnt lgkmcnt(1)
	v_mfma_f32_16x16x32_bf16 v[36:39], v[36:39], v[32:35], 0
	ds_read_b128 v[44:47], v95
	ds_read_b128 v[100:103], v95 offset:2048
	s_add_i32 s24, s24, 7
	s_and_b32 s24, s24, 0xff
	s_waitcnt lgkmcnt(1)
	v_mfma_f32_16x16x32_bf16 v[44:47], v[44:47], v[28:31], v[36:39]
	s_lshl_b32 s24, s24, 13
	s_add_i32 s63, s24, 0x100
	v_add_u32_e32 v95, s63, v134
	v_mfma_f32_16x16x32_bf16 v[36:39], v[40:43], v[32:35], 0
	v_add_u32_e32 v108, s63, v135
	s_sub_i32 s39, s39, s18
	s_mulk_i32 s39, 0x7c
	s_waitcnt lgkmcnt(0)
	v_mfma_f32_16x16x32_bf16 v[40:43], v[100:103], v[28:31], v[36:39]
	ds_read_b128 v[100:103], v95 offset:2048
	s_add_i32 s25, s53, s25
	s_add_i32 s24, s53, s24
	ds_read_b128 v[36:39], v95
	ds_read_b128 v[104:107], v108
	ds_read_b128 v[108:111], v108 offset:2048
	s_waitcnt lgkmcnt(2)
	v_mfma_f32_16x16x32_bf16 v[36:39], v[36:39], v[32:35], 0
	v_add_u32_e32 v95, s39, v148
	s_lshl_b32 s18, s18, 6
	v_mfma_f32_16x16x32_bf16 v[32:35], v[100:103], v[32:35], 0
	ds_read2_b32 v[100:101], v95 offset0:232 offset1:233
	s_waitcnt lgkmcnt(0)
	v_add_f32_e32 v68, v68, v100
	v_mfma_f32_16x16x32_bf16 v[36:39], v[104:107], v[28:31], v[36:39]
	v_add_f32_e32 v100, v140, v68
	v_add_f32_e32 v68, v69, v101
	v_add_f32_e32 v101, v141, v68
	v_mfma_f32_16x16x32_bf16 v[28:31], v[108:111], v[28:31], v[32:35]
	s_nop 2
	ds_read2_b32 v[32:33], v95 offset0:234 offset1:235
	ds_read2_b32 v[34:35], v95 offset0:248 offset1:249
	ds_read2_b32 v[102:103], v95 offset0:250 offset1:251
	v_max3_f32 v68, v100, s59, v101
	s_waitcnt lgkmcnt(2)
	v_add_f32_e32 v32, v70, v32
	v_add_f32_e32 v104, v142, v32
	v_add_f32_e32 v32, v71, v33
	s_waitcnt lgkmcnt(1)
	v_add_f32_e32 v33, v72, v34
	v_add_f32_e32 v72, v144, v33
	v_add_f32_e32 v33, v73, v35
	v_add_f32_e32 v105, v143, v32
	v_add_f32_e32 v73, v145, v33
	s_waitcnt lgkmcnt(0)
	v_add_f32_e32 v33, v74, v102
	v_max3_f32 v32, v68, v104, v105
	v_add_f32_e32 v74, v146, v33
	v_add_f32_e32 v33, v75, v103
	v_max3_f32 v32, v32, v72, v73
	v_add_f32_e32 v75, v147, v33
	v_max3_f32 v102, v32, v74, v75
	v_add_u32_e32 v32, 0x41c, v95
	ds_read2_b32 v[32:33], v32 offset1:1
	v_add_u32_e32 v34, 0x424, v95
	v_add_u32_e32 v68, 0x45c, v95
	v_add_u32_e32 v70, 0x464, v95
	ds_read2_b32 v[34:35], v34 offset1:1
	ds_read2_b32 v[68:69], v68 offset1:1
	ds_read2_b32 v[70:71], v70 offset1:1
	s_waitcnt lgkmcnt(3)
	v_add_f32_e32 v32, v76, v32
	v_add_f32_e32 v76, v140, v32
	v_add_f32_e32 v32, v77, v33
	s_waitcnt lgkmcnt(2)
	v_add_f32_e32 v33, v78, v34
	v_add_f32_e32 v78, v142, v33
	v_add_f32_e32 v33, v79, v35
	v_add_f32_e32 v79, v143, v33
	s_waitcnt lgkmcnt(1)
	v_add_f32_e32 v33, v80, v68
	v_add_f32_e32 v77, v141, v32
	v_add_f32_e32 v80, v144, v33
	v_add_f32_e32 v33, v81, v69
	v_max3_f32 v32, v102, v76, v77
	v_add_f32_e32 v81, v145, v33
	s_waitcnt lgkmcnt(0)
	v_add_f32_e32 v33, v82, v70
	v_max3_f32 v32, v32, v78, v79
	v_add_f32_e32 v82, v146, v33
	v_add_f32_e32 v33, v83, v71
	v_max3_f32 v32, v32, v80, v81
	v_add_f32_e32 v83, v147, v33
	v_max3_f32 v102, v32, v82, v83
	v_add_u32_e32 v32, 0x498, v95
	ds_read2_b32 v[32:33], v32 offset1:1
	v_add_u32_e32 v34, 0x4a0, v95
	v_add_u32_e32 v68, 0x4d8, v95
	v_add_u32_e32 v70, 0x4e0, v95
	ds_read2_b32 v[34:35], v34 offset1:1
	ds_read2_b32 v[68:69], v68 offset1:1
	ds_read2_b32 v[70:71], v70 offset1:1
	s_waitcnt lgkmcnt(3)
	v_add_f32_e32 v32, v84, v32
	v_add_f32_e32 v84, v140, v32
	v_add_f32_e32 v32, v85, v33
	s_waitcnt lgkmcnt(2)
	v_add_f32_e32 v33, v86, v34
	v_add_f32_e32 v86, v142, v33
	v_add_f32_e32 v33, v87, v35
	v_add_f32_e32 v87, v143, v33
	s_waitcnt lgkmcnt(1)
	v_add_f32_e32 v33, v88, v68
	v_add_f32_e32 v85, v141, v32
	v_add_f32_e32 v88, v144, v33
	v_add_f32_e32 v33, v89, v69
	v_max3_f32 v32, v102, v84, v85
	v_add_f32_e32 v89, v145, v33
	s_waitcnt lgkmcnt(0)
	v_add_f32_e32 v33, v90, v70
	v_max3_f32 v32, v32, v86, v87
	v_add_f32_e32 v90, v146, v33
	v_add_f32_e32 v33, v91, v71
	v_max3_f32 v32, v32, v88, v89
	v_add_f32_e32 v91, v147, v33
	v_max3_f32 v102, v32, v90, v91
	v_add_u32_e32 v32, 0x514, v95
	ds_read2_b32 v[32:33], v32 offset1:1
	v_add_u32_e32 v34, 0x51c, v95
	v_add_u32_e32 v68, 0x554, v95
	v_add_u32_e32 v70, 0x55c, v95
	ds_read2_b32 v[34:35], v34 offset1:1
	ds_read2_b32 v[68:69], v68 offset1:1
	ds_read2_b32 v[70:71], v70 offset1:1
	s_waitcnt lgkmcnt(3)
	v_add_f32_e32 v32, v96, v32
	v_add_f32_e32 v96, v140, v32
	v_add_f32_e32 v32, v97, v33
	s_waitcnt lgkmcnt(2)
	v_add_f32_e32 v33, v98, v34
	v_add_f32_e32 v98, v142, v33
	v_add_f32_e32 v33, v99, v35
	v_add_f32_e32 v99, v143, v33
	s_waitcnt lgkmcnt(1)
	v_add_f32_e32 v33, v64, v68
	v_add_f32_e32 v97, v141, v32
	v_add_f32_e32 v68, v144, v33
	v_add_f32_e32 v33, v65, v69
	v_max3_f32 v32, v102, v96, v97
	v_add_f32_e32 v69, v145, v33
	s_waitcnt lgkmcnt(0)
	v_add_f32_e32 v33, v66, v70
	v_max3_f32 v32, v32, v98, v99
	v_add_f32_e32 v70, v146, v33
	v_add_f32_e32 v33, v67, v71
	v_max3_f32 v32, v32, v68, v69
	v_add_f32_e32 v71, v147, v33
	v_max3_f32 v102, v32, v70, v71
	v_add_u32_e32 v32, 0x590, v95
	ds_read2_b32 v[32:33], v32 offset1:1
	v_add_u32_e32 v34, 0x598, v95
	v_add_u32_e32 v64, 0x5d0, v95
	v_add_u32_e32 v66, 0x5d8, v95
	ds_read2_b32 v[34:35], v34 offset1:1
	ds_read2_b32 v[64:65], v64 offset1:1
	ds_read2_b32 v[66:67], v66 offset1:1
	s_waitcnt lgkmcnt(3)
	v_add_f32_e32 v32, v60, v32
	v_add_f32_e32 v60, v140, v32
	v_add_f32_e32 v32, v61, v33
	s_waitcnt lgkmcnt(2)
	v_add_f32_e32 v33, v62, v34
	v_add_f32_e32 v62, v142, v33
	v_add_f32_e32 v33, v63, v35
	v_add_f32_e32 v63, v143, v33
	s_waitcnt lgkmcnt(1)
	v_add_f32_e32 v33, v56, v64
	v_add_f32_e32 v61, v141, v32
	v_add_f32_e32 v64, v144, v33
	v_add_f32_e32 v33, v57, v65
	v_max3_f32 v32, v102, v60, v61
	v_add_f32_e32 v65, v145, v33
	s_waitcnt lgkmcnt(0)
	v_add_f32_e32 v33, v58, v66
	v_max3_f32 v32, v32, v62, v63
	v_add_f32_e32 v66, v146, v33
	v_add_f32_e32 v33, v59, v67
	v_max3_f32 v32, v32, v64, v65
	v_add_f32_e32 v67, v147, v33
	v_max3_f32 v102, v32, v66, v67
	v_add_u32_e32 v32, 0x60c, v95
	ds_read2_b32 v[32:33], v32 offset1:1
	v_add_u32_e32 v34, 0x614, v95
	v_add_u32_e32 v56, 0x64c, v95
	v_add_u32_e32 v58, 0x654, v95
	ds_read2_b32 v[34:35], v34 offset1:1
	ds_read2_b32 v[56:57], v56 offset1:1
	ds_read2_b32 v[58:59], v58 offset1:1
	s_waitcnt lgkmcnt(3)
	v_add_f32_e32 v32, v52, v32
	v_add_f32_e32 v52, v140, v32
	v_add_f32_e32 v32, v53, v33
	s_waitcnt lgkmcnt(2)
	v_add_f32_e32 v33, v54, v34
	v_add_f32_e32 v54, v142, v33
	v_add_f32_e32 v33, v55, v35
	v_add_f32_e32 v55, v143, v33
	s_waitcnt lgkmcnt(1)
	v_add_f32_e32 v33, v48, v56
	v_add_f32_e32 v53, v141, v32
	v_add_f32_e32 v56, v144, v33
	v_add_f32_e32 v33, v49, v57
	v_max3_f32 v32, v102, v52, v53
	v_add_f32_e32 v57, v145, v33
	s_waitcnt lgkmcnt(0)
	v_add_f32_e32 v33, v50, v58
	v_max3_f32 v32, v32, v54, v55
	v_add_f32_e32 v58, v146, v33
	v_add_f32_e32 v33, v51, v59
	v_max3_f32 v32, v32, v56, v57
	v_add_f32_e32 v59, v147, v33
	v_max3_f32 v102, v32, v58, v59
	v_add_u32_e32 v32, 0x688, v95
	ds_read2_b32 v[32:33], v32 offset1:1
	v_add_u32_e32 v34, 0x690, v95
	v_add_u32_e32 v48, 0x6c8, v95
	v_add_u32_e32 v50, 0x6d0, v95
	ds_read2_b32 v[34:35], v34 offset1:1
	ds_read2_b32 v[48:49], v48 offset1:1
	ds_read2_b32 v[50:51], v50 offset1:1
	s_waitcnt lgkmcnt(3)
	v_add_f32_e32 v32, v44, v32
	v_add_f32_e32 v44, v140, v32
	v_add_f32_e32 v32, v45, v33
	s_waitcnt lgkmcnt(2)
	v_add_f32_e32 v33, v46, v34
	v_add_f32_e32 v46, v142, v33
	v_add_f32_e32 v33, v47, v35
	v_add_f32_e32 v47, v143, v33
	s_waitcnt lgkmcnt(1)
	v_add_f32_e32 v33, v40, v48
	v_add_f32_e32 v45, v141, v32
	v_add_f32_e32 v48, v144, v33
	v_add_f32_e32 v33, v41, v49
	v_max3_f32 v32, v102, v44, v45
	v_add_f32_e32 v49, v145, v33
	s_waitcnt lgkmcnt(0)
	v_add_f32_e32 v33, v42, v50
	v_max3_f32 v32, v32, v46, v47
	v_add_f32_e32 v50, v146, v33
	v_add_f32_e32 v33, v43, v51
	v_max3_f32 v32, v32, v48, v49
	v_add_f32_e32 v51, v147, v33
	v_max3_f32 v102, v32, v50, v51
	v_add_u32_e32 v32, 0x704, v95
	ds_read2_b32 v[32:33], v32 offset1:1
	v_add_u32_e32 v34, 0x70c, v95
	v_add_u32_e32 v40, 0x744, v95
	v_add_u32_e32 v42, 0x74c, v95
	ds_read2_b32 v[34:35], v34 offset1:1
	ds_read2_b32 v[40:41], v40 offset1:1
	ds_read2_b32 v[42:43], v42 offset1:1
	s_waitcnt lgkmcnt(3)
	v_add_f32_e32 v32, v36, v32
	v_add_f32_e32 v95, v140, v32
	v_add_f32_e32 v32, v37, v33
	v_add_f32_e32 v103, v141, v32
	s_waitcnt lgkmcnt(2)
	v_add_f32_e32 v33, v38, v34
	s_waitcnt lgkmcnt(1)
	v_add_f32_e32 v28, v28, v40
	v_max3_f32 v32, v102, v95, v103
	v_add_f32_e32 v102, v142, v33
	v_add_f32_e32 v33, v39, v35
	v_add_f32_e32 v107, v144, v28
	v_add_f32_e32 v28, v29, v41
	v_add_f32_e32 v106, v143, v33
	v_add_f32_e32 v108, v145, v28
	s_waitcnt lgkmcnt(0)
	v_add_f32_e32 v28, v30, v42
	v_max3_f32 v32, v32, v102, v106
	v_add_f32_e32 v30, v146, v28
	v_add_f32_e32 v28, v31, v43
	v_max3_f32 v29, v32, v107, v108
	v_add_f32_e32 v28, v147, v28
	v_max3_f32 v29, v29, v30, v28
	v_mov_b32_e32 v31, v29
	s_nop 1
	v_permlane16_swap_b32 v29, v31
	v_add_u32_e32 v34, s38, v136
	s_waitcnt lgkmcnt(0)
	v_max_f32_e32 v31, v31, v31
	v_max_f32_e32 v29, v29, v31
	v_mov_b32_e32 v31, v29
	s_nop 1
	v_permlane32_swap_b32 v29, v31
	s_waitcnt lgkmcnt(0)
	v_max_f32_e32 v31, v31, v31
	v_max_f32_e32 v29, v29, v31
	v_pk_mul_f32 v[28:29], v[28:29], s[20:21] op_sel_hi:[1,0]
	s_nop 0
	v_fma_f32 v31, v100, s20, -v29
	v_exp_f32_e32 v31, v31
	v_fma_f32 v32, v101, s20, -v29
	v_exp_f32_e32 v36, v32
	v_fma_f32 v33, v104, s20, -v29
	v_exp_f32_e32 v37, v33
	v_fma_f32 v33, v105, s20, -v29
	v_exp_f32_e32 v38, v33
	v_fma_f32 v33, v72, s20, -v29
	v_add_f32_e32 v32, 0, v31
	v_exp_f32_e32 v39, v33
	v_fma_f32 v33, v73, s20, -v29
	v_add_f32_e32 v32, v36, v32
	v_exp_f32_e32 v72, v33
	v_fma_f32 v33, v74, s20, -v29
	v_add_f32_e32 v32, v37, v32
	v_exp_f32_e32 v73, v33
	v_fma_f32 v33, v75, s20, -v29
	v_add_f32_e32 v32, v38, v32
	v_exp_f32_e32 v74, v33
	v_fma_f32 v33, v76, s20, -v29
	v_add_f32_e32 v32, v39, v32
	v_exp_f32_e32 v75, v33
	v_fma_f32 v33, v77, s20, -v29
	v_add_f32_e32 v32, v72, v32
	v_exp_f32_e32 v76, v33
	v_fma_f32 v33, v78, s20, -v29
	v_add_f32_e32 v32, v73, v32
	v_exp_f32_e32 v77, v33
	v_fma_f32 v33, v79, s20, -v29
	v_add_f32_e32 v32, v74, v32
	v_exp_f32_e32 v78, v33
	v_fma_f32 v33, v80, s20, -v29
	v_add_f32_e32 v32, v75, v32
	v_exp_f32_e32 v79, v33
	v_fma_f32 v33, v81, s20, -v29
	v_add_f32_e32 v32, v76, v32
	v_exp_f32_e32 v80, v33
	v_fma_f32 v33, v82, s20, -v29
	v_add_f32_e32 v32, v77, v32
	v_exp_f32_e32 v81, v33
	v_fma_f32 v33, v83, s20, -v29
	v_add_f32_e32 v32, v78, v32
	v_exp_f32_e32 v82, v33
	v_fma_f32 v33, v84, s20, -v29
	v_add_f32_e32 v32, v79, v32
	v_exp_f32_e32 v83, v33
	v_fma_f32 v33, v85, s20, -v29
	v_add_f32_e32 v32, v80, v32
	v_exp_f32_e32 v84, v33
	v_fma_f32 v33, v86, s20, -v29
	v_add_f32_e32 v32, v81, v32
	v_exp_f32_e32 v85, v33
	v_fma_f32 v33, v87, s20, -v29
	v_add_f32_e32 v32, v82, v32
	v_exp_f32_e32 v86, v33
	v_fma_f32 v33, v88, s20, -v29
	v_add_f32_e32 v32, v83, v32
	v_exp_f32_e32 v87, v33
	v_fma_f32 v33, v89, s20, -v29
	v_add_f32_e32 v32, v84, v32
	v_exp_f32_e32 v88, v33
	v_fma_f32 v33, v90, s20, -v29
	v_add_f32_e32 v32, v85, v32
	v_exp_f32_e32 v89, v33
	v_fma_f32 v33, v91, s20, -v29
	v_add_f32_e32 v32, v86, v32
	v_exp_f32_e32 v90, v33
	v_fma_f32 v33, v96, s20, -v29
	v_add_f32_e32 v32, v87, v32
	v_exp_f32_e32 v91, v33
	v_fma_f32 v33, v97, s20, -v29
	v_add_f32_e32 v32, v88, v32
	v_exp_f32_e32 v96, v33
	v_fma_f32 v33, v98, s20, -v29
	v_add_f32_e32 v32, v89, v32
	v_exp_f32_e32 v97, v33
	v_fma_f32 v33, v99, s20, -v29
	v_add_f32_e32 v32, v90, v32
	v_exp_f32_e32 v98, v33
	v_fma_f32 v33, v68, s20, -v29
	v_add_f32_e32 v32, v91, v32
	v_exp_f32_e32 v68, v33
	v_fma_f32 v33, v69, s20, -v29
	v_add_f32_e32 v32, v96, v32
	v_exp_f32_e32 v69, v33
	v_fma_f32 v33, v70, s20, -v29
	v_add_f32_e32 v32, v97, v32
	v_exp_f32_e32 v70, v33
	v_fma_f32 v33, v71, s20, -v29
	v_add_f32_e32 v32, v98, v32
	v_exp_f32_e32 v71, v33
	v_fma_f32 v33, v60, s20, -v29
	v_add_f32_e32 v32, v68, v32
	v_exp_f32_e32 v60, v33
	v_fma_f32 v33, v61, s20, -v29
	v_add_f32_e32 v32, v69, v32
	v_exp_f32_e32 v61, v33
	v_fma_f32 v33, v62, s20, -v29
	v_add_f32_e32 v32, v70, v32
	v_exp_f32_e32 v62, v33
	v_fma_f32 v33, v63, s20, -v29
	v_add_f32_e32 v32, v71, v32
	v_exp_f32_e32 v63, v33
	v_fma_f32 v33, v64, s20, -v29
	v_add_f32_e32 v32, v60, v32
	v_exp_f32_e32 v64, v33
	v_fma_f32 v33, v65, s20, -v29
	v_add_f32_e32 v32, v61, v32
	v_exp_f32_e32 v65, v33
	v_fma_f32 v33, v66, s20, -v29
	v_add_f32_e32 v32, v62, v32
	v_exp_f32_e32 v66, v33
	v_fma_f32 v33, v67, s20, -v29
	v_add_f32_e32 v32, v63, v32
	v_exp_f32_e32 v67, v33
	v_fma_f32 v33, v52, s20, -v29
	v_add_f32_e32 v32, v64, v32
	v_exp_f32_e32 v99, v33
	v_fma_f32 v33, v53, s20, -v29
	v_add_f32_e32 v32, v65, v32
	v_exp_f32_e32 v100, v33
	v_fma_f32 v33, v54, s20, -v29
	v_add_f32_e32 v32, v66, v32
	v_exp_f32_e32 v101, v33
	v_fma_f32 v33, v55, s20, -v29
	v_add_f32_e32 v32, v67, v32
	v_exp_f32_e32 v104, v33
	v_fma_f32 v33, v56, s20, -v29
	v_add_f32_e32 v32, v99, v32
	v_exp_f32_e32 v105, v33
	v_fma_f32 v33, v57, s20, -v29
	v_add_f32_e32 v32, v100, v32
	v_exp_f32_e32 v109, v33
	v_fma_f32 v33, v58, s20, -v29
	v_add_f32_e32 v32, v101, v32
	v_exp_f32_e32 v110, v33
	v_fma_f32 v33, v59, s20, -v29
	v_add_f32_e32 v32, v104, v32
	v_exp_f32_e32 v111, v33
	v_fma_f32 v33, v44, s20, -v29
	v_add_f32_e32 v32, v105, v32
	v_exp_f32_e32 v112, v33
	v_fma_f32 v33, v45, s20, -v29
	v_add_f32_e32 v32, v109, v32
	v_exp_f32_e32 v113, v33
	v_fma_f32 v33, v46, s20, -v29
	v_add_f32_e32 v32, v110, v32
	v_exp_f32_e32 v114, v33
	v_fma_f32 v33, v47, s20, -v29
	v_add_f32_e32 v32, v111, v32
	v_exp_f32_e32 v115, v33
	v_fma_f32 v33, v48, s20, -v29
	v_add_f32_e32 v32, v112, v32
	v_exp_f32_e32 v127, v33
	v_fma_f32 v33, v49, s20, -v29
	v_add_f32_e32 v32, v113, v32
	v_exp_f32_e32 v129, v33
	v_add_f32_e32 v32, v114, v32
	v_add_f32_e32 v32, v115, v32
	v_add_f32_e32 v32, v127, v32
	v_add_f32_e32 v52, v129, v32
	v_fma_f32 v32, v50, s20, -v29
	v_cvt_pk_bf16_f32 v36, v31, v36
	v_add_u32_e32 v31, s38, v137
	v_exp_f32_e32 v132, v32
	ds_read_b64_tr_b16 v[32:33], v34
	ds_read_b64_tr_b16 v[34:35], v34 offset:2048
	ds_read_b64_tr_b16 v[40:41], v31
	ds_read_b64_tr_b16 v[42:43], v31 offset:2048
	v_add_u32_e32 v31, s38, v138
	v_fma_f32 v48, v51, s20, -v29
	ds_read_b64_tr_b16 v[44:45], v31
	ds_read_b64_tr_b16 v[46:47], v31 offset:2048
	v_add_u32_e32 v31, s38, v139
	v_cvt_pk_bf16_f32 v37, v37, v38
	v_cvt_pk_bf16_f32 v38, v39, v72
	v_exp_f32_e32 v72, v48
	ds_read_b64_tr_b16 v[48:49], v31
	ds_read_b64_tr_b16 v[50:51], v31 offset:2048
	v_add_u32_e32 v54, s35, v136
	v_cvt_pk_bf16_f32 v39, v73, v74
	v_add_f32_e32 v31, v132, v52
	ds_read_b64_tr_b16 v[52:53], v54
	ds_read_b64_tr_b16 v[54:55], v54 offset:2048
	s_waitcnt lgkmcnt(8)
	v_mfma_f32_16x16x32_bf16 v[32:35], v[32:35], v[36:39], 0
	v_fma_f32 v73, v95, s20, -v29
	v_exp_f32_e32 v73, v73
	v_fma_f32 v74, v103, s20, -v29
	s_waitcnt lgkmcnt(6)
	v_mfma_f32_16x16x32_bf16 v[40:43], v[40:43], v[36:39], 0
	v_exp_f32_e32 v74, v74
	v_add_f32_e32 v31, v72, v31
	v_add_f32_e32 v31, v73, v31
	s_waitcnt lgkmcnt(4)
	v_mfma_f32_16x16x32_bf16 v[44:47], v[44:47], v[36:39], 0
	v_add_f32_e32 v31, v74, v31
	v_fma_f32 v30, v30, s20, -v29
	s_waitcnt lgkmcnt(2)
	v_mfma_f32_16x16x32_bf16 v[36:39], v[48:51], v[36:39], 0
	v_add_u32_e32 v49, s35, v137
	v_cvt_pk_bf16_f32 v48, v75, v76
	ds_read_b64_tr_b16 v[56:57], v49
	ds_read_b64_tr_b16 v[58:59], v49 offset:2048
	v_cvt_pk_bf16_f32 v49, v77, v78
	v_cvt_pk_bf16_f32 v50, v79, v80
	v_cvt_pk_bf16_f32 v51, v81, v82
	v_fma_f32 v75, v102, s20, -v29
	v_exp_f32_e32 v75, v75
	s_waitcnt lgkmcnt(2)
	v_mfma_f32_16x16x32_bf16 v[32:35], v[52:55], v[48:51], v[32:35]
	v_add_u32_e32 v54, s35, v138
	ds_read_b64_tr_b16 v[52:53], v54
	ds_read_b64_tr_b16 v[54:55], v54 offset:2048
	v_fma_f32 v76, v106, s20, -v29
	s_waitcnt lgkmcnt(2)
	v_mfma_f32_16x16x32_bf16 v[40:43], v[56:59], v[48:51], v[40:43]
	v_add_u32_e32 v58, s35, v139
	ds_read_b64_tr_b16 v[56:57], v58
	ds_read_b64_tr_b16 v[58:59], v58 offset:2048
	v_add_f32_e32 v31, v75, v31
	s_waitcnt lgkmcnt(2)
	v_mfma_f32_16x16x32_bf16 v[44:47], v[52:55], v[48:51], v[44:47]
	v_add_u32_e32 v54, s34, v136
	ds_read_b64_tr_b16 v[52:53], v54
	ds_read_b64_tr_b16 v[54:55], v54 offset:2048
	s_waitcnt lgkmcnt(2)
	v_mfma_f32_16x16x32_bf16 v[36:39], v[56:59], v[48:51], v[36:39]
	v_add_u32_e32 v49, s34, v137
	v_cvt_pk_bf16_f32 v48, v83, v84
	ds_read_b64_tr_b16 v[56:57], v49
	ds_read_b64_tr_b16 v[58:59], v49 offset:2048
	v_cvt_pk_bf16_f32 v49, v85, v86
	v_cvt_pk_bf16_f32 v50, v87, v88
	v_cvt_pk_bf16_f32 v51, v89, v90
	s_waitcnt lgkmcnt(2)
	s_nop 0
	v_mfma_f32_16x16x32_bf16 v[32:35], v[52:55], v[48:51], v[32:35]
	v_add_u32_e32 v54, s34, v138
	ds_read_b64_tr_b16 v[52:53], v54
	ds_read_b64_tr_b16 v[54:55], v54 offset:2048
	s_waitcnt lgkmcnt(2)
	v_mfma_f32_16x16x32_bf16 v[40:43], v[56:59], v[48:51], v[40:43]
	v_add_u32_e32 v58, s34, v139
	ds_read_b64_tr_b16 v[56:57], v58
	ds_read_b64_tr_b16 v[58:59], v58 offset:2048
	s_waitcnt lgkmcnt(2)
	v_mfma_f32_16x16x32_bf16 v[44:47], v[52:55], v[48:51], v[44:47]
	v_add_u32_e32 v54, s29, v136
	ds_read_b64_tr_b16 v[52:53], v54
	ds_read_b64_tr_b16 v[54:55], v54 offset:2048
	s_waitcnt lgkmcnt(2)
	v_mfma_f32_16x16x32_bf16 v[36:39], v[56:59], v[48:51], v[36:39]
	v_add_u32_e32 v49, s29, v137
	v_cvt_pk_bf16_f32 v48, v91, v96
	ds_read_b64_tr_b16 v[56:57], v49
	ds_read_b64_tr_b16 v[58:59], v49 offset:2048
	v_cvt_pk_bf16_f32 v49, v97, v98
	v_cvt_pk_bf16_f32 v50, v68, v69
	v_cvt_pk_bf16_f32 v51, v70, v71
	v_exp_f32_e32 v68, v76
	v_fma_f32 v69, v107, s20, -v29
	s_waitcnt lgkmcnt(2)
	v_mfma_f32_16x16x32_bf16 v[32:35], v[52:55], v[48:51], v[32:35]
	v_add_u32_e32 v54, s29, v138
	ds_read_b64_tr_b16 v[52:53], v54
	ds_read_b64_tr_b16 v[54:55], v54 offset:2048
	v_add_f32_e32 v31, v68, v31
	s_waitcnt lgkmcnt(2)
	v_mfma_f32_16x16x32_bf16 v[40:43], v[56:59], v[48:51], v[40:43]
	v_add_u32_e32 v58, s29, v139
	ds_read_b64_tr_b16 v[56:57], v58
	ds_read_b64_tr_b16 v[58:59], v58 offset:2048
	s_waitcnt lgkmcnt(2)
	v_mfma_f32_16x16x32_bf16 v[44:47], v[52:55], v[48:51], v[44:47]
	v_add_u32_e32 v54, s28, v136
	ds_read_b64_tr_b16 v[52:53], v54
	ds_read_b64_tr_b16 v[54:55], v54 offset:2048
	s_waitcnt lgkmcnt(2)
	v_mfma_f32_16x16x32_bf16 v[36:39], v[56:59], v[48:51], v[36:39]
	v_add_u32_e32 v49, s28, v137
	v_cvt_pk_bf16_f32 v48, v60, v61
	ds_read_b64_tr_b16 v[56:57], v49
	ds_read_b64_tr_b16 v[58:59], v49 offset:2048
	v_cvt_pk_bf16_f32 v49, v62, v63
	v_cvt_pk_bf16_f32 v50, v64, v65
	v_cvt_pk_bf16_f32 v51, v66, v67
	v_exp_f32_e32 v60, v69
	v_fma_f32 v61, v108, s20, -v29
	s_waitcnt lgkmcnt(2)
	v_mfma_f32_16x16x32_bf16 v[32:35], v[52:55], v[48:51], v[32:35]
	v_add_u32_e32 v54, s28, v138
	ds_read_b64_tr_b16 v[52:53], v54
	ds_read_b64_tr_b16 v[54:55], v54 offset:2048
	v_exp_f32_e32 v61, v61
	s_waitcnt lgkmcnt(2)
	v_mfma_f32_16x16x32_bf16 v[40:43], v[56:59], v[48:51], v[40:43]
	v_add_u32_e32 v58, s28, v139
	ds_read_b64_tr_b16 v[56:57], v58
	ds_read_b64_tr_b16 v[58:59], v58 offset:2048
	v_add_f32_e32 v31, v60, v31
	s_waitcnt lgkmcnt(2)
	v_mfma_f32_16x16x32_bf16 v[44:47], v[52:55], v[48:51], v[44:47]
	v_add_u32_e32 v54, s27, v136
	ds_read_b64_tr_b16 v[52:53], v54
	ds_read_b64_tr_b16 v[54:55], v54 offset:2048
	v_add_f32_e32 v62, v61, v31
	s_waitcnt lgkmcnt(2)
	v_mfma_f32_16x16x32_bf16 v[36:39], v[56:59], v[48:51], v[36:39]
	v_add_u32_e32 v49, s27, v137
	v_cvt_pk_bf16_f32 v48, v99, v100
	ds_read_b64_tr_b16 v[56:57], v49
	ds_read_b64_tr_b16 v[58:59], v49 offset:2048
	v_cvt_pk_bf16_f32 v49, v101, v104
	v_cvt_pk_bf16_f32 v50, v105, v109
	v_cvt_pk_bf16_f32 v51, v110, v111
	v_add_u32_e32 v31, s27, v139
	v_exp_f32_e32 v63, v30
	s_waitcnt lgkmcnt(2)
	v_mfma_f32_16x16x32_bf16 v[32:35], v[52:55], v[48:51], v[32:35]
	v_add_u32_e32 v54, s27, v138
	ds_read_b64_tr_b16 v[52:53], v54
	ds_read_b64_tr_b16 v[54:55], v54 offset:2048
	v_sub_f32_e32 v64, v28, v29
	s_waitcnt lgkmcnt(2)
	v_mfma_f32_16x16x32_bf16 v[40:43], v[56:59], v[48:51], v[40:43]
	ds_read_b64_tr_b16 v[56:57], v31
	ds_read_b64_tr_b16 v[58:59], v31 offset:2048
	s_waitcnt lgkmcnt(2)
	v_mfma_f32_16x16x32_bf16 v[28:31], v[52:55], v[48:51], v[44:47]
	s_nop 2
	v_add_u32_e32 v46, s25, v136
	ds_read_b64_tr_b16 v[44:45], v46
	ds_read_b64_tr_b16 v[46:47], v46 offset:2048
	s_waitcnt lgkmcnt(2)
	v_mfma_f32_16x16x32_bf16 v[36:39], v[56:59], v[48:51], v[36:39]
	v_add_u32_e32 v49, s25, v137
	v_cvt_pk_bf16_f32 v48, v112, v113
	ds_read_b64_tr_b16 v[52:53], v49
	ds_read_b64_tr_b16 v[54:55], v49 offset:2048
	v_cvt_pk_bf16_f32 v49, v114, v115
	v_cvt_pk_bf16_f32 v50, v127, v129
	v_cvt_pk_bf16_f32 v51, v132, v72
	v_exp_f32_e32 v56, v64
	v_add_f32_e32 v57, v63, v62
	s_waitcnt lgkmcnt(2)
	v_mfma_f32_16x16x32_bf16 v[32:35], v[44:47], v[48:51], v[32:35]
	v_add_u32_e32 v46, s25, v138
	ds_read_b64_tr_b16 v[44:45], v46
	ds_read_b64_tr_b16 v[46:47], v46 offset:2048
	v_add_f32_e32 v57, v56, v57
	s_waitcnt lgkmcnt(2)
	v_mfma_f32_16x16x32_bf16 v[40:43], v[52:55], v[48:51], v[40:43]
	v_add_u32_e32 v54, s25, v139
	ds_read_b64_tr_b16 v[52:53], v54
	ds_read_b64_tr_b16 v[54:55], v54 offset:2048
	v_mov_b32_e32 v58, v57
	s_nop 1
	v_permlane16_swap_b32 v57, v58
	s_waitcnt lgkmcnt(3)
	v_mfma_f32_16x16x32_bf16 v[28:31], v[44:47], v[48:51], v[28:31]
	v_add_u32_e32 v46, s24, v136
	ds_read_b64_tr_b16 v[44:45], v46
	ds_read_b64_tr_b16 v[46:47], v46 offset:2048
	s_waitcnt lgkmcnt(3)
	v_mfma_f32_16x16x32_bf16 v[36:39], v[52:55], v[48:51], v[36:39]
	v_add_u32_e32 v51, s24, v137
	v_cvt_pk_bf16_f32 v48, v73, v74
	v_cvt_pk_bf16_f32 v49, v75, v68
	v_cvt_pk_bf16_f32 v50, v60, v61
	ds_read_b64_tr_b16 v[52:53], v51
	ds_read_b64_tr_b16 v[54:55], v51 offset:2048
	v_cvt_pk_bf16_f32 v51, v63, v56
	s_waitcnt lgkmcnt(4)
	v_add_f32_e32 v56, v57, v58
	ds_bpermute_b32 v57, v94, v56
	s_waitcnt lgkmcnt(3)
	v_mfma_f32_16x16x32_bf16 v[32:35], v[44:47], v[48:51], v[32:35]
	v_add_u32_e32 v46, s24, v138
	ds_read_b64_tr_b16 v[44:45], v46
	ds_read_b64_tr_b16 v[46:47], v46 offset:2048
	s_waitcnt lgkmcnt(0)
	v_mfma_f32_16x16x32_bf16 v[28:31], v[44:47], v[48:51], v[28:31]
	v_add_f32_e32 v44, v56, v57
	v_mfma_f32_16x16x32_bf16 v[40:43], v[52:55], v[48:51], v[40:43]
	v_add_u32_e32 v54, s24, v139
	v_div_scale_f32 v45, s[24:25], v44, v44, 1.0
	v_rcp_f32_e32 v46, v45
	ds_read_b64_tr_b16 v[52:53], v54
	ds_read_b64_tr_b16 v[54:55], v54 offset:2048
	s_waitcnt lgkmcnt(0)
	v_mfma_f32_16x16x32_bf16 v[36:39], v[52:55], v[48:51], v[36:39]
	v_fma_f32 v47, -v45, v46, 1.0
	v_fmac_f32_e32 v46, v47, v46
	v_div_scale_f32 v47, vcc, 1.0, v44, 1.0
	v_mul_f32_e32 v48, v47, v46
	v_fma_f32 v49, -v45, v48, v47
	v_fmac_f32_e32 v48, v49, v46
	v_fma_f32 v45, -v45, v48, v47
	v_div_fmas_f32 v45, v45, v46, v48
	v_div_fixup_f32 v44, v45, v44, 1.0
	v_lshl_add_u64 v[46:47], v[130:131], 0, s[18:19]
	v_mad_u64_u32 v[48:49], s[24:25], v46, s55, v[92:93]
	v_pk_mul_f32 v[32:33], v[44:45], v[32:33] op_sel_hi:[0,1]
	v_pk_mul_f32 v[34:35], v[44:45], v[34:35] op_sel_hi:[0,1]
	v_pk_mul_f32 v[28:29], v[44:45], v[28:29] op_sel_hi:[0,1]
	v_pk_mul_f32 v[30:31], v[44:45], v[30:31] op_sel_hi:[0,1]
	v_mad_i32_i24 v49, v47, s55, v49
	v_cvt_pk_bf16_f32 v32, v32, v33
	v_cvt_pk_bf16_f32 v33, v34, v35
	v_cvt_pk_bf16_f32 v28, v28, v29
	v_cvt_pk_bf16_f32 v29, v30, v31
	global_store_dwordx2 v[48:49], v[32:33], off
	v_pk_mul_f32 v[32:33], v[44:45], v[40:41] op_sel_hi:[0,1]
	v_pk_mul_f32 v[34:35], v[44:45], v[42:43] op_sel_hi:[0,1]
	global_store_dwordx2 v[48:49], v[28:29], off offset:64
	v_pk_mul_f32 v[28:29], v[44:45], v[36:37] op_sel_hi:[0,1]
	v_pk_mul_f32 v[30:31], v[44:45], v[38:39] op_sel_hi:[0,1]
	v_cvt_pk_bf16_f32 v32, v32, v33
	v_cvt_pk_bf16_f32 v33, v34, v35
	v_cvt_pk_bf16_f32 v28, v28, v29
	v_cvt_pk_bf16_f32 v29, v30, v31
	global_store_dwordx2 v[48:49], v[32:33], off offset:32
	global_store_dwordx2 v[48:49], v[28:29], off offset:96
	s_waitcnt lgkmcnt(0)
	s_barrier
	s_andn2_b64 vcc, exec, s[22:23]
	s_cbranch_vccnz .LBB0_594
	s_mul_i32 s18, s62, 57
	s_lshr_b32 s18, s18, 9
	s_mul_i32 s18, s18, 9
	s_sub_i32 s18, s62, s18
	s_and_b32 s18, s18, 0xff
	s_lshl_b32 s18, s18, 13
	v_add_u32_e32 v28, s18, v1
	ds_write_b128 v28, v[24:27]
	v_add_u32_e32 v24, s18, v123
	ds_write_b128 v24, v[20:23]
